# K-loop: loop-control SALU moved into MFMA cadence gaps of the last block; s_setprio 0 issued before the last MFMA of each block (on top of v15)
# speedup vs baseline: 1.0086x; 1.0029x over previous
.LBB0_92:
	ds_read_b128 v[146:149], v143
	ds_read_b128 v[150:153], v143 offset:1024
	ds_read_b128 v[154:157], v143 offset:2048
	ds_read_b128 v[158:161], v143 offset:3072
	ds_read_b128 v[162:165], v144
	ds_read_b128 v[166:169], v144 offset:1024
	ds_read_b128 v[170:173], v144 offset:2048
	ds_read_b128 v[178:181], v144 offset:3072
	ds_read_b128 v[182:185], v145
	ds_read_b128 v[186:189], v145 offset:1024
	ds_read_b128 v[190:193], v145 offset:2048
	ds_read_b128 v[194:197], v145 offset:3072
	ds_read_b128 v[198:201], v145 offset:4096
	ds_read_b128 v[206:209], v145 offset:5120
	ds_read_b128 v[210:213], v145 offset:6144
	ds_read_b128 v[214:217], v145 offset:7168
	s_add_u32 s0, s28, 0xfff80080
	s_addc_u32 s1, s29, -1
	s_cmp_eq_u32 s68, 28
	s_cselect_b32 s35, s13, s1
	s_cselect_b32 s34, s63, s0
	s_cselect_b32 s31, s64, s67
	s_cselect_b32 s30, s65, s66
	s_add_i32 m0, s27, 0xc000
	v_lshl_add_u64 v[174:175], s[28:29], 0, v[136:137]
	global_load_lds_dwordx4 v[174:175], off
	s_add_i32 m0, s27, 0xe000
	v_lshl_add_u64 v[174:175], s[28:29], 0, v[138:139]
	global_load_lds_dwordx4 v[174:175], off
	s_waitcnt vmcnt(8) lgkmcnt(0)
	s_setprio 1
	s_barrier
	v_mfma_f32_16x16x32_bf16 v[124:127], v[146:149], v[182:185], v[124:127]
	v_mfma_f32_16x16x32_bf16 v[120:123], v[154:157], v[182:185], v[120:123]
	v_mfma_f32_16x16x32_bf16 v[116:119], v[146:149], v[190:193], v[116:119]
	v_mfma_f32_16x16x32_bf16 v[108:111], v[154:157], v[190:193], v[108:111]
	v_mfma_f32_16x16x32_bf16 v[100:103], v[146:149], v[198:201], v[100:103]
	v_mfma_f32_16x16x32_bf16 v[92:95], v[154:157], v[198:201], v[92:95]
	v_mfma_f32_16x16x32_bf16 v[84:87], v[146:149], v[210:213], v[84:87]
	v_mfma_f32_16x16x32_bf16 v[76:79], v[154:157], v[210:213], v[76:79]
	v_mfma_f32_16x16x32_bf16 v[124:127], v[150:153], v[186:189], v[124:127]
	v_mfma_f32_16x16x32_bf16 v[120:123], v[158:161], v[186:189], v[120:123]
	v_mfma_f32_16x16x32_bf16 v[116:119], v[150:153], v[194:197], v[116:119]
	v_mfma_f32_16x16x32_bf16 v[108:111], v[158:161], v[194:197], v[108:111]
	v_mfma_f32_16x16x32_bf16 v[100:103], v[150:153], v[206:209], v[100:103]
	v_mfma_f32_16x16x32_bf16 v[92:95], v[158:161], v[206:209], v[92:95]
	v_mfma_f32_16x16x32_bf16 v[84:87], v[150:153], v[214:217], v[84:87]
	v_mfma_f32_16x16x32_bf16 v[76:79], v[158:161], v[214:217], v[76:79]
	v_mfma_f32_16x16x32_bf16 v[112:115], v[162:165], v[182:185], v[112:115]
	v_mfma_f32_16x16x32_bf16 v[104:107], v[170:173], v[182:185], v[104:107]
	v_mfma_f32_16x16x32_bf16 v[96:99], v[162:165], v[190:193], v[96:99]
	v_mfma_f32_16x16x32_bf16 v[88:91], v[170:173], v[190:193], v[88:91]
	v_mfma_f32_16x16x32_bf16 v[80:83], v[162:165], v[198:201], v[80:83]
	v_mfma_f32_16x16x32_bf16 v[72:75], v[170:173], v[198:201], v[72:75]
	v_mfma_f32_16x16x32_bf16 v[68:71], v[162:165], v[210:213], v[68:71]
	v_mfma_f32_16x16x32_bf16 v[64:67], v[170:173], v[210:213], v[64:67]
	v_mfma_f32_16x16x32_bf16 v[112:115], v[166:169], v[186:189], v[112:115]
	v_mfma_f32_16x16x32_bf16 v[104:107], v[178:181], v[186:189], v[104:107]
	v_mfma_f32_16x16x32_bf16 v[96:99], v[166:169], v[194:197], v[96:99]
	v_mfma_f32_16x16x32_bf16 v[88:91], v[178:181], v[194:197], v[88:91]
	v_mfma_f32_16x16x32_bf16 v[80:83], v[166:169], v[206:209], v[80:83]
	v_mfma_f32_16x16x32_bf16 v[72:75], v[178:181], v[206:209], v[72:75]
	v_mfma_f32_16x16x32_bf16 v[68:71], v[166:169], v[214:217], v[68:71]
	s_setprio 0
	v_mfma_f32_16x16x32_bf16 v[64:67], v[178:181], v[214:217], v[64:67]
	s_barrier
	ds_read_b128 v[182:185], v145 offset:16384
	ds_read_b128 v[186:189], v145 offset:17408
	ds_read_b128 v[190:193], v145 offset:18432
	ds_read_b128 v[194:197], v145 offset:19456
	ds_read_b128 v[198:201], v145 offset:20480
	ds_read_b128 v[206:209], v145 offset:21504
	ds_read_b128 v[210:213], v145 offset:22528
	ds_read_b128 v[214:217], v145 offset:23552
	s_add_i32 s0, s58, s48
	s_mov_b32 m0, s0
	v_lshl_add_u64 v[174:175], s[30:31], 0, v[132:133]
	global_load_lds_dwordx4 v[174:175], off
	s_add_i32 m0, s0, 0x2000
	s_add_u32 s0, s30, 0x80000
	v_lshl_add_u64 v[202:203], s[30:31], 0, v[128:129]
	s_addc_u32 s1, s31, 0
	s_add_i32 s2, s59, s48
	global_load_lds_dwordx4 v[202:203], off
	v_lshl_add_u64 v[218:219], s[0:1], 0, v[132:133]
	s_mov_b32 m0, s2
	v_lshl_add_u64 v[220:221], s[34:35], 0, v[130:131]
	global_load_lds_dwordx4 v[218:219], off
	s_add_i32 m0, s2, 0x2000
	v_lshl_add_u64 v[218:219], s[0:1], 0, v[128:129]
	global_load_lds_dwordx4 v[218:219], off
	s_mov_b32 m0, s27
	v_lshl_add_u64 v[218:219], s[34:35], 0, v[134:135]
	global_load_lds_dwordx4 v[218:219], off
	s_mov_b32 m0, s50
	s_nop 0
	global_load_lds_dwordx4 v[220:221], off
	s_waitcnt vmcnt(8) lgkmcnt(0)
	s_setprio 1
	s_barrier
	v_mfma_f32_16x16x32_bf16 v[60:63], v[146:149], v[182:185], v[60:63]
	v_mfma_f32_16x16x32_bf16 v[56:59], v[154:157], v[182:185], v[56:59]
	v_mfma_f32_16x16x32_bf16 v[52:55], v[146:149], v[190:193], v[52:55]
	v_mfma_f32_16x16x32_bf16 v[44:47], v[154:157], v[190:193], v[44:47]
	v_mfma_f32_16x16x32_bf16 v[36:39], v[146:149], v[198:201], v[36:39]
	v_mfma_f32_16x16x32_bf16 v[28:31], v[154:157], v[198:201], v[28:31]
	v_mfma_f32_16x16x32_bf16 v[20:23], v[146:149], v[210:213], v[20:23]
	v_mfma_f32_16x16x32_bf16 v[12:15], v[154:157], v[210:213], v[12:15]
	v_mfma_f32_16x16x32_bf16 v[60:63], v[150:153], v[186:189], v[60:63]
	v_mfma_f32_16x16x32_bf16 v[56:59], v[158:161], v[186:189], v[56:59]
	v_mfma_f32_16x16x32_bf16 v[52:55], v[150:153], v[194:197], v[52:55]
	v_mfma_f32_16x16x32_bf16 v[44:47], v[158:161], v[194:197], v[44:47]
	v_mfma_f32_16x16x32_bf16 v[36:39], v[150:153], v[206:209], v[36:39]
	v_mfma_f32_16x16x32_bf16 v[28:31], v[158:161], v[206:209], v[28:31]
	v_mfma_f32_16x16x32_bf16 v[20:23], v[150:153], v[214:217], v[20:23]
	v_mfma_f32_16x16x32_bf16 v[12:15], v[158:161], v[214:217], v[12:15]
	v_mfma_f32_16x16x32_bf16 v[48:51], v[162:165], v[182:185], v[48:51]
	v_mfma_f32_16x16x32_bf16 v[40:43], v[170:173], v[182:185], v[40:43]
	v_mfma_f32_16x16x32_bf16 v[32:35], v[162:165], v[190:193], v[32:35]
	v_mfma_f32_16x16x32_bf16 v[24:27], v[170:173], v[190:193], v[24:27]
	v_mfma_f32_16x16x32_bf16 v[16:19], v[162:165], v[198:201], v[16:19]
	v_mfma_f32_16x16x32_bf16 v[8:11], v[170:173], v[198:201], v[8:11]
	v_mfma_f32_16x16x32_bf16 v[4:7], v[162:165], v[210:213], v[4:7]
	v_mfma_f32_16x16x32_bf16 v[0:3], v[170:173], v[210:213], v[0:3]
	v_mfma_f32_16x16x32_bf16 v[48:51], v[166:169], v[186:189], v[48:51]
	v_mfma_f32_16x16x32_bf16 v[40:43], v[178:181], v[186:189], v[40:43]
	v_mfma_f32_16x16x32_bf16 v[32:35], v[166:169], v[194:197], v[32:35]
	v_mfma_f32_16x16x32_bf16 v[24:27], v[178:181], v[194:197], v[24:27]
	v_mfma_f32_16x16x32_bf16 v[16:19], v[166:169], v[206:209], v[16:19]
	v_mfma_f32_16x16x32_bf16 v[8:11], v[178:181], v[206:209], v[8:11]
	v_mfma_f32_16x16x32_bf16 v[4:7], v[166:169], v[214:217], v[4:7]
	s_setprio 0
	v_mfma_f32_16x16x32_bf16 v[0:3], v[178:181], v[214:217], v[0:3]
	s_barrier
	ds_read_b128 v[182:185], v145 offset:32768
	ds_read_b128 v[186:189], v145 offset:33792
	ds_read_b128 v[190:193], v145 offset:34816
	ds_read_b128 v[194:197], v145 offset:35840
	ds_read_b128 v[198:201], v145 offset:36864
	ds_read_b128 v[206:209], v145 offset:37888
	ds_read_b128 v[210:213], v145 offset:38912
	ds_read_b128 v[214:217], v145 offset:39936
	s_add_i32 s2, 0, 0x18000
	s_add_i32 s38, 0, 0x1c000
	v_add_u32_e32 v158, s2, v142
	v_add_u32_e32 v177, s38, v142
	ds_read_b128 v[146:149], v158
	ds_read_b128 v[150:153], v158 offset:1024
	ds_read_b128 v[154:157], v158 offset:2048
	ds_read_b128 v[158:161], v158 offset:3072
	ds_read_b128 v[162:165], v177
	ds_read_b128 v[166:169], v177 offset:1024
	ds_read_b128 v[170:173], v177 offset:2048
	ds_read_b128 v[178:181], v177 offset:3072
	s_add_u32 s0, s34, 0x80000
	s_addc_u32 s1, s35, 0
	s_mov_b32 m0, s51
	v_lshl_add_u64 v[222:223], s[0:1], 0, v[134:135]
	global_load_lds_dwordx4 v[222:223], off
	s_mov_b32 m0, s52
	v_lshl_add_u64 v[222:223], s[0:1], 0, v[130:131]
	global_load_lds_dwordx4 v[222:223], off
	s_waitcnt vmcnt(8) lgkmcnt(0)
	s_setprio 1
	s_barrier
	v_mfma_f32_16x16x32_bf16 v[124:127], v[146:149], v[182:185], v[124:127]
	v_mfma_f32_16x16x32_bf16 v[120:123], v[154:157], v[182:185], v[120:123]
	v_mfma_f32_16x16x32_bf16 v[116:119], v[146:149], v[190:193], v[116:119]
	v_mfma_f32_16x16x32_bf16 v[108:111], v[154:157], v[190:193], v[108:111]
	v_mfma_f32_16x16x32_bf16 v[100:103], v[146:149], v[198:201], v[100:103]
	v_mfma_f32_16x16x32_bf16 v[92:95], v[154:157], v[198:201], v[92:95]
	v_mfma_f32_16x16x32_bf16 v[84:87], v[146:149], v[210:213], v[84:87]
	v_mfma_f32_16x16x32_bf16 v[76:79], v[154:157], v[210:213], v[76:79]
	v_mfma_f32_16x16x32_bf16 v[124:127], v[150:153], v[186:189], v[124:127]
	v_mfma_f32_16x16x32_bf16 v[120:123], v[158:161], v[186:189], v[120:123]
	v_mfma_f32_16x16x32_bf16 v[116:119], v[150:153], v[194:197], v[116:119]
	v_mfma_f32_16x16x32_bf16 v[108:111], v[158:161], v[194:197], v[108:111]
	v_mfma_f32_16x16x32_bf16 v[100:103], v[150:153], v[206:209], v[100:103]
	v_mfma_f32_16x16x32_bf16 v[92:95], v[158:161], v[206:209], v[92:95]
	v_mfma_f32_16x16x32_bf16 v[84:87], v[150:153], v[214:217], v[84:87]
	v_mfma_f32_16x16x32_bf16 v[76:79], v[158:161], v[214:217], v[76:79]
	v_mfma_f32_16x16x32_bf16 v[112:115], v[162:165], v[182:185], v[112:115]
	v_mfma_f32_16x16x32_bf16 v[104:107], v[170:173], v[182:185], v[104:107]
	v_mfma_f32_16x16x32_bf16 v[96:99], v[162:165], v[190:193], v[96:99]
	v_mfma_f32_16x16x32_bf16 v[88:91], v[170:173], v[190:193], v[88:91]
	v_mfma_f32_16x16x32_bf16 v[80:83], v[162:165], v[198:201], v[80:83]
	v_mfma_f32_16x16x32_bf16 v[72:75], v[170:173], v[198:201], v[72:75]
	v_mfma_f32_16x16x32_bf16 v[68:71], v[162:165], v[210:213], v[68:71]
	v_mfma_f32_16x16x32_bf16 v[64:67], v[170:173], v[210:213], v[64:67]
	v_mfma_f32_16x16x32_bf16 v[112:115], v[166:169], v[186:189], v[112:115]
	v_mfma_f32_16x16x32_bf16 v[104:107], v[178:181], v[186:189], v[104:107]
	v_mfma_f32_16x16x32_bf16 v[96:99], v[166:169], v[194:197], v[96:99]
	v_mfma_f32_16x16x32_bf16 v[88:91], v[178:181], v[194:197], v[88:91]
	v_mfma_f32_16x16x32_bf16 v[80:83], v[166:169], v[206:209], v[80:83]
	v_mfma_f32_16x16x32_bf16 v[72:75], v[178:181], v[206:209], v[72:75]
	v_mfma_f32_16x16x32_bf16 v[68:71], v[166:169], v[214:217], v[68:71]
	s_setprio 0
	v_mfma_f32_16x16x32_bf16 v[64:67], v[178:181], v[214:217], v[64:67]
	s_barrier
	ds_read_b128 v[182:185], v145 offset:49152
	ds_read_b128 v[186:189], v145 offset:50176
	ds_read_b128 v[190:193], v145 offset:51200
	ds_read_b128 v[194:197], v145 offset:52224
	ds_read_b128 v[198:201], v145 offset:53248
	ds_read_b128 v[206:209], v145 offset:54272
	ds_read_b128 v[210:213], v145 offset:55296
	ds_read_b128 v[214:217], v145 offset:56320
	s_add_i32 s0, s2, s48
	s_mov_b32 m0, s0
	v_lshl_add_u64 v[174:175], v[174:175], 0, s[8:9]
	global_load_lds_dwordx4 v[174:175], off
	s_add_i32 m0, s0, 0x2000
	s_add_u32 s0, s30, 0x80080
	v_lshl_add_u64 v[174:175], v[202:203], 0, s[8:9]
	s_addc_u32 s1, s31, 0
	s_add_i32 s2, s38, s48
	global_load_lds_dwordx4 v[174:175], off
	s_mov_b32 m0, s2
	v_lshl_add_u64 v[174:175], s[0:1], 0, v[132:133]
	global_load_lds_dwordx4 v[174:175], off
	s_add_i32 m0, s2, 0x2000
	v_lshl_add_u64 v[174:175], s[0:1], 0, v[128:129]
	global_load_lds_dwordx4 v[174:175], off
	s_mov_b32 m0, s55
	v_lshl_add_u64 v[174:175], v[218:219], 0, s[8:9]
	global_load_lds_dwordx4 v[174:175], off
	s_mov_b32 m0, s56
	v_lshl_add_u64 v[174:175], v[220:221], 0, s[8:9]
	global_load_lds_dwordx4 v[174:175], off
	s_waitcnt vmcnt(8) lgkmcnt(0)
	s_setprio 1
	s_barrier
	v_mfma_f32_16x16x32_bf16 v[60:63], v[146:149], v[182:185], v[60:63]
	v_mfma_f32_16x16x32_bf16 v[56:59], v[154:157], v[182:185], v[56:59]
	v_mfma_f32_16x16x32_bf16 v[52:55], v[146:149], v[190:193], v[52:55]
	v_mfma_f32_16x16x32_bf16 v[44:47], v[154:157], v[190:193], v[44:47]
	v_mfma_f32_16x16x32_bf16 v[36:39], v[146:149], v[198:201], v[36:39]
	v_mfma_f32_16x16x32_bf16 v[28:31], v[154:157], v[198:201], v[28:31]
	v_mfma_f32_16x16x32_bf16 v[20:23], v[146:149], v[210:213], v[20:23]
	v_mfma_f32_16x16x32_bf16 v[12:15], v[154:157], v[210:213], v[12:15]
	v_mfma_f32_16x16x32_bf16 v[60:63], v[150:153], v[186:189], v[60:63]
	v_mfma_f32_16x16x32_bf16 v[56:59], v[158:161], v[186:189], v[56:59]
	v_mfma_f32_16x16x32_bf16 v[52:55], v[150:153], v[194:197], v[52:55]
	v_mfma_f32_16x16x32_bf16 v[44:47], v[158:161], v[194:197], v[44:47]
	v_mfma_f32_16x16x32_bf16 v[36:39], v[150:153], v[206:209], v[36:39]
	v_mfma_f32_16x16x32_bf16 v[28:31], v[158:161], v[206:209], v[28:31]
	v_mfma_f32_16x16x32_bf16 v[20:23], v[150:153], v[214:217], v[20:23]
	v_mfma_f32_16x16x32_bf16 v[12:15], v[158:161], v[214:217], v[12:15]
	v_mfma_f32_16x16x32_bf16 v[48:51], v[162:165], v[182:185], v[48:51]
	v_mfma_f32_16x16x32_bf16 v[40:43], v[170:173], v[182:185], v[40:43]
	v_mfma_f32_16x16x32_bf16 v[32:35], v[162:165], v[190:193], v[32:35]
	v_mfma_f32_16x16x32_bf16 v[24:27], v[170:173], v[190:193], v[24:27]
	v_mfma_f32_16x16x32_bf16 v[16:19], v[162:165], v[198:201], v[16:19]
	v_mfma_f32_16x16x32_bf16 v[8:11], v[170:173], v[198:201], v[8:11]
	v_mfma_f32_16x16x32_bf16 v[4:7], v[162:165], v[210:213], v[4:7]
	v_mfma_f32_16x16x32_bf16 v[0:3], v[170:173], v[210:213], v[0:3]
	v_mfma_f32_16x16x32_bf16 v[48:51], v[166:169], v[186:189], v[48:51]
	s_add_i32 s68, s68, 2
	v_mfma_f32_16x16x32_bf16 v[40:43], v[178:181], v[186:189], v[40:43]
	s_add_u32 s28, s28, 0x100
	v_mfma_f32_16x16x32_bf16 v[32:35], v[166:169], v[194:197], v[32:35]
	s_addc_u32 s29, s29, 0
	v_mfma_f32_16x16x32_bf16 v[24:27], v[178:181], v[194:197], v[24:27]
	s_add_u32 s66, s66, 0x100
	v_mfma_f32_16x16x32_bf16 v[16:19], v[166:169], v[206:209], v[16:19]
	s_addc_u32 s67, s67, 0
	v_mfma_f32_16x16x32_bf16 v[8:11], v[178:181], v[206:209], v[8:11]
	s_cmp_gt_u32 s68, 29
	v_mfma_f32_16x16x32_bf16 v[4:7], v[166:169], v[214:217], v[4:7]
	s_setprio 0
	v_mfma_f32_16x16x32_bf16 v[0:3], v[178:181], v[214:217], v[0:3]
	s_barrier
	s_cbranch_scc0 .LBB0_92
	s_and_b64 vcc, exec, s[10:11]
	s_cbranch_vccz .LBB0_95
	s_barrier

.LBB0_300:
	ds_read_b128 v[128:131], v157
	ds_read_b128 v[132:135], v157 offset:1024
	ds_read_b128 v[136:139], v157 offset:2048
	ds_read_b128 v[140:143], v157 offset:3072
	ds_read_b128 v[160:163], v158
	ds_read_b128 v[164:167], v158 offset:1024
	ds_read_b128 v[168:171], v158 offset:2048
	ds_read_b128 v[172:175], v158 offset:3072
	ds_read_b128 v[178:181], v159
	ds_read_b128 v[182:185], v159 offset:1024
	ds_read_b128 v[186:189], v159 offset:2048
	ds_read_b128 v[190:193], v159 offset:3072
	ds_read_b128 v[194:197], v159 offset:4096
	ds_read_b128 v[198:201], v159 offset:5120
	ds_read_b128 v[206:209], v159 offset:6144
	ds_read_b128 v[210:213], v159 offset:7168
	s_add_u32 s0, s62, 0xfff80080
	s_addc_u32 s1, s63, -1
	s_cmp_eq_u32 s89, 28
	s_cselect_b32 s67, s14, s1
	s_cselect_b32 s66, s49, s0
	s_cselect_b32 s65, s61, s88
	s_cselect_b32 s64, s68, s69
	s_add_i32 m0, s72, 0xc000
	v_lshl_add_u64 v[152:153], s[62:63], 0, v[148:149]
	global_load_lds_dwordx4 v[152:153], off
	s_add_i32 m0, s72, 0xe000
	v_lshl_add_u64 v[152:153], s[62:63], 0, v[150:151]
	global_load_lds_dwordx4 v[152:153], off
	s_waitcnt vmcnt(8) lgkmcnt(0)
	s_setprio 1
	s_barrier
	v_mfma_f32_16x16x32_bf16 v[124:127], v[128:131], v[178:181], v[124:127]
	v_mfma_f32_16x16x32_bf16 v[120:123], v[136:139], v[178:181], v[120:123]
	v_mfma_f32_16x16x32_bf16 v[112:115], v[128:131], v[186:189], v[112:115]
	v_mfma_f32_16x16x32_bf16 v[108:111], v[136:139], v[186:189], v[108:111]
	v_mfma_f32_16x16x32_bf16 v[96:99], v[128:131], v[194:197], v[96:99]
	v_mfma_f32_16x16x32_bf16 v[92:95], v[136:139], v[194:197], v[92:95]
	v_mfma_f32_16x16x32_bf16 v[80:83], v[128:131], v[206:209], v[80:83]
	v_mfma_f32_16x16x32_bf16 v[76:79], v[136:139], v[206:209], v[76:79]
	v_mfma_f32_16x16x32_bf16 v[124:127], v[132:135], v[182:185], v[124:127]
	v_mfma_f32_16x16x32_bf16 v[120:123], v[140:143], v[182:185], v[120:123]
	v_mfma_f32_16x16x32_bf16 v[112:115], v[132:135], v[190:193], v[112:115]
	v_mfma_f32_16x16x32_bf16 v[108:111], v[140:143], v[190:193], v[108:111]
	v_mfma_f32_16x16x32_bf16 v[96:99], v[132:135], v[198:201], v[96:99]
	v_mfma_f32_16x16x32_bf16 v[92:95], v[140:143], v[198:201], v[92:95]
	v_mfma_f32_16x16x32_bf16 v[80:83], v[132:135], v[210:213], v[80:83]
	v_mfma_f32_16x16x32_bf16 v[76:79], v[140:143], v[210:213], v[76:79]
	v_mfma_f32_16x16x32_bf16 v[116:119], v[160:163], v[178:181], v[116:119]
	v_mfma_f32_16x16x32_bf16 v[104:107], v[168:171], v[178:181], v[104:107]
	v_mfma_f32_16x16x32_bf16 v[100:103], v[160:163], v[186:189], v[100:103]
	v_mfma_f32_16x16x32_bf16 v[88:91], v[168:171], v[186:189], v[88:91]
	v_mfma_f32_16x16x32_bf16 v[84:87], v[160:163], v[194:197], v[84:87]
	v_mfma_f32_16x16x32_bf16 v[72:75], v[168:171], v[194:197], v[72:75]
	v_mfma_f32_16x16x32_bf16 v[68:71], v[160:163], v[206:209], v[68:71]
	v_mfma_f32_16x16x32_bf16 v[64:67], v[168:171], v[206:209], v[64:67]
	v_mfma_f32_16x16x32_bf16 v[116:119], v[164:167], v[182:185], v[116:119]
	v_mfma_f32_16x16x32_bf16 v[104:107], v[172:175], v[182:185], v[104:107]
	v_mfma_f32_16x16x32_bf16 v[100:103], v[164:167], v[190:193], v[100:103]
	v_mfma_f32_16x16x32_bf16 v[88:91], v[172:175], v[190:193], v[88:91]
	v_mfma_f32_16x16x32_bf16 v[84:87], v[164:167], v[198:201], v[84:87]
	v_mfma_f32_16x16x32_bf16 v[72:75], v[172:175], v[198:201], v[72:75]
	v_mfma_f32_16x16x32_bf16 v[68:71], v[164:167], v[210:213], v[68:71]
	s_setprio 0
	v_mfma_f32_16x16x32_bf16 v[64:67], v[172:175], v[210:213], v[64:67]
	s_barrier
	ds_read_b128 v[178:181], v159 offset:16384
	ds_read_b128 v[182:185], v159 offset:17408
	ds_read_b128 v[186:189], v159 offset:18432
	ds_read_b128 v[190:193], v159 offset:19456
	ds_read_b128 v[194:197], v159 offset:20480
	ds_read_b128 v[198:201], v159 offset:21504
	ds_read_b128 v[206:209], v159 offset:22528
	ds_read_b128 v[210:213], v159 offset:23552
	s_add_i32 s0, s83, s71
	s_mov_b32 m0, s0
	v_lshl_add_u64 v[152:153], s[64:65], 0, v[146:147]
	global_load_lds_dwordx4 v[152:153], off
	s_add_i32 m0, s0, 0x2000
	s_add_u32 s0, s64, 0x80000
	v_lshl_add_u64 v[202:203], s[64:65], 0, v[144:145]
	s_addc_u32 s1, s65, 0
	s_add_i32 s2, s84, s71
	global_load_lds_dwordx4 v[202:203], off
	v_lshl_add_u64 v[214:215], s[0:1], 0, v[146:147]
	s_mov_b32 m0, s2
	v_lshl_add_u64 v[216:217], s[66:67], 0, v[144:145]
	global_load_lds_dwordx4 v[214:215], off
	s_add_i32 m0, s2, 0x2000
	v_lshl_add_u64 v[214:215], s[0:1], 0, v[144:145]
	global_load_lds_dwordx4 v[214:215], off
	s_mov_b32 m0, s72
	v_lshl_add_u64 v[214:215], s[66:67], 0, v[146:147]
	global_load_lds_dwordx4 v[214:215], off
	s_mov_b32 m0, s73
	s_nop 0
	global_load_lds_dwordx4 v[216:217], off
	s_waitcnt vmcnt(8) lgkmcnt(0)
	s_setprio 1
	s_barrier
	v_mfma_f32_16x16x32_bf16 v[60:63], v[128:131], v[178:181], v[60:63]
	v_mfma_f32_16x16x32_bf16 v[56:59], v[136:139], v[178:181], v[56:59]
	v_mfma_f32_16x16x32_bf16 v[48:51], v[128:131], v[186:189], v[48:51]
	v_mfma_f32_16x16x32_bf16 v[44:47], v[136:139], v[186:189], v[44:47]
	v_mfma_f32_16x16x32_bf16 v[32:35], v[128:131], v[194:197], v[32:35]
	v_mfma_f32_16x16x32_bf16 v[28:31], v[136:139], v[194:197], v[28:31]
	v_mfma_f32_16x16x32_bf16 v[16:19], v[128:131], v[206:209], v[16:19]
	v_mfma_f32_16x16x32_bf16 v[12:15], v[136:139], v[206:209], v[12:15]
	v_mfma_f32_16x16x32_bf16 v[60:63], v[132:135], v[182:185], v[60:63]
	v_mfma_f32_16x16x32_bf16 v[56:59], v[140:143], v[182:185], v[56:59]
	v_mfma_f32_16x16x32_bf16 v[48:51], v[132:135], v[190:193], v[48:51]
	v_mfma_f32_16x16x32_bf16 v[44:47], v[140:143], v[190:193], v[44:47]
	v_mfma_f32_16x16x32_bf16 v[32:35], v[132:135], v[198:201], v[32:35]
	v_mfma_f32_16x16x32_bf16 v[28:31], v[140:143], v[198:201], v[28:31]
	v_mfma_f32_16x16x32_bf16 v[16:19], v[132:135], v[210:213], v[16:19]
	v_mfma_f32_16x16x32_bf16 v[12:15], v[140:143], v[210:213], v[12:15]
	v_mfma_f32_16x16x32_bf16 v[52:55], v[160:163], v[178:181], v[52:55]
	v_mfma_f32_16x16x32_bf16 v[40:43], v[168:171], v[178:181], v[40:43]
	v_mfma_f32_16x16x32_bf16 v[36:39], v[160:163], v[186:189], v[36:39]
	v_mfma_f32_16x16x32_bf16 v[24:27], v[168:171], v[186:189], v[24:27]
	v_mfma_f32_16x16x32_bf16 v[20:23], v[160:163], v[194:197], v[20:23]
	v_mfma_f32_16x16x32_bf16 v[8:11], v[168:171], v[194:197], v[8:11]
	v_mfma_f32_16x16x32_bf16 v[4:7], v[160:163], v[206:209], v[4:7]
	v_mfma_f32_16x16x32_bf16 v[0:3], v[168:171], v[206:209], v[0:3]
	v_mfma_f32_16x16x32_bf16 v[52:55], v[164:167], v[182:185], v[52:55]
	v_mfma_f32_16x16x32_bf16 v[40:43], v[172:175], v[182:185], v[40:43]
	v_mfma_f32_16x16x32_bf16 v[36:39], v[164:167], v[190:193], v[36:39]
	v_mfma_f32_16x16x32_bf16 v[24:27], v[172:175], v[190:193], v[24:27]
	v_mfma_f32_16x16x32_bf16 v[20:23], v[164:167], v[198:201], v[20:23]
	v_mfma_f32_16x16x32_bf16 v[8:11], v[172:175], v[198:201], v[8:11]
	v_mfma_f32_16x16x32_bf16 v[4:7], v[164:167], v[210:213], v[4:7]
	s_setprio 0
	v_mfma_f32_16x16x32_bf16 v[0:3], v[172:175], v[210:213], v[0:3]
	s_barrier
	ds_read_b128 v[178:181], v159 offset:32768
	ds_read_b128 v[182:185], v159 offset:33792
	ds_read_b128 v[186:189], v159 offset:34816
	ds_read_b128 v[190:193], v159 offset:35840
	ds_read_b128 v[194:197], v159 offset:36864
	ds_read_b128 v[198:201], v159 offset:37888
	ds_read_b128 v[206:209], v159 offset:38912
	ds_read_b128 v[210:213], v159 offset:39936
	s_add_i32 s2, 0, 0x18000
	s_add_i32 s3, 0, 0x1c000
	v_add_u32_e32 v140, s2, v156
	v_add_u32_e32 v172, s3, v156
	ds_read_b128 v[128:131], v140
	ds_read_b128 v[132:135], v140 offset:1024
	ds_read_b128 v[136:139], v140 offset:2048
	ds_read_b128 v[140:143], v140 offset:3072
	ds_read_b128 v[160:163], v172
	ds_read_b128 v[164:167], v172 offset:1024
	ds_read_b128 v[168:171], v172 offset:2048
	ds_read_b128 v[172:175], v172 offset:3072
	s_add_u32 s0, s66, 0x80000
	s_addc_u32 s1, s67, 0
	s_mov_b32 m0, s74
	v_lshl_add_u64 v[218:219], s[0:1], 0, v[146:147]
	global_load_lds_dwordx4 v[218:219], off
	s_mov_b32 m0, s75
	v_lshl_add_u64 v[218:219], s[0:1], 0, v[144:145]
	global_load_lds_dwordx4 v[218:219], off
	s_waitcnt vmcnt(8) lgkmcnt(0)
	s_setprio 1
	s_barrier
	v_mfma_f32_16x16x32_bf16 v[124:127], v[128:131], v[178:181], v[124:127]
	v_mfma_f32_16x16x32_bf16 v[120:123], v[136:139], v[178:181], v[120:123]
	v_mfma_f32_16x16x32_bf16 v[112:115], v[128:131], v[186:189], v[112:115]
	v_mfma_f32_16x16x32_bf16 v[108:111], v[136:139], v[186:189], v[108:111]
	v_mfma_f32_16x16x32_bf16 v[96:99], v[128:131], v[194:197], v[96:99]
	v_mfma_f32_16x16x32_bf16 v[92:95], v[136:139], v[194:197], v[92:95]
	v_mfma_f32_16x16x32_bf16 v[80:83], v[128:131], v[206:209], v[80:83]
	v_mfma_f32_16x16x32_bf16 v[76:79], v[136:139], v[206:209], v[76:79]
	v_mfma_f32_16x16x32_bf16 v[124:127], v[132:135], v[182:185], v[124:127]
	v_mfma_f32_16x16x32_bf16 v[120:123], v[140:143], v[182:185], v[120:123]
	v_mfma_f32_16x16x32_bf16 v[112:115], v[132:135], v[190:193], v[112:115]
	v_mfma_f32_16x16x32_bf16 v[108:111], v[140:143], v[190:193], v[108:111]
	v_mfma_f32_16x16x32_bf16 v[96:99], v[132:135], v[198:201], v[96:99]
	v_mfma_f32_16x16x32_bf16 v[92:95], v[140:143], v[198:201], v[92:95]
	v_mfma_f32_16x16x32_bf16 v[80:83], v[132:135], v[210:213], v[80:83]
	v_mfma_f32_16x16x32_bf16 v[76:79], v[140:143], v[210:213], v[76:79]
	v_mfma_f32_16x16x32_bf16 v[116:119], v[160:163], v[178:181], v[116:119]
	v_mfma_f32_16x16x32_bf16 v[104:107], v[168:171], v[178:181], v[104:107]
	v_mfma_f32_16x16x32_bf16 v[100:103], v[160:163], v[186:189], v[100:103]
	v_mfma_f32_16x16x32_bf16 v[88:91], v[168:171], v[186:189], v[88:91]
	v_mfma_f32_16x16x32_bf16 v[84:87], v[160:163], v[194:197], v[84:87]
	v_mfma_f32_16x16x32_bf16 v[72:75], v[168:171], v[194:197], v[72:75]
	v_mfma_f32_16x16x32_bf16 v[68:71], v[160:163], v[206:209], v[68:71]
	v_mfma_f32_16x16x32_bf16 v[64:67], v[168:171], v[206:209], v[64:67]
	v_mfma_f32_16x16x32_bf16 v[116:119], v[164:167], v[182:185], v[116:119]
	v_mfma_f32_16x16x32_bf16 v[104:107], v[172:175], v[182:185], v[104:107]
	v_mfma_f32_16x16x32_bf16 v[100:103], v[164:167], v[190:193], v[100:103]
	v_mfma_f32_16x16x32_bf16 v[88:91], v[172:175], v[190:193], v[88:91]
	v_mfma_f32_16x16x32_bf16 v[84:87], v[164:167], v[198:201], v[84:87]
	v_mfma_f32_16x16x32_bf16 v[72:75], v[172:175], v[198:201], v[72:75]
	v_mfma_f32_16x16x32_bf16 v[68:71], v[164:167], v[210:213], v[68:71]
	s_setprio 0
	v_mfma_f32_16x16x32_bf16 v[64:67], v[172:175], v[210:213], v[64:67]
	s_barrier
	ds_read_b128 v[178:181], v159 offset:49152
	ds_read_b128 v[182:185], v159 offset:50176
	ds_read_b128 v[186:189], v159 offset:51200
	ds_read_b128 v[190:193], v159 offset:52224
	ds_read_b128 v[194:197], v159 offset:53248
	ds_read_b128 v[198:201], v159 offset:54272
	ds_read_b128 v[206:209], v159 offset:55296
	ds_read_b128 v[210:213], v159 offset:56320
	s_add_i32 s0, s2, s71
	s_mov_b32 m0, s0
	v_lshl_add_u64 v[152:153], v[152:153], 0, s[12:13]
	global_load_lds_dwordx4 v[152:153], off
	s_add_i32 m0, s0, 0x2000
	s_add_u32 s0, s64, 0x80080
	v_lshl_add_u64 v[152:153], v[202:203], 0, s[12:13]
	s_addc_u32 s1, s65, 0
	s_add_i32 s2, s3, s71
	global_load_lds_dwordx4 v[152:153], off
	s_mov_b32 m0, s2
	v_lshl_add_u64 v[152:153], s[0:1], 0, v[146:147]
	global_load_lds_dwordx4 v[152:153], off
	s_add_i32 m0, s2, 0x2000
	v_lshl_add_u64 v[152:153], s[0:1], 0, v[144:145]
	global_load_lds_dwordx4 v[152:153], off
	s_mov_b32 m0, s81
	v_lshl_add_u64 v[152:153], v[214:215], 0, s[12:13]
	global_load_lds_dwordx4 v[152:153], off
	s_mov_b32 m0, s82
	v_lshl_add_u64 v[152:153], v[216:217], 0, s[12:13]
	global_load_lds_dwordx4 v[152:153], off
	s_waitcnt vmcnt(8) lgkmcnt(0)
	s_setprio 1
	s_barrier
	v_mfma_f32_16x16x32_bf16 v[60:63], v[128:131], v[178:181], v[60:63]
	v_mfma_f32_16x16x32_bf16 v[56:59], v[136:139], v[178:181], v[56:59]
	v_mfma_f32_16x16x32_bf16 v[48:51], v[128:131], v[186:189], v[48:51]
	v_mfma_f32_16x16x32_bf16 v[44:47], v[136:139], v[186:189], v[44:47]
	v_mfma_f32_16x16x32_bf16 v[32:35], v[128:131], v[194:197], v[32:35]
	v_mfma_f32_16x16x32_bf16 v[28:31], v[136:139], v[194:197], v[28:31]
	v_mfma_f32_16x16x32_bf16 v[16:19], v[128:131], v[206:209], v[16:19]
	v_mfma_f32_16x16x32_bf16 v[12:15], v[136:139], v[206:209], v[12:15]
	v_mfma_f32_16x16x32_bf16 v[60:63], v[132:135], v[182:185], v[60:63]
	v_mfma_f32_16x16x32_bf16 v[56:59], v[140:143], v[182:185], v[56:59]
	v_mfma_f32_16x16x32_bf16 v[48:51], v[132:135], v[190:193], v[48:51]
	v_mfma_f32_16x16x32_bf16 v[44:47], v[140:143], v[190:193], v[44:47]
	v_mfma_f32_16x16x32_bf16 v[32:35], v[132:135], v[198:201], v[32:35]
	v_mfma_f32_16x16x32_bf16 v[28:31], v[140:143], v[198:201], v[28:31]
	v_mfma_f32_16x16x32_bf16 v[16:19], v[132:135], v[210:213], v[16:19]
	v_mfma_f32_16x16x32_bf16 v[12:15], v[140:143], v[210:213], v[12:15]
	v_mfma_f32_16x16x32_bf16 v[52:55], v[160:163], v[178:181], v[52:55]
	v_mfma_f32_16x16x32_bf16 v[40:43], v[168:171], v[178:181], v[40:43]
	v_mfma_f32_16x16x32_bf16 v[36:39], v[160:163], v[186:189], v[36:39]
	v_mfma_f32_16x16x32_bf16 v[24:27], v[168:171], v[186:189], v[24:27]
	v_mfma_f32_16x16x32_bf16 v[20:23], v[160:163], v[194:197], v[20:23]
	v_mfma_f32_16x16x32_bf16 v[8:11], v[168:171], v[194:197], v[8:11]
	v_mfma_f32_16x16x32_bf16 v[4:7], v[160:163], v[206:209], v[4:7]
	v_mfma_f32_16x16x32_bf16 v[0:3], v[168:171], v[206:209], v[0:3]
	v_mfma_f32_16x16x32_bf16 v[52:55], v[164:167], v[182:185], v[52:55]
	s_add_i32 s89, s89, 2
	v_mfma_f32_16x16x32_bf16 v[40:43], v[172:175], v[182:185], v[40:43]
	s_add_u32 s62, s62, 0x100
	v_mfma_f32_16x16x32_bf16 v[36:39], v[164:167], v[190:193], v[36:39]
	s_addc_u32 s63, s63, 0
	v_mfma_f32_16x16x32_bf16 v[24:27], v[172:175], v[190:193], v[24:27]
	s_add_u32 s69, s69, 0x100
	v_mfma_f32_16x16x32_bf16 v[20:23], v[164:167], v[198:201], v[20:23]
	s_addc_u32 s88, s88, 0
	v_mfma_f32_16x16x32_bf16 v[8:11], v[172:175], v[198:201], v[8:11]
	s_cmp_gt_u32 s89, 29
	v_mfma_f32_16x16x32_bf16 v[4:7], v[164:167], v[210:213], v[4:7]
	s_setprio 0
	v_mfma_f32_16x16x32_bf16 v[0:3], v[172:175], v[210:213], v[0:3]
	s_barrier
	s_cbranch_scc0 .LBB0_300
	s_and_b64 vcc, exec, s[16:17]
	s_cbranch_vccz .LBB0_303
	s_barrier

.LBB0_399:
	ds_read_b128 v[128:131], v207
	ds_read_b128 v[132:135], v207 offset:1024
	ds_read_b128 v[136:139], v207 offset:2048
	ds_read_b128 v[140:143], v207 offset:3072
	ds_read_b128 v[144:147], v208
	ds_read_b128 v[148:151], v208 offset:1024
	ds_read_b128 v[152:155], v208 offset:2048
	ds_read_b128 v[156:159], v208 offset:3072
	ds_read_b128 v[160:163], v209
	ds_read_b128 v[164:167], v209 offset:1024
	ds_read_b128 v[168:171], v209 offset:2048
	ds_read_b128 v[172:175], v209 offset:3072
	ds_read_b128 v[190:193], v209 offset:4096
	ds_read_b128 v[194:197], v209 offset:5120
	ds_read_b128 v[198:201], v209 offset:6144
	ds_read_b128 v[210:213], v209 offset:7168
	s_add_u32 s0, s4, 0xfff80080
	s_addc_u32 s1, s5, -1
	s_cmp_eq_u32 vcc_hi, 28
	s_cselect_b32 s11, s7, s1
	s_cselect_b32 s10, s12, s0
	s_cselect_b32 s9, s13, vcc_lo
	s_cselect_b32 s8, s15, s65
	s_add_i32 m0, s81, 0xc000
	v_lshl_add_u64 v[202:203], s[4:5], 0, v[186:187]
	global_load_lds_dwordx4 v[202:203], off
	s_add_i32 m0, s81, 0xe000
	v_lshl_add_u64 v[202:203], s[4:5], 0, v[188:189]
	global_load_lds_dwordx4 v[202:203], off
	s_waitcnt vmcnt(8) lgkmcnt(0)
	s_setprio 1
	s_barrier
	v_mfma_f32_16x16x32_bf16 v[124:127], v[128:131], v[160:163], v[124:127]
	v_mfma_f32_16x16x32_bf16 v[56:59], v[136:139], v[160:163], v[56:59]
	v_mfma_f32_16x16x32_bf16 v[116:119], v[128:131], v[168:171], v[116:119]
	v_mfma_f32_16x16x32_bf16 v[52:55], v[136:139], v[168:171], v[52:55]
	v_mfma_f32_16x16x32_bf16 v[108:111], v[128:131], v[190:193], v[108:111]
	v_mfma_f32_16x16x32_bf16 v[44:47], v[136:139], v[190:193], v[44:47]
	v_mfma_f32_16x16x32_bf16 v[104:107], v[128:131], v[198:201], v[104:107]
	v_mfma_f32_16x16x32_bf16 v[32:35], v[136:139], v[198:201], v[32:35]
	v_mfma_f32_16x16x32_bf16 v[124:127], v[132:135], v[164:167], v[124:127]
	v_mfma_f32_16x16x32_bf16 v[56:59], v[140:143], v[164:167], v[56:59]
	v_mfma_f32_16x16x32_bf16 v[116:119], v[132:135], v[172:175], v[116:119]
	v_mfma_f32_16x16x32_bf16 v[52:55], v[140:143], v[172:175], v[52:55]
	v_mfma_f32_16x16x32_bf16 v[108:111], v[132:135], v[194:197], v[108:111]
	v_mfma_f32_16x16x32_bf16 v[44:47], v[140:143], v[194:197], v[44:47]
	v_mfma_f32_16x16x32_bf16 v[104:107], v[132:135], v[210:213], v[104:107]
	v_mfma_f32_16x16x32_bf16 v[32:35], v[140:143], v[210:213], v[32:35]
	v_mfma_f32_16x16x32_bf16 v[120:123], v[144:147], v[160:163], v[120:123]
	v_mfma_f32_16x16x32_bf16 v[60:63], v[152:155], v[160:163], v[60:63]
	v_mfma_f32_16x16x32_bf16 v[112:115], v[144:147], v[168:171], v[112:115]
	v_mfma_f32_16x16x32_bf16 v[48:51], v[152:155], v[168:171], v[48:51]
	v_mfma_f32_16x16x32_bf16 v[100:103], v[144:147], v[190:193], v[100:103]
	v_mfma_f32_16x16x32_bf16 v[40:43], v[152:155], v[190:193], v[40:43]
	v_mfma_f32_16x16x32_bf16 v[96:99], v[144:147], v[198:201], v[96:99]
	v_mfma_f32_16x16x32_bf16 v[36:39], v[152:155], v[198:201], v[36:39]
	v_mfma_f32_16x16x32_bf16 v[120:123], v[148:151], v[164:167], v[120:123]
	v_mfma_f32_16x16x32_bf16 v[60:63], v[156:159], v[164:167], v[60:63]
	v_mfma_f32_16x16x32_bf16 v[112:115], v[148:151], v[172:175], v[112:115]
	v_mfma_f32_16x16x32_bf16 v[48:51], v[156:159], v[172:175], v[48:51]
	v_mfma_f32_16x16x32_bf16 v[100:103], v[148:151], v[194:197], v[100:103]
	v_mfma_f32_16x16x32_bf16 v[40:43], v[156:159], v[194:197], v[40:43]
	v_mfma_f32_16x16x32_bf16 v[96:99], v[148:151], v[210:213], v[96:99]
	s_setprio 0
	v_mfma_f32_16x16x32_bf16 v[36:39], v[156:159], v[210:213], v[36:39]
	s_barrier
	ds_read_b128 v[160:163], v209 offset:16384
	ds_read_b128 v[164:167], v209 offset:17408
	ds_read_b128 v[168:171], v209 offset:18432
	ds_read_b128 v[172:175], v209 offset:19456
	ds_read_b128 v[190:193], v209 offset:20480
	ds_read_b128 v[194:197], v209 offset:21504
	ds_read_b128 v[198:201], v209 offset:22528
	ds_read_b128 v[210:213], v209 offset:23552
	s_add_i32 s0, s95, s80
	s_mov_b32 m0, s0
	v_lshl_add_u64 v[202:203], s[8:9], 0, v[180:181]
	global_load_lds_dwordx4 v[202:203], off
	s_add_i32 m0, s0, 0x2000
	s_add_u32 s0, s8, 0x80000
	v_lshl_add_u64 v[214:215], s[8:9], 0, v[184:185]
	s_addc_u32 s1, s9, 0
	s_add_i32 s2, s96, s80
	global_load_lds_dwordx4 v[214:215], off
	v_lshl_add_u64 v[216:217], s[0:1], 0, v[180:181]
	s_mov_b32 m0, s2
	v_lshl_add_u64 v[218:219], s[10:11], 0, v[182:183]
	global_load_lds_dwordx4 v[216:217], off
	s_add_i32 m0, s2, 0x2000
	v_lshl_add_u64 v[216:217], s[0:1], 0, v[184:185]
	global_load_lds_dwordx4 v[216:217], off
	s_mov_b32 m0, s81
	v_lshl_add_u64 v[216:217], s[10:11], 0, v[178:179]
	global_load_lds_dwordx4 v[216:217], off
	s_mov_b32 m0, s82
	s_nop 0
	global_load_lds_dwordx4 v[218:219], off
	s_waitcnt vmcnt(8) lgkmcnt(0)
	s_setprio 1
	s_barrier
	v_mfma_f32_16x16x32_bf16 v[92:95], v[128:131], v[160:163], v[92:95]
	v_mfma_f32_16x16x32_bf16 v[24:27], v[136:139], v[160:163], v[24:27]
	v_mfma_f32_16x16x32_bf16 v[84:87], v[128:131], v[168:171], v[84:87]
	v_mfma_f32_16x16x32_bf16 v[20:23], v[136:139], v[168:171], v[20:23]
	v_mfma_f32_16x16x32_bf16 v[76:79], v[128:131], v[190:193], v[76:79]
	v_mfma_f32_16x16x32_bf16 v[12:15], v[136:139], v[190:193], v[12:15]
	v_mfma_f32_16x16x32_bf16 v[72:75], v[128:131], v[198:201], v[72:75]
	v_mfma_f32_16x16x32_bf16 v[0:3], v[136:139], v[198:201], v[0:3]
	v_mfma_f32_16x16x32_bf16 v[92:95], v[132:135], v[164:167], v[92:95]
	v_mfma_f32_16x16x32_bf16 v[24:27], v[140:143], v[164:167], v[24:27]
	v_mfma_f32_16x16x32_bf16 v[84:87], v[132:135], v[172:175], v[84:87]
	v_mfma_f32_16x16x32_bf16 v[20:23], v[140:143], v[172:175], v[20:23]
	v_mfma_f32_16x16x32_bf16 v[76:79], v[132:135], v[194:197], v[76:79]
	v_mfma_f32_16x16x32_bf16 v[12:15], v[140:143], v[194:197], v[12:15]
	v_mfma_f32_16x16x32_bf16 v[72:75], v[132:135], v[210:213], v[72:75]
	v_mfma_f32_16x16x32_bf16 v[0:3], v[140:143], v[210:213], v[0:3]
	v_mfma_f32_16x16x32_bf16 v[88:91], v[144:147], v[160:163], v[88:91]
	v_mfma_f32_16x16x32_bf16 v[28:31], v[152:155], v[160:163], v[28:31]
	v_mfma_f32_16x16x32_bf16 v[80:83], v[144:147], v[168:171], v[80:83]
	v_mfma_f32_16x16x32_bf16 v[16:19], v[152:155], v[168:171], v[16:19]
	v_mfma_f32_16x16x32_bf16 v[68:71], v[144:147], v[190:193], v[68:71]
	v_mfma_f32_16x16x32_bf16 v[8:11], v[152:155], v[190:193], v[8:11]
	v_mfma_f32_16x16x32_bf16 v[64:67], v[144:147], v[198:201], v[64:67]
	v_mfma_f32_16x16x32_bf16 v[4:7], v[152:155], v[198:201], v[4:7]
	v_mfma_f32_16x16x32_bf16 v[88:91], v[148:151], v[164:167], v[88:91]
	v_mfma_f32_16x16x32_bf16 v[28:31], v[156:159], v[164:167], v[28:31]
	v_mfma_f32_16x16x32_bf16 v[80:83], v[148:151], v[172:175], v[80:83]
	v_mfma_f32_16x16x32_bf16 v[16:19], v[156:159], v[172:175], v[16:19]
	v_mfma_f32_16x16x32_bf16 v[68:71], v[148:151], v[194:197], v[68:71]
	v_mfma_f32_16x16x32_bf16 v[8:11], v[156:159], v[194:197], v[8:11]
	v_mfma_f32_16x16x32_bf16 v[64:67], v[148:151], v[210:213], v[64:67]
	s_setprio 0
	v_mfma_f32_16x16x32_bf16 v[4:7], v[156:159], v[210:213], v[4:7]
	s_barrier
	ds_read_b128 v[160:163], v209 offset:32768
	ds_read_b128 v[164:167], v209 offset:33792
	ds_read_b128 v[168:171], v209 offset:34816
	ds_read_b128 v[172:175], v209 offset:35840
	ds_read_b128 v[190:193], v209 offset:36864
	ds_read_b128 v[194:197], v209 offset:37888
	ds_read_b128 v[198:201], v209 offset:38912
	ds_read_b128 v[210:213], v209 offset:39936
	s_add_i32 s2, 0, 0x18000
	s_add_i32 s3, 0, 0x1c000
	v_add_u32_e32 v140, s2, v206
	v_add_u32_e32 v156, s3, v206
	ds_read_b128 v[128:131], v140
	ds_read_b128 v[132:135], v140 offset:1024
	ds_read_b128 v[136:139], v140 offset:2048
	ds_read_b128 v[140:143], v140 offset:3072
	ds_read_b128 v[144:147], v156
	ds_read_b128 v[148:151], v156 offset:1024
	ds_read_b128 v[152:155], v156 offset:2048
	ds_read_b128 v[156:159], v156 offset:3072
	s_add_u32 s0, s10, 0x80000
	s_addc_u32 s1, s11, 0
	s_mov_b32 m0, s83
	v_lshl_add_u64 v[220:221], s[0:1], 0, v[178:179]
	global_load_lds_dwordx4 v[220:221], off
	s_mov_b32 m0, s84
	v_lshl_add_u64 v[220:221], s[0:1], 0, v[182:183]
	global_load_lds_dwordx4 v[220:221], off
	s_waitcnt vmcnt(8) lgkmcnt(0)
	s_setprio 1
	s_barrier
	v_mfma_f32_16x16x32_bf16 v[124:127], v[128:131], v[160:163], v[124:127]
	v_mfma_f32_16x16x32_bf16 v[56:59], v[136:139], v[160:163], v[56:59]
	v_mfma_f32_16x16x32_bf16 v[116:119], v[128:131], v[168:171], v[116:119]
	v_mfma_f32_16x16x32_bf16 v[52:55], v[136:139], v[168:171], v[52:55]
	v_mfma_f32_16x16x32_bf16 v[108:111], v[128:131], v[190:193], v[108:111]
	v_mfma_f32_16x16x32_bf16 v[44:47], v[136:139], v[190:193], v[44:47]
	v_mfma_f32_16x16x32_bf16 v[104:107], v[128:131], v[198:201], v[104:107]
	v_mfma_f32_16x16x32_bf16 v[32:35], v[136:139], v[198:201], v[32:35]
	v_mfma_f32_16x16x32_bf16 v[124:127], v[132:135], v[164:167], v[124:127]
	v_mfma_f32_16x16x32_bf16 v[56:59], v[140:143], v[164:167], v[56:59]
	v_mfma_f32_16x16x32_bf16 v[116:119], v[132:135], v[172:175], v[116:119]
	v_mfma_f32_16x16x32_bf16 v[52:55], v[140:143], v[172:175], v[52:55]
	v_mfma_f32_16x16x32_bf16 v[108:111], v[132:135], v[194:197], v[108:111]
	v_mfma_f32_16x16x32_bf16 v[44:47], v[140:143], v[194:197], v[44:47]
	v_mfma_f32_16x16x32_bf16 v[104:107], v[132:135], v[210:213], v[104:107]
	v_mfma_f32_16x16x32_bf16 v[32:35], v[140:143], v[210:213], v[32:35]
	v_mfma_f32_16x16x32_bf16 v[120:123], v[144:147], v[160:163], v[120:123]
	v_mfma_f32_16x16x32_bf16 v[60:63], v[152:155], v[160:163], v[60:63]
	v_mfma_f32_16x16x32_bf16 v[112:115], v[144:147], v[168:171], v[112:115]
	v_mfma_f32_16x16x32_bf16 v[48:51], v[152:155], v[168:171], v[48:51]
	v_mfma_f32_16x16x32_bf16 v[100:103], v[144:147], v[190:193], v[100:103]
	v_mfma_f32_16x16x32_bf16 v[40:43], v[152:155], v[190:193], v[40:43]
	v_mfma_f32_16x16x32_bf16 v[96:99], v[144:147], v[198:201], v[96:99]
	v_mfma_f32_16x16x32_bf16 v[36:39], v[152:155], v[198:201], v[36:39]
	v_mfma_f32_16x16x32_bf16 v[120:123], v[148:151], v[164:167], v[120:123]
	v_mfma_f32_16x16x32_bf16 v[60:63], v[156:159], v[164:167], v[60:63]
	v_mfma_f32_16x16x32_bf16 v[112:115], v[148:151], v[172:175], v[112:115]
	v_mfma_f32_16x16x32_bf16 v[48:51], v[156:159], v[172:175], v[48:51]
	v_mfma_f32_16x16x32_bf16 v[100:103], v[148:151], v[194:197], v[100:103]
	v_mfma_f32_16x16x32_bf16 v[40:43], v[156:159], v[194:197], v[40:43]
	v_mfma_f32_16x16x32_bf16 v[96:99], v[148:151], v[210:213], v[96:99]
	s_setprio 0
	v_mfma_f32_16x16x32_bf16 v[36:39], v[156:159], v[210:213], v[36:39]
	s_barrier
	ds_read_b128 v[160:163], v209 offset:49152
	ds_read_b128 v[164:167], v209 offset:50176
	ds_read_b128 v[168:171], v209 offset:51200
	ds_read_b128 v[172:175], v209 offset:52224
	ds_read_b128 v[190:193], v209 offset:53248
	ds_read_b128 v[194:197], v209 offset:54272
	ds_read_b128 v[198:201], v209 offset:55296
	ds_read_b128 v[210:213], v209 offset:56320
	s_add_i32 s0, s2, s80
	s_mov_b32 m0, s0
	v_lshl_add_u64 v[202:203], v[202:203], 0, s[24:25]
	global_load_lds_dwordx4 v[202:203], off
	s_add_i32 m0, s0, 0x2000
	s_add_u32 s0, s8, 0x80080
	v_lshl_add_u64 v[202:203], v[214:215], 0, s[24:25]
	s_addc_u32 s1, s9, 0
	s_add_i32 s2, s3, s80
	global_load_lds_dwordx4 v[202:203], off
	s_mov_b32 m0, s2
	v_lshl_add_u64 v[202:203], s[0:1], 0, v[180:181]
	global_load_lds_dwordx4 v[202:203], off
	s_add_i32 m0, s2, 0x2000
	v_lshl_add_u64 v[202:203], s[0:1], 0, v[184:185]
	global_load_lds_dwordx4 v[202:203], off
	s_mov_b32 m0, s90
	v_lshl_add_u64 v[202:203], v[216:217], 0, s[24:25]
	global_load_lds_dwordx4 v[202:203], off
	s_mov_b32 m0, s91
	v_lshl_add_u64 v[202:203], v[218:219], 0, s[24:25]
	global_load_lds_dwordx4 v[202:203], off
	s_waitcnt vmcnt(8) lgkmcnt(0)
	s_setprio 1
	s_barrier
	v_mfma_f32_16x16x32_bf16 v[92:95], v[128:131], v[160:163], v[92:95]
	v_mfma_f32_16x16x32_bf16 v[24:27], v[136:139], v[160:163], v[24:27]
	v_mfma_f32_16x16x32_bf16 v[84:87], v[128:131], v[168:171], v[84:87]
	v_mfma_f32_16x16x32_bf16 v[20:23], v[136:139], v[168:171], v[20:23]
	v_mfma_f32_16x16x32_bf16 v[76:79], v[128:131], v[190:193], v[76:79]
	v_mfma_f32_16x16x32_bf16 v[12:15], v[136:139], v[190:193], v[12:15]
	v_mfma_f32_16x16x32_bf16 v[72:75], v[128:131], v[198:201], v[72:75]
	v_mfma_f32_16x16x32_bf16 v[0:3], v[136:139], v[198:201], v[0:3]
	v_mfma_f32_16x16x32_bf16 v[92:95], v[132:135], v[164:167], v[92:95]
	v_mfma_f32_16x16x32_bf16 v[24:27], v[140:143], v[164:167], v[24:27]
	v_mfma_f32_16x16x32_bf16 v[84:87], v[132:135], v[172:175], v[84:87]
	v_mfma_f32_16x16x32_bf16 v[20:23], v[140:143], v[172:175], v[20:23]
	v_mfma_f32_16x16x32_bf16 v[76:79], v[132:135], v[194:197], v[76:79]
	v_mfma_f32_16x16x32_bf16 v[12:15], v[140:143], v[194:197], v[12:15]
	v_mfma_f32_16x16x32_bf16 v[72:75], v[132:135], v[210:213], v[72:75]
	v_mfma_f32_16x16x32_bf16 v[0:3], v[140:143], v[210:213], v[0:3]
	v_mfma_f32_16x16x32_bf16 v[88:91], v[144:147], v[160:163], v[88:91]
	v_mfma_f32_16x16x32_bf16 v[28:31], v[152:155], v[160:163], v[28:31]
	v_mfma_f32_16x16x32_bf16 v[80:83], v[144:147], v[168:171], v[80:83]
	v_mfma_f32_16x16x32_bf16 v[16:19], v[152:155], v[168:171], v[16:19]
	v_mfma_f32_16x16x32_bf16 v[68:71], v[144:147], v[190:193], v[68:71]
	v_mfma_f32_16x16x32_bf16 v[8:11], v[152:155], v[190:193], v[8:11]
	v_mfma_f32_16x16x32_bf16 v[64:67], v[144:147], v[198:201], v[64:67]
	v_mfma_f32_16x16x32_bf16 v[4:7], v[152:155], v[198:201], v[4:7]
	v_mfma_f32_16x16x32_bf16 v[88:91], v[148:151], v[164:167], v[88:91]
	s_add_i32 vcc_hi, vcc_hi, 2
	v_mfma_f32_16x16x32_bf16 v[28:31], v[156:159], v[164:167], v[28:31]
	s_add_u32 s4, s4, 0x100
	v_mfma_f32_16x16x32_bf16 v[80:83], v[148:151], v[172:175], v[80:83]
	s_addc_u32 s5, s5, 0
	v_mfma_f32_16x16x32_bf16 v[16:19], v[156:159], v[172:175], v[16:19]
	s_add_u32 s65, s65, 0x100
	v_mfma_f32_16x16x32_bf16 v[68:71], v[148:151], v[194:197], v[68:71]
	s_addc_u32 vcc_lo, vcc_lo, 0
	v_mfma_f32_16x16x32_bf16 v[8:11], v[156:159], v[194:197], v[8:11]
	s_cmp_gt_u32 vcc_hi, 29
	v_mfma_f32_16x16x32_bf16 v[64:67], v[148:151], v[210:213], v[64:67]
	s_setprio 0
	v_mfma_f32_16x16x32_bf16 v[4:7], v[156:159], v[210:213], v[4:7]
	s_barrier
	s_cbranch_scc0 .LBB0_399
	s_and_b64 vcc, exec, s[26:27]
	s_cbranch_vccz .LBB0_402
	s_barrier

.LBB0_541:
	ds_read_b128 v[128:131], v157
	ds_read_b128 v[132:135], v157 offset:1024
	ds_read_b128 v[136:139], v157 offset:2048
	ds_read_b128 v[140:143], v157 offset:3072
	ds_read_b128 v[160:163], v158
	ds_read_b128 v[164:167], v158 offset:1024
	ds_read_b128 v[168:171], v158 offset:2048
	ds_read_b128 v[172:175], v158 offset:3072
	ds_read_b128 v[178:181], v159
	ds_read_b128 v[182:185], v159 offset:1024
	ds_read_b128 v[186:189], v159 offset:2048
	ds_read_b128 v[190:193], v159 offset:3072
	ds_read_b128 v[194:197], v159 offset:4096
	ds_read_b128 v[206:209], v159 offset:5120
	ds_read_b128 v[210:213], v159 offset:6144
	ds_read_b128 v[214:217], v159 offset:7168
	s_add_u32 s58, s56, 0x100
	s_addc_u32 s59, s57, 0
	s_cmpk_eq_i32 s89, 0x54
	s_cselect_b32 s63, s12, s59
	s_cselect_b32 s62, s55, s58
	s_cselect_b32 s61, s85, s88
	s_cselect_b32 s60, s86, s87
	s_add_i32 m0, s66, 0xc000
	v_lshl_add_u64 v[152:153], s[56:57], 0, v[148:149]
	global_load_lds_dwordx4 v[152:153], off
	s_add_i32 m0, s66, 0xe000
	v_lshl_add_u64 v[152:153], s[56:57], 0, v[150:151]
	global_load_lds_dwordx4 v[152:153], off
	s_waitcnt vmcnt(8) lgkmcnt(0)
	s_setprio 1
	s_barrier
	v_mfma_f32_16x16x32_bf16 v[124:127], v[128:131], v[178:181], v[124:127]
	v_mfma_f32_16x16x32_bf16 v[120:123], v[136:139], v[178:181], v[120:123]
	v_mfma_f32_16x16x32_bf16 v[112:115], v[128:131], v[186:189], v[112:115]
	v_mfma_f32_16x16x32_bf16 v[108:111], v[136:139], v[186:189], v[108:111]
	v_mfma_f32_16x16x32_bf16 v[96:99], v[128:131], v[194:197], v[96:99]
	v_mfma_f32_16x16x32_bf16 v[92:95], v[136:139], v[194:197], v[92:95]
	v_mfma_f32_16x16x32_bf16 v[80:83], v[128:131], v[210:213], v[80:83]
	v_mfma_f32_16x16x32_bf16 v[76:79], v[136:139], v[210:213], v[76:79]
	v_mfma_f32_16x16x32_bf16 v[124:127], v[132:135], v[182:185], v[124:127]
	v_mfma_f32_16x16x32_bf16 v[120:123], v[140:143], v[182:185], v[120:123]
	v_mfma_f32_16x16x32_bf16 v[112:115], v[132:135], v[190:193], v[112:115]
	v_mfma_f32_16x16x32_bf16 v[108:111], v[140:143], v[190:193], v[108:111]
	v_mfma_f32_16x16x32_bf16 v[96:99], v[132:135], v[206:209], v[96:99]
	v_mfma_f32_16x16x32_bf16 v[92:95], v[140:143], v[206:209], v[92:95]
	v_mfma_f32_16x16x32_bf16 v[80:83], v[132:135], v[214:217], v[80:83]
	v_mfma_f32_16x16x32_bf16 v[76:79], v[140:143], v[214:217], v[76:79]
	v_mfma_f32_16x16x32_bf16 v[116:119], v[160:163], v[178:181], v[116:119]
	v_mfma_f32_16x16x32_bf16 v[104:107], v[168:171], v[178:181], v[104:107]
	v_mfma_f32_16x16x32_bf16 v[100:103], v[160:163], v[186:189], v[100:103]
	v_mfma_f32_16x16x32_bf16 v[88:91], v[168:171], v[186:189], v[88:91]
	v_mfma_f32_16x16x32_bf16 v[84:87], v[160:163], v[194:197], v[84:87]
	v_mfma_f32_16x16x32_bf16 v[72:75], v[168:171], v[194:197], v[72:75]
	v_mfma_f32_16x16x32_bf16 v[68:71], v[160:163], v[210:213], v[68:71]
	v_mfma_f32_16x16x32_bf16 v[64:67], v[168:171], v[210:213], v[64:67]
	v_mfma_f32_16x16x32_bf16 v[116:119], v[164:167], v[182:185], v[116:119]
	v_mfma_f32_16x16x32_bf16 v[104:107], v[172:175], v[182:185], v[104:107]
	v_mfma_f32_16x16x32_bf16 v[100:103], v[164:167], v[190:193], v[100:103]
	v_mfma_f32_16x16x32_bf16 v[88:91], v[172:175], v[190:193], v[88:91]
	v_mfma_f32_16x16x32_bf16 v[84:87], v[164:167], v[206:209], v[84:87]
	v_mfma_f32_16x16x32_bf16 v[72:75], v[172:175], v[206:209], v[72:75]
	v_mfma_f32_16x16x32_bf16 v[68:71], v[164:167], v[214:217], v[68:71]
	s_setprio 0
	v_mfma_f32_16x16x32_bf16 v[64:67], v[172:175], v[214:217], v[64:67]
	s_barrier
	ds_read_b128 v[178:181], v159 offset:16384
	ds_read_b128 v[182:185], v159 offset:17408
	ds_read_b128 v[186:189], v159 offset:18432
	ds_read_b128 v[190:193], v159 offset:19456
	ds_read_b128 v[194:197], v159 offset:20480
	ds_read_b128 v[206:209], v159 offset:21504
	ds_read_b128 v[210:213], v159 offset:22528
	ds_read_b128 v[214:217], v159 offset:23552
	s_add_i32 s0, s79, s65
	s_mov_b32 m0, s0
	v_lshl_add_u64 v[152:153], s[60:61], 0, v[146:147]
	global_load_lds_dwordx4 v[152:153], off
	s_add_i32 m0, s0, 0x2000
	s_add_u32 s0, s60, 0x160000
	v_lshl_add_u64 v[198:199], s[60:61], 0, v[144:145]
	s_addc_u32 s1, s61, 0
	s_add_i32 s2, s80, s65
	global_load_lds_dwordx4 v[198:199], off
	v_lshl_add_u64 v[202:203], s[0:1], 0, v[146:147]
	s_mov_b32 m0, s2
	v_lshl_add_u64 v[218:219], s[62:63], 0, v[144:145]
	global_load_lds_dwordx4 v[202:203], off
	s_add_i32 m0, s2, 0x2000
	v_lshl_add_u64 v[202:203], s[0:1], 0, v[144:145]
	global_load_lds_dwordx4 v[202:203], off
	s_mov_b32 m0, s66
	v_lshl_add_u64 v[202:203], s[62:63], 0, v[146:147]
	global_load_lds_dwordx4 v[202:203], off
	s_mov_b32 m0, s67
	s_nop 0
	global_load_lds_dwordx4 v[218:219], off
	s_waitcnt vmcnt(8) lgkmcnt(0)
	s_setprio 1
	s_barrier
	v_mfma_f32_16x16x32_bf16 v[60:63], v[128:131], v[178:181], v[60:63]
	v_mfma_f32_16x16x32_bf16 v[56:59], v[136:139], v[178:181], v[56:59]
	v_mfma_f32_16x16x32_bf16 v[48:51], v[128:131], v[186:189], v[48:51]
	v_mfma_f32_16x16x32_bf16 v[44:47], v[136:139], v[186:189], v[44:47]
	v_mfma_f32_16x16x32_bf16 v[32:35], v[128:131], v[194:197], v[32:35]
	v_mfma_f32_16x16x32_bf16 v[28:31], v[136:139], v[194:197], v[28:31]
	v_mfma_f32_16x16x32_bf16 v[16:19], v[128:131], v[210:213], v[16:19]
	v_mfma_f32_16x16x32_bf16 v[12:15], v[136:139], v[210:213], v[12:15]
	v_mfma_f32_16x16x32_bf16 v[60:63], v[132:135], v[182:185], v[60:63]
	v_mfma_f32_16x16x32_bf16 v[56:59], v[140:143], v[182:185], v[56:59]
	v_mfma_f32_16x16x32_bf16 v[48:51], v[132:135], v[190:193], v[48:51]
	v_mfma_f32_16x16x32_bf16 v[44:47], v[140:143], v[190:193], v[44:47]
	v_mfma_f32_16x16x32_bf16 v[32:35], v[132:135], v[206:209], v[32:35]
	v_mfma_f32_16x16x32_bf16 v[28:31], v[140:143], v[206:209], v[28:31]
	v_mfma_f32_16x16x32_bf16 v[16:19], v[132:135], v[214:217], v[16:19]
	v_mfma_f32_16x16x32_bf16 v[12:15], v[140:143], v[214:217], v[12:15]
	v_mfma_f32_16x16x32_bf16 v[52:55], v[160:163], v[178:181], v[52:55]
	v_mfma_f32_16x16x32_bf16 v[40:43], v[168:171], v[178:181], v[40:43]
	v_mfma_f32_16x16x32_bf16 v[36:39], v[160:163], v[186:189], v[36:39]
	v_mfma_f32_16x16x32_bf16 v[24:27], v[168:171], v[186:189], v[24:27]
	v_mfma_f32_16x16x32_bf16 v[20:23], v[160:163], v[194:197], v[20:23]
	v_mfma_f32_16x16x32_bf16 v[8:11], v[168:171], v[194:197], v[8:11]
	v_mfma_f32_16x16x32_bf16 v[4:7], v[160:163], v[210:213], v[4:7]
	v_mfma_f32_16x16x32_bf16 v[0:3], v[168:171], v[210:213], v[0:3]
	v_mfma_f32_16x16x32_bf16 v[52:55], v[164:167], v[182:185], v[52:55]
	v_mfma_f32_16x16x32_bf16 v[40:43], v[172:175], v[182:185], v[40:43]
	v_mfma_f32_16x16x32_bf16 v[36:39], v[164:167], v[190:193], v[36:39]
	v_mfma_f32_16x16x32_bf16 v[24:27], v[172:175], v[190:193], v[24:27]
	v_mfma_f32_16x16x32_bf16 v[20:23], v[164:167], v[206:209], v[20:23]
	v_mfma_f32_16x16x32_bf16 v[8:11], v[172:175], v[206:209], v[8:11]
	v_mfma_f32_16x16x32_bf16 v[4:7], v[164:167], v[214:217], v[4:7]
	s_setprio 0
	v_mfma_f32_16x16x32_bf16 v[0:3], v[172:175], v[214:217], v[0:3]
	s_barrier
	ds_read_b128 v[178:181], v159 offset:32768
	ds_read_b128 v[182:185], v159 offset:33792
	ds_read_b128 v[186:189], v159 offset:34816
	ds_read_b128 v[190:193], v159 offset:35840
	ds_read_b128 v[194:197], v159 offset:36864
	ds_read_b128 v[206:209], v159 offset:37888
	ds_read_b128 v[210:213], v159 offset:38912
	ds_read_b128 v[214:217], v159 offset:39936
	s_add_i32 s2, 0, 0x18000
	s_add_i32 s3, 0, 0x1c000
	v_add_u32_e32 v140, s2, v156
	v_add_u32_e32 v172, s3, v156
	ds_read_b128 v[128:131], v140
	ds_read_b128 v[132:135], v140 offset:1024
	ds_read_b128 v[136:139], v140 offset:2048
	ds_read_b128 v[140:143], v140 offset:3072
	ds_read_b128 v[160:163], v172
	ds_read_b128 v[164:167], v172 offset:1024
	ds_read_b128 v[168:171], v172 offset:2048
	ds_read_b128 v[172:175], v172 offset:3072
	s_add_u32 s0, s62, 0x160000
	s_addc_u32 s1, s63, 0
	s_mov_b32 m0, s68
	v_lshl_add_u64 v[220:221], s[0:1], 0, v[146:147]
	global_load_lds_dwordx4 v[220:221], off
	s_mov_b32 m0, s69
	v_lshl_add_u64 v[220:221], s[0:1], 0, v[144:145]
	global_load_lds_dwordx4 v[220:221], off
	s_waitcnt vmcnt(8) lgkmcnt(0)
	s_setprio 1
	s_barrier
	v_mfma_f32_16x16x32_bf16 v[124:127], v[128:131], v[178:181], v[124:127]
	v_mfma_f32_16x16x32_bf16 v[120:123], v[136:139], v[178:181], v[120:123]
	v_mfma_f32_16x16x32_bf16 v[112:115], v[128:131], v[186:189], v[112:115]
	v_mfma_f32_16x16x32_bf16 v[108:111], v[136:139], v[186:189], v[108:111]
	v_mfma_f32_16x16x32_bf16 v[96:99], v[128:131], v[194:197], v[96:99]
	v_mfma_f32_16x16x32_bf16 v[92:95], v[136:139], v[194:197], v[92:95]
	v_mfma_f32_16x16x32_bf16 v[80:83], v[128:131], v[210:213], v[80:83]
	v_mfma_f32_16x16x32_bf16 v[76:79], v[136:139], v[210:213], v[76:79]
	v_mfma_f32_16x16x32_bf16 v[124:127], v[132:135], v[182:185], v[124:127]
	v_mfma_f32_16x16x32_bf16 v[120:123], v[140:143], v[182:185], v[120:123]
	v_mfma_f32_16x16x32_bf16 v[112:115], v[132:135], v[190:193], v[112:115]
	v_mfma_f32_16x16x32_bf16 v[108:111], v[140:143], v[190:193], v[108:111]
	v_mfma_f32_16x16x32_bf16 v[96:99], v[132:135], v[206:209], v[96:99]
	v_mfma_f32_16x16x32_bf16 v[92:95], v[140:143], v[206:209], v[92:95]
	v_mfma_f32_16x16x32_bf16 v[80:83], v[132:135], v[214:217], v[80:83]
	v_mfma_f32_16x16x32_bf16 v[76:79], v[140:143], v[214:217], v[76:79]
	v_mfma_f32_16x16x32_bf16 v[116:119], v[160:163], v[178:181], v[116:119]
	v_mfma_f32_16x16x32_bf16 v[104:107], v[168:171], v[178:181], v[104:107]
	v_mfma_f32_16x16x32_bf16 v[100:103], v[160:163], v[186:189], v[100:103]
	v_mfma_f32_16x16x32_bf16 v[88:91], v[168:171], v[186:189], v[88:91]
	v_mfma_f32_16x16x32_bf16 v[84:87], v[160:163], v[194:197], v[84:87]
	v_mfma_f32_16x16x32_bf16 v[72:75], v[168:171], v[194:197], v[72:75]
	v_mfma_f32_16x16x32_bf16 v[68:71], v[160:163], v[210:213], v[68:71]
	v_mfma_f32_16x16x32_bf16 v[64:67], v[168:171], v[210:213], v[64:67]
	v_mfma_f32_16x16x32_bf16 v[116:119], v[164:167], v[182:185], v[116:119]
	v_mfma_f32_16x16x32_bf16 v[104:107], v[172:175], v[182:185], v[104:107]
	v_mfma_f32_16x16x32_bf16 v[100:103], v[164:167], v[190:193], v[100:103]
	v_mfma_f32_16x16x32_bf16 v[88:91], v[172:175], v[190:193], v[88:91]
	v_mfma_f32_16x16x32_bf16 v[84:87], v[164:167], v[206:209], v[84:87]
	v_mfma_f32_16x16x32_bf16 v[72:75], v[172:175], v[206:209], v[72:75]
	v_mfma_f32_16x16x32_bf16 v[68:71], v[164:167], v[214:217], v[68:71]
	s_setprio 0
	v_mfma_f32_16x16x32_bf16 v[64:67], v[172:175], v[214:217], v[64:67]
	s_barrier
	ds_read_b128 v[178:181], v159 offset:49152
	ds_read_b128 v[182:185], v159 offset:50176
	ds_read_b128 v[186:189], v159 offset:51200
	ds_read_b128 v[190:193], v159 offset:52224
	ds_read_b128 v[194:197], v159 offset:53248
	ds_read_b128 v[206:209], v159 offset:54272
	ds_read_b128 v[210:213], v159 offset:55296
	ds_read_b128 v[214:217], v159 offset:56320
	s_add_i32 s0, s2, s65
	s_mov_b32 m0, s0
	v_lshl_add_u64 v[152:153], v[152:153], 0, s[10:11]
	global_load_lds_dwordx4 v[152:153], off
	s_add_i32 m0, s0, 0x2000
	s_add_u32 s0, s60, 0x160080
	v_lshl_add_u64 v[152:153], v[198:199], 0, s[10:11]
	s_addc_u32 s1, s61, 0
	s_add_i32 s2, s3, s65
	global_load_lds_dwordx4 v[152:153], off
	s_mov_b32 m0, s2
	v_lshl_add_u64 v[152:153], s[0:1], 0, v[146:147]
	global_load_lds_dwordx4 v[152:153], off
	s_add_i32 m0, s2, 0x2000
	v_lshl_add_u64 v[152:153], s[0:1], 0, v[144:145]
	global_load_lds_dwordx4 v[152:153], off
	s_mov_b32 m0, s77
	v_lshl_add_u64 v[152:153], v[202:203], 0, s[10:11]
	global_load_lds_dwordx4 v[152:153], off
	s_mov_b32 m0, s78
	v_lshl_add_u64 v[152:153], v[218:219], 0, s[10:11]
	global_load_lds_dwordx4 v[152:153], off
	s_waitcnt vmcnt(8) lgkmcnt(0)
	s_setprio 1
	s_barrier
	v_mfma_f32_16x16x32_bf16 v[60:63], v[128:131], v[178:181], v[60:63]
	v_mfma_f32_16x16x32_bf16 v[56:59], v[136:139], v[178:181], v[56:59]
	v_mfma_f32_16x16x32_bf16 v[48:51], v[128:131], v[186:189], v[48:51]
	v_mfma_f32_16x16x32_bf16 v[44:47], v[136:139], v[186:189], v[44:47]
	v_mfma_f32_16x16x32_bf16 v[32:35], v[128:131], v[194:197], v[32:35]
	v_mfma_f32_16x16x32_bf16 v[28:31], v[136:139], v[194:197], v[28:31]
	v_mfma_f32_16x16x32_bf16 v[16:19], v[128:131], v[210:213], v[16:19]
	v_mfma_f32_16x16x32_bf16 v[12:15], v[136:139], v[210:213], v[12:15]
	v_mfma_f32_16x16x32_bf16 v[60:63], v[132:135], v[182:185], v[60:63]
	v_mfma_f32_16x16x32_bf16 v[56:59], v[140:143], v[182:185], v[56:59]
	v_mfma_f32_16x16x32_bf16 v[48:51], v[132:135], v[190:193], v[48:51]
	v_mfma_f32_16x16x32_bf16 v[44:47], v[140:143], v[190:193], v[44:47]
	v_mfma_f32_16x16x32_bf16 v[32:35], v[132:135], v[206:209], v[32:35]
	v_mfma_f32_16x16x32_bf16 v[28:31], v[140:143], v[206:209], v[28:31]
	v_mfma_f32_16x16x32_bf16 v[16:19], v[132:135], v[214:217], v[16:19]
	v_mfma_f32_16x16x32_bf16 v[12:15], v[140:143], v[214:217], v[12:15]
	v_mfma_f32_16x16x32_bf16 v[52:55], v[160:163], v[178:181], v[52:55]
	v_mfma_f32_16x16x32_bf16 v[40:43], v[168:171], v[178:181], v[40:43]
	v_mfma_f32_16x16x32_bf16 v[36:39], v[160:163], v[186:189], v[36:39]
	v_mfma_f32_16x16x32_bf16 v[24:27], v[168:171], v[186:189], v[24:27]
	v_mfma_f32_16x16x32_bf16 v[20:23], v[160:163], v[194:197], v[20:23]
	v_mfma_f32_16x16x32_bf16 v[8:11], v[168:171], v[194:197], v[8:11]
	v_mfma_f32_16x16x32_bf16 v[4:7], v[160:163], v[210:213], v[4:7]
	v_mfma_f32_16x16x32_bf16 v[0:3], v[168:171], v[210:213], v[0:3]
	v_mfma_f32_16x16x32_bf16 v[52:55], v[164:167], v[182:185], v[52:55]
	v_mfma_f32_16x16x32_bf16 v[40:43], v[172:175], v[182:185], v[40:43]
	s_add_i32 s89, s89, 2
	v_mfma_f32_16x16x32_bf16 v[36:39], v[164:167], v[190:193], v[36:39]
	s_add_u32 s87, s87, 0x100
	v_mfma_f32_16x16x32_bf16 v[24:27], v[172:175], v[190:193], v[24:27]
	s_addc_u32 s88, s88, 0
	v_mfma_f32_16x16x32_bf16 v[20:23], v[164:167], v[206:209], v[20:23]
	s_cmpk_gt_u32 s89, 0x55
	v_mfma_f32_16x16x32_bf16 v[8:11], v[172:175], v[206:209], v[8:11]
	s_mov_b64 s[56:57], s[58:59]
	v_mfma_f32_16x16x32_bf16 v[4:7], v[164:167], v[214:217], v[4:7]
	s_setprio 0
	v_mfma_f32_16x16x32_bf16 v[0:3], v[172:175], v[214:217], v[0:3]
	s_barrier
	s_cbranch_scc0 .LBB0_541
	s_and_b64 vcc, exec, s[14:15]
	s_cbranch_vccz .LBB0_544
	s_barrier

.LBB0_666:
	ds_read_b128 v[140:143], v147
	ds_read_b128 v[150:153], v147 offset:1024
	ds_read_b128 v[154:157], v147 offset:2048
	ds_read_b128 v[158:161], v147 offset:3072
	ds_read_b128 v[162:165], v148
	ds_read_b128 v[166:169], v148 offset:1024
	ds_read_b128 v[170:173], v148 offset:2048
	ds_read_b128 v[178:181], v148 offset:3072
	ds_read_b128 v[182:185], v149
	ds_read_b128 v[186:189], v149 offset:1024
	ds_read_b128 v[190:193], v149 offset:2048
	ds_read_b128 v[194:197], v149 offset:3072
	ds_read_b128 v[206:209], v149 offset:4096
	ds_read_b128 v[210:213], v149 offset:5120
	ds_read_b128 v[214:217], v149 offset:6144
	ds_read_b128 v[218:221], v149 offset:7168
	s_add_u32 s0, s28, 0xfff80080
	s_addc_u32 s1, s29, -1
	s_cmp_eq_u32 s71, 28
	s_cselect_b32 s35, s15, s1
	s_cselect_b32 s34, s66, s0
	s_cselect_b32 s31, s67, s70
	s_cselect_b32 s30, s68, s69
	s_add_i32 m0, s27, 0xc000
	v_lshl_add_u64 v[174:175], s[28:29], 0, v[136:137]
	global_load_lds_dwordx4 v[174:175], off
	s_add_i32 m0, s27, 0xe000
	v_lshl_add_u64 v[174:175], s[28:29], 0, v[138:139]
	global_load_lds_dwordx4 v[174:175], off
	s_waitcnt vmcnt(8) lgkmcnt(0)
	s_setprio 1
	s_barrier
	v_mfma_f32_16x16x32_bf16 v[124:127], v[140:143], v[182:185], v[124:127]
	v_mfma_f32_16x16x32_bf16 v[120:123], v[154:157], v[182:185], v[120:123]
	v_mfma_f32_16x16x32_bf16 v[116:119], v[140:143], v[190:193], v[116:119]
	v_mfma_f32_16x16x32_bf16 v[108:111], v[154:157], v[190:193], v[108:111]
	v_mfma_f32_16x16x32_bf16 v[100:103], v[140:143], v[206:209], v[100:103]
	v_mfma_f32_16x16x32_bf16 v[92:95], v[154:157], v[206:209], v[92:95]
	v_mfma_f32_16x16x32_bf16 v[84:87], v[140:143], v[214:217], v[84:87]
	v_mfma_f32_16x16x32_bf16 v[76:79], v[154:157], v[214:217], v[76:79]
	v_mfma_f32_16x16x32_bf16 v[124:127], v[150:153], v[186:189], v[124:127]
	v_mfma_f32_16x16x32_bf16 v[120:123], v[158:161], v[186:189], v[120:123]
	v_mfma_f32_16x16x32_bf16 v[116:119], v[150:153], v[194:197], v[116:119]
	v_mfma_f32_16x16x32_bf16 v[108:111], v[158:161], v[194:197], v[108:111]
	v_mfma_f32_16x16x32_bf16 v[100:103], v[150:153], v[210:213], v[100:103]
	v_mfma_f32_16x16x32_bf16 v[92:95], v[158:161], v[210:213], v[92:95]
	v_mfma_f32_16x16x32_bf16 v[84:87], v[150:153], v[218:221], v[84:87]
	v_mfma_f32_16x16x32_bf16 v[76:79], v[158:161], v[218:221], v[76:79]
	v_mfma_f32_16x16x32_bf16 v[112:115], v[162:165], v[182:185], v[112:115]
	v_mfma_f32_16x16x32_bf16 v[104:107], v[170:173], v[182:185], v[104:107]
	v_mfma_f32_16x16x32_bf16 v[96:99], v[162:165], v[190:193], v[96:99]
	v_mfma_f32_16x16x32_bf16 v[88:91], v[170:173], v[190:193], v[88:91]
	v_mfma_f32_16x16x32_bf16 v[80:83], v[162:165], v[206:209], v[80:83]
	v_mfma_f32_16x16x32_bf16 v[72:75], v[170:173], v[206:209], v[72:75]
	v_mfma_f32_16x16x32_bf16 v[68:71], v[162:165], v[214:217], v[68:71]
	v_mfma_f32_16x16x32_bf16 v[64:67], v[170:173], v[214:217], v[64:67]
	v_mfma_f32_16x16x32_bf16 v[112:115], v[166:169], v[186:189], v[112:115]
	v_mfma_f32_16x16x32_bf16 v[104:107], v[178:181], v[186:189], v[104:107]
	v_mfma_f32_16x16x32_bf16 v[96:99], v[166:169], v[194:197], v[96:99]
	v_mfma_f32_16x16x32_bf16 v[88:91], v[178:181], v[194:197], v[88:91]
	v_mfma_f32_16x16x32_bf16 v[80:83], v[166:169], v[210:213], v[80:83]
	v_mfma_f32_16x16x32_bf16 v[72:75], v[178:181], v[210:213], v[72:75]
	v_mfma_f32_16x16x32_bf16 v[68:71], v[166:169], v[218:221], v[68:71]
	s_setprio 0
	v_mfma_f32_16x16x32_bf16 v[64:67], v[178:181], v[218:221], v[64:67]
	s_barrier
	ds_read_b128 v[182:185], v149 offset:16384
	ds_read_b128 v[186:189], v149 offset:17408
	ds_read_b128 v[190:193], v149 offset:18432
	ds_read_b128 v[194:197], v149 offset:19456
	ds_read_b128 v[206:209], v149 offset:20480
	ds_read_b128 v[210:213], v149 offset:21504
	ds_read_b128 v[214:217], v149 offset:22528
	ds_read_b128 v[218:221], v149 offset:23552
	s_add_i32 s0, s62, s53
	s_mov_b32 m0, s0
	v_lshl_add_u64 v[174:175], s[30:31], 0, v[132:133]
	global_load_lds_dwordx4 v[174:175], off
	s_add_i32 m0, s0, 0x2000
	s_add_u32 s0, s30, 0x80000
	v_lshl_add_u64 v[198:199], s[30:31], 0, v[128:129]
	s_addc_u32 s1, s31, 0
	s_add_i32 s2, s63, s53
	global_load_lds_dwordx4 v[198:199], off
	v_lshl_add_u64 v[202:203], s[0:1], 0, v[132:133]
	s_mov_b32 m0, s2
	v_lshl_add_u64 v[222:223], s[34:35], 0, v[130:131]
	global_load_lds_dwordx4 v[202:203], off
	s_add_i32 m0, s2, 0x2000
	v_lshl_add_u64 v[202:203], s[0:1], 0, v[128:129]
	global_load_lds_dwordx4 v[202:203], off
	s_mov_b32 m0, s27
	v_lshl_add_u64 v[202:203], s[34:35], 0, v[134:135]
	global_load_lds_dwordx4 v[202:203], off
	s_mov_b32 m0, s55
	s_nop 0
	global_load_lds_dwordx4 v[222:223], off
	s_waitcnt vmcnt(8) lgkmcnt(0)
	s_setprio 1
	s_barrier
	v_mfma_f32_16x16x32_bf16 v[60:63], v[140:143], v[182:185], v[60:63]
	v_mfma_f32_16x16x32_bf16 v[56:59], v[154:157], v[182:185], v[56:59]
	v_mfma_f32_16x16x32_bf16 v[52:55], v[140:143], v[190:193], v[52:55]
	v_mfma_f32_16x16x32_bf16 v[44:47], v[154:157], v[190:193], v[44:47]
	v_mfma_f32_16x16x32_bf16 v[36:39], v[140:143], v[206:209], v[36:39]
	v_mfma_f32_16x16x32_bf16 v[28:31], v[154:157], v[206:209], v[28:31]
	v_mfma_f32_16x16x32_bf16 v[20:23], v[140:143], v[214:217], v[20:23]
	v_mfma_f32_16x16x32_bf16 v[12:15], v[154:157], v[214:217], v[12:15]
	v_mfma_f32_16x16x32_bf16 v[60:63], v[150:153], v[186:189], v[60:63]
	v_mfma_f32_16x16x32_bf16 v[56:59], v[158:161], v[186:189], v[56:59]
	v_mfma_f32_16x16x32_bf16 v[52:55], v[150:153], v[194:197], v[52:55]
	v_mfma_f32_16x16x32_bf16 v[44:47], v[158:161], v[194:197], v[44:47]
	v_mfma_f32_16x16x32_bf16 v[36:39], v[150:153], v[210:213], v[36:39]
	v_mfma_f32_16x16x32_bf16 v[28:31], v[158:161], v[210:213], v[28:31]
	v_mfma_f32_16x16x32_bf16 v[20:23], v[150:153], v[218:221], v[20:23]
	v_mfma_f32_16x16x32_bf16 v[12:15], v[158:161], v[218:221], v[12:15]
	v_mfma_f32_16x16x32_bf16 v[48:51], v[162:165], v[182:185], v[48:51]
	v_mfma_f32_16x16x32_bf16 v[40:43], v[170:173], v[182:185], v[40:43]
	v_mfma_f32_16x16x32_bf16 v[32:35], v[162:165], v[190:193], v[32:35]
	v_mfma_f32_16x16x32_bf16 v[24:27], v[170:173], v[190:193], v[24:27]
	v_mfma_f32_16x16x32_bf16 v[16:19], v[162:165], v[206:209], v[16:19]
	v_mfma_f32_16x16x32_bf16 v[8:11], v[170:173], v[206:209], v[8:11]
	v_mfma_f32_16x16x32_bf16 v[4:7], v[162:165], v[214:217], v[4:7]
	v_mfma_f32_16x16x32_bf16 v[0:3], v[170:173], v[214:217], v[0:3]
	v_mfma_f32_16x16x32_bf16 v[48:51], v[166:169], v[186:189], v[48:51]
	v_mfma_f32_16x16x32_bf16 v[40:43], v[178:181], v[186:189], v[40:43]
	v_mfma_f32_16x16x32_bf16 v[32:35], v[166:169], v[194:197], v[32:35]
	v_mfma_f32_16x16x32_bf16 v[24:27], v[178:181], v[194:197], v[24:27]
	v_mfma_f32_16x16x32_bf16 v[16:19], v[166:169], v[210:213], v[16:19]
	v_mfma_f32_16x16x32_bf16 v[8:11], v[178:181], v[210:213], v[8:11]
	v_mfma_f32_16x16x32_bf16 v[4:7], v[166:169], v[218:221], v[4:7]
	s_setprio 0
	v_mfma_f32_16x16x32_bf16 v[0:3], v[178:181], v[218:221], v[0:3]
	s_barrier
	ds_read_b128 v[182:185], v149 offset:32768
	ds_read_b128 v[186:189], v149 offset:33792
	ds_read_b128 v[190:193], v149 offset:34816
	ds_read_b128 v[194:197], v149 offset:35840
	ds_read_b128 v[206:209], v149 offset:36864
	ds_read_b128 v[210:213], v149 offset:37888
	ds_read_b128 v[214:217], v149 offset:38912
	ds_read_b128 v[218:221], v149 offset:39936
	s_add_i32 s2, 0, 0x18000
	s_add_i32 s3, 0, 0x1c000
	v_add_u32_e32 v158, s2, v146
	v_add_u32_e32 v177, s3, v146
	ds_read_b128 v[140:143], v158
	ds_read_b128 v[150:153], v158 offset:1024
	ds_read_b128 v[154:157], v158 offset:2048
	ds_read_b128 v[158:161], v158 offset:3072
	ds_read_b128 v[162:165], v177
	ds_read_b128 v[166:169], v177 offset:1024
	ds_read_b128 v[170:173], v177 offset:2048
	ds_read_b128 v[178:181], v177 offset:3072
	s_add_u32 s0, s34, 0x80000
	s_addc_u32 s1, s35, 0
	s_mov_b32 m0, s56
	v_lshl_add_u64 v[224:225], s[0:1], 0, v[134:135]
	global_load_lds_dwordx4 v[224:225], off
	s_mov_b32 m0, s57
	v_lshl_add_u64 v[224:225], s[0:1], 0, v[130:131]
	global_load_lds_dwordx4 v[224:225], off
	s_waitcnt vmcnt(8) lgkmcnt(0)
	s_setprio 1
	s_barrier
	v_mfma_f32_16x16x32_bf16 v[124:127], v[140:143], v[182:185], v[124:127]
	v_mfma_f32_16x16x32_bf16 v[120:123], v[154:157], v[182:185], v[120:123]
	v_mfma_f32_16x16x32_bf16 v[116:119], v[140:143], v[190:193], v[116:119]
	v_mfma_f32_16x16x32_bf16 v[108:111], v[154:157], v[190:193], v[108:111]
	v_mfma_f32_16x16x32_bf16 v[100:103], v[140:143], v[206:209], v[100:103]
	v_mfma_f32_16x16x32_bf16 v[92:95], v[154:157], v[206:209], v[92:95]
	v_mfma_f32_16x16x32_bf16 v[84:87], v[140:143], v[214:217], v[84:87]
	v_mfma_f32_16x16x32_bf16 v[76:79], v[154:157], v[214:217], v[76:79]
	v_mfma_f32_16x16x32_bf16 v[124:127], v[150:153], v[186:189], v[124:127]
	v_mfma_f32_16x16x32_bf16 v[120:123], v[158:161], v[186:189], v[120:123]
	v_mfma_f32_16x16x32_bf16 v[116:119], v[150:153], v[194:197], v[116:119]
	v_mfma_f32_16x16x32_bf16 v[108:111], v[158:161], v[194:197], v[108:111]
	v_mfma_f32_16x16x32_bf16 v[100:103], v[150:153], v[210:213], v[100:103]
	v_mfma_f32_16x16x32_bf16 v[92:95], v[158:161], v[210:213], v[92:95]
	v_mfma_f32_16x16x32_bf16 v[84:87], v[150:153], v[218:221], v[84:87]
	v_mfma_f32_16x16x32_bf16 v[76:79], v[158:161], v[218:221], v[76:79]
	v_mfma_f32_16x16x32_bf16 v[112:115], v[162:165], v[182:185], v[112:115]
	v_mfma_f32_16x16x32_bf16 v[104:107], v[170:173], v[182:185], v[104:107]
	v_mfma_f32_16x16x32_bf16 v[96:99], v[162:165], v[190:193], v[96:99]
	v_mfma_f32_16x16x32_bf16 v[88:91], v[170:173], v[190:193], v[88:91]
	v_mfma_f32_16x16x32_bf16 v[80:83], v[162:165], v[206:209], v[80:83]
	v_mfma_f32_16x16x32_bf16 v[72:75], v[170:173], v[206:209], v[72:75]
	v_mfma_f32_16x16x32_bf16 v[68:71], v[162:165], v[214:217], v[68:71]
	v_mfma_f32_16x16x32_bf16 v[64:67], v[170:173], v[214:217], v[64:67]
	v_mfma_f32_16x16x32_bf16 v[112:115], v[166:169], v[186:189], v[112:115]
	v_mfma_f32_16x16x32_bf16 v[104:107], v[178:181], v[186:189], v[104:107]
	v_mfma_f32_16x16x32_bf16 v[96:99], v[166:169], v[194:197], v[96:99]
	v_mfma_f32_16x16x32_bf16 v[88:91], v[178:181], v[194:197], v[88:91]
	v_mfma_f32_16x16x32_bf16 v[80:83], v[166:169], v[210:213], v[80:83]
	v_mfma_f32_16x16x32_bf16 v[72:75], v[178:181], v[210:213], v[72:75]
	v_mfma_f32_16x16x32_bf16 v[68:71], v[166:169], v[218:221], v[68:71]
	s_setprio 0
	v_mfma_f32_16x16x32_bf16 v[64:67], v[178:181], v[218:221], v[64:67]
	s_barrier
	ds_read_b128 v[182:185], v149 offset:49152
	ds_read_b128 v[186:189], v149 offset:50176
	ds_read_b128 v[190:193], v149 offset:51200
	ds_read_b128 v[194:197], v149 offset:52224
	ds_read_b128 v[206:209], v149 offset:53248
	ds_read_b128 v[210:213], v149 offset:54272
	ds_read_b128 v[214:217], v149 offset:55296
	ds_read_b128 v[218:221], v149 offset:56320
	s_add_i32 s0, s2, s53
	s_mov_b32 m0, s0
	v_lshl_add_u64 v[174:175], v[174:175], 0, s[8:9]
	global_load_lds_dwordx4 v[174:175], off
	s_add_i32 m0, s0, 0x2000
	s_add_u32 s0, s30, 0x80080
	v_lshl_add_u64 v[174:175], v[198:199], 0, s[8:9]
	s_addc_u32 s1, s31, 0
	s_add_i32 s2, s3, s53
	global_load_lds_dwordx4 v[174:175], off
	s_mov_b32 m0, s2
	v_lshl_add_u64 v[174:175], s[0:1], 0, v[132:133]
	global_load_lds_dwordx4 v[174:175], off
	s_add_i32 m0, s2, 0x2000
	v_lshl_add_u64 v[174:175], s[0:1], 0, v[128:129]
	global_load_lds_dwordx4 v[174:175], off
	s_mov_b32 m0, s60
	v_lshl_add_u64 v[174:175], v[202:203], 0, s[8:9]
	global_load_lds_dwordx4 v[174:175], off
	s_mov_b32 m0, s61
	v_lshl_add_u64 v[174:175], v[222:223], 0, s[8:9]
	global_load_lds_dwordx4 v[174:175], off
	s_waitcnt vmcnt(8) lgkmcnt(0)
	s_setprio 1
	s_barrier
	v_mfma_f32_16x16x32_bf16 v[60:63], v[140:143], v[182:185], v[60:63]
	v_mfma_f32_16x16x32_bf16 v[56:59], v[154:157], v[182:185], v[56:59]
	v_mfma_f32_16x16x32_bf16 v[52:55], v[140:143], v[190:193], v[52:55]
	v_mfma_f32_16x16x32_bf16 v[44:47], v[154:157], v[190:193], v[44:47]
	v_mfma_f32_16x16x32_bf16 v[36:39], v[140:143], v[206:209], v[36:39]
	v_mfma_f32_16x16x32_bf16 v[28:31], v[154:157], v[206:209], v[28:31]
	v_mfma_f32_16x16x32_bf16 v[20:23], v[140:143], v[214:217], v[20:23]
	v_mfma_f32_16x16x32_bf16 v[12:15], v[154:157], v[214:217], v[12:15]
	v_mfma_f32_16x16x32_bf16 v[60:63], v[150:153], v[186:189], v[60:63]
	v_mfma_f32_16x16x32_bf16 v[56:59], v[158:161], v[186:189], v[56:59]
	v_mfma_f32_16x16x32_bf16 v[52:55], v[150:153], v[194:197], v[52:55]
	v_mfma_f32_16x16x32_bf16 v[44:47], v[158:161], v[194:197], v[44:47]
	v_mfma_f32_16x16x32_bf16 v[36:39], v[150:153], v[210:213], v[36:39]
	v_mfma_f32_16x16x32_bf16 v[28:31], v[158:161], v[210:213], v[28:31]
	v_mfma_f32_16x16x32_bf16 v[20:23], v[150:153], v[218:221], v[20:23]
	v_mfma_f32_16x16x32_bf16 v[12:15], v[158:161], v[218:221], v[12:15]
	v_mfma_f32_16x16x32_bf16 v[48:51], v[162:165], v[182:185], v[48:51]
	v_mfma_f32_16x16x32_bf16 v[40:43], v[170:173], v[182:185], v[40:43]
	v_mfma_f32_16x16x32_bf16 v[32:35], v[162:165], v[190:193], v[32:35]
	v_mfma_f32_16x16x32_bf16 v[24:27], v[170:173], v[190:193], v[24:27]
	v_mfma_f32_16x16x32_bf16 v[16:19], v[162:165], v[206:209], v[16:19]
	v_mfma_f32_16x16x32_bf16 v[8:11], v[170:173], v[206:209], v[8:11]
	v_mfma_f32_16x16x32_bf16 v[4:7], v[162:165], v[214:217], v[4:7]
	v_mfma_f32_16x16x32_bf16 v[0:3], v[170:173], v[214:217], v[0:3]
	v_mfma_f32_16x16x32_bf16 v[48:51], v[166:169], v[186:189], v[48:51]
	s_add_i32 s71, s71, 2
	v_mfma_f32_16x16x32_bf16 v[40:43], v[178:181], v[186:189], v[40:43]
	s_add_u32 s28, s28, 0x100
	v_mfma_f32_16x16x32_bf16 v[32:35], v[166:169], v[194:197], v[32:35]
	s_addc_u32 s29, s29, 0
	v_mfma_f32_16x16x32_bf16 v[24:27], v[178:181], v[194:197], v[24:27]
	s_add_u32 s69, s69, 0x100
	v_mfma_f32_16x16x32_bf16 v[16:19], v[166:169], v[210:213], v[16:19]
	s_addc_u32 s70, s70, 0
	v_mfma_f32_16x16x32_bf16 v[8:11], v[178:181], v[210:213], v[8:11]
	s_cmp_gt_u32 s71, 29
	v_mfma_f32_16x16x32_bf16 v[4:7], v[166:169], v[218:221], v[4:7]
	s_setprio 0
	v_mfma_f32_16x16x32_bf16 v[0:3], v[178:181], v[218:221], v[0:3]
	s_barrier
	s_cbranch_scc0 .LBB0_666
	s_and_b64 vcc, exec, s[12:13]
	s_cbranch_vccz .LBB0_669
	s_barrier

.LBB0_828:
	ds_read_b128 v[138:141], v145
	ds_read_b128 v[150:153], v145 offset:1024
	ds_read_b128 v[154:157], v145 offset:2048
	ds_read_b128 v[158:161], v145 offset:3072
	ds_read_b128 v[162:165], v146
	ds_read_b128 v[166:169], v146 offset:1024
	ds_read_b128 v[170:173], v146 offset:2048
	ds_read_b128 v[178:181], v146 offset:3072
	ds_read_b128 v[182:185], v147
	ds_read_b128 v[186:189], v147 offset:1024
	ds_read_b128 v[190:193], v147 offset:2048
	ds_read_b128 v[194:197], v147 offset:3072
	ds_read_b128 v[206:209], v147 offset:4096
	ds_read_b128 v[210:213], v147 offset:5120
	ds_read_b128 v[214:217], v147 offset:6144
	ds_read_b128 v[218:221], v147 offset:7168
	s_add_u32 s2, s58, s62
	s_addc_u32 s3, s59, s63
	s_add_u32 s9, s2, 0x100
	s_addc_u32 s38, s3, 0
	s_and_b64 s[0:1], s[60:61], exec
	v_cndmask_b32_e64 v137, 0, 1, s[64:65]
	s_cselect_b32 s65, s23, s38
	s_cselect_b32 s64, s12, s9
	s_add_u32 s0, s56, s62
	s_addc_u32 s1, s57, s63
	s_add_u32 s9, s0, 0x100
	s_addc_u32 s38, s1, 0
	s_and_b64 s[0:1], s[60:61], exec
	s_cselect_b32 s67, s13, s38
	s_cselect_b32 s66, s8, s9
	s_add_u32 s70, s2, 0x80080
	s_addc_u32 s71, s3, 0
	s_add_i32 s39, s87, s79
	s_add_i32 m0, s74, 0xc000
	s_add_i32 s53, s74, 0xe000
	s_add_i32 s50, s39, 0x2000
	s_add_u32 s68, s66, 0x80000
	s_addc_u32 s69, s67, 0
	s_add_i32 s51, s88, s79
	s_add_i32 s38, s51, 0x2000
	s_add_i32 s1, 0, 0x18000
	s_add_i32 s9, 0, 0x1c000
	s_add_u32 s62, s64, 0x80000
	s_addc_u32 s63, s65, 0
	s_add_i32 s3, s1, s79
	s_add_i32 s76, s3, 0x2000
	s_add_u32 s60, s66, 0x80080
	s_addc_u32 s61, s67, 0
	s_add_i32 s2, s9, s79
	s_add_i32 s0, s2, 0x2000
	v_cmp_ne_u32_e32 vcc, 1, v137
	v_lshl_add_u64 v[174:175], s[70:71], 0, v[128:129]
	global_load_lds_dwordx4 v[174:175], off
	s_mov_b32 m0, s53
	v_lshl_add_u64 v[174:175], s[70:71], 0, v[132:133]
	global_load_lds_dwordx4 v[174:175], off
	s_waitcnt vmcnt(8) lgkmcnt(0)
	s_setprio 1
	s_barrier
	v_mfma_f32_16x16x32_bf16 v[124:127], v[138:141], v[182:185], v[124:127]
	v_mfma_f32_16x16x32_bf16 v[120:123], v[154:157], v[182:185], v[120:123]
	v_mfma_f32_16x16x32_bf16 v[108:111], v[138:141], v[190:193], v[108:111]
	v_mfma_f32_16x16x32_bf16 v[104:107], v[154:157], v[190:193], v[104:107]
	v_mfma_f32_16x16x32_bf16 v[92:95], v[138:141], v[206:209], v[92:95]
	v_mfma_f32_16x16x32_bf16 v[88:91], v[154:157], v[206:209], v[88:91]
	v_mfma_f32_16x16x32_bf16 v[76:79], v[138:141], v[214:217], v[76:79]
	v_mfma_f32_16x16x32_bf16 v[72:75], v[154:157], v[214:217], v[72:75]
	v_mfma_f32_16x16x32_bf16 v[124:127], v[150:153], v[186:189], v[124:127]
	v_mfma_f32_16x16x32_bf16 v[120:123], v[158:161], v[186:189], v[120:123]
	v_mfma_f32_16x16x32_bf16 v[108:111], v[150:153], v[194:197], v[108:111]
	v_mfma_f32_16x16x32_bf16 v[104:107], v[158:161], v[194:197], v[104:107]
	v_mfma_f32_16x16x32_bf16 v[92:95], v[150:153], v[210:213], v[92:95]
	v_mfma_f32_16x16x32_bf16 v[88:91], v[158:161], v[210:213], v[88:91]
	v_mfma_f32_16x16x32_bf16 v[76:79], v[150:153], v[218:221], v[76:79]
	v_mfma_f32_16x16x32_bf16 v[72:75], v[158:161], v[218:221], v[72:75]
	v_mfma_f32_16x16x32_bf16 v[116:119], v[162:165], v[182:185], v[116:119]
	v_mfma_f32_16x16x32_bf16 v[112:115], v[170:173], v[182:185], v[112:115]
	v_mfma_f32_16x16x32_bf16 v[100:103], v[162:165], v[190:193], v[100:103]
	v_mfma_f32_16x16x32_bf16 v[96:99], v[170:173], v[190:193], v[96:99]
	v_mfma_f32_16x16x32_bf16 v[84:87], v[162:165], v[206:209], v[84:87]
	v_mfma_f32_16x16x32_bf16 v[80:83], v[170:173], v[206:209], v[80:83]
	v_mfma_f32_16x16x32_bf16 v[68:71], v[162:165], v[214:217], v[68:71]
	v_mfma_f32_16x16x32_bf16 v[64:67], v[170:173], v[214:217], v[64:67]
	v_mfma_f32_16x16x32_bf16 v[116:119], v[166:169], v[186:189], v[116:119]
	v_mfma_f32_16x16x32_bf16 v[112:115], v[178:181], v[186:189], v[112:115]
	v_mfma_f32_16x16x32_bf16 v[100:103], v[166:169], v[194:197], v[100:103]
	v_mfma_f32_16x16x32_bf16 v[96:99], v[178:181], v[194:197], v[96:99]
	v_mfma_f32_16x16x32_bf16 v[84:87], v[166:169], v[210:213], v[84:87]
	v_mfma_f32_16x16x32_bf16 v[80:83], v[178:181], v[210:213], v[80:83]
	v_mfma_f32_16x16x32_bf16 v[68:71], v[166:169], v[218:221], v[68:71]
	s_setprio 0
	v_mfma_f32_16x16x32_bf16 v[64:67], v[178:181], v[218:221], v[64:67]
	s_barrier
	ds_read_b128 v[182:185], v147 offset:16384
	ds_read_b128 v[186:189], v147 offset:17408
	ds_read_b128 v[190:193], v147 offset:18432
	ds_read_b128 v[194:197], v147 offset:19456
	ds_read_b128 v[206:209], v147 offset:20480
	ds_read_b128 v[210:213], v147 offset:21504
	ds_read_b128 v[214:217], v147 offset:22528
	ds_read_b128 v[218:221], v147 offset:23552
	s_mov_b32 m0, s39
	v_lshl_add_u64 v[174:175], s[66:67], 0, v[130:131]
	global_load_lds_dwordx4 v[174:175], off
	v_lshl_add_u64 v[198:199], s[66:67], 0, v[134:135]
	s_mov_b32 m0, s50
	v_lshl_add_u64 v[202:203], s[68:69], 0, v[130:131]
	global_load_lds_dwordx4 v[198:199], off
	s_mov_b32 m0, s51
	v_lshl_add_u64 v[222:223], s[64:65], 0, v[132:133]
	global_load_lds_dwordx4 v[202:203], off
	s_mov_b32 m0, s38
	v_lshl_add_u64 v[202:203], s[68:69], 0, v[134:135]
	global_load_lds_dwordx4 v[202:203], off
	s_mov_b32 m0, s74
	v_lshl_add_u64 v[202:203], s[64:65], 0, v[128:129]
	global_load_lds_dwordx4 v[202:203], off
	s_mov_b32 m0, s55
	s_nop 0
	global_load_lds_dwordx4 v[222:223], off
	s_waitcnt vmcnt(8) lgkmcnt(0)
	s_setprio 1
	s_barrier
	v_mfma_f32_16x16x32_bf16 v[60:63], v[138:141], v[182:185], v[60:63]
	v_mfma_f32_16x16x32_bf16 v[56:59], v[154:157], v[182:185], v[56:59]
	v_mfma_f32_16x16x32_bf16 v[44:47], v[138:141], v[190:193], v[44:47]
	v_mfma_f32_16x16x32_bf16 v[40:43], v[154:157], v[190:193], v[40:43]
	v_mfma_f32_16x16x32_bf16 v[28:31], v[138:141], v[206:209], v[28:31]
	v_mfma_f32_16x16x32_bf16 v[24:27], v[154:157], v[206:209], v[24:27]
	v_mfma_f32_16x16x32_bf16 v[12:15], v[138:141], v[214:217], v[12:15]
	v_mfma_f32_16x16x32_bf16 v[8:11], v[154:157], v[214:217], v[8:11]
	v_mfma_f32_16x16x32_bf16 v[60:63], v[150:153], v[186:189], v[60:63]
	v_mfma_f32_16x16x32_bf16 v[56:59], v[158:161], v[186:189], v[56:59]
	v_mfma_f32_16x16x32_bf16 v[44:47], v[150:153], v[194:197], v[44:47]
	v_mfma_f32_16x16x32_bf16 v[40:43], v[158:161], v[194:197], v[40:43]
	v_mfma_f32_16x16x32_bf16 v[28:31], v[150:153], v[210:213], v[28:31]
	v_mfma_f32_16x16x32_bf16 v[24:27], v[158:161], v[210:213], v[24:27]
	v_mfma_f32_16x16x32_bf16 v[12:15], v[150:153], v[218:221], v[12:15]
	v_mfma_f32_16x16x32_bf16 v[8:11], v[158:161], v[218:221], v[8:11]
	v_mfma_f32_16x16x32_bf16 v[52:55], v[162:165], v[182:185], v[52:55]
	v_mfma_f32_16x16x32_bf16 v[48:51], v[170:173], v[182:185], v[48:51]
	v_mfma_f32_16x16x32_bf16 v[36:39], v[162:165], v[190:193], v[36:39]
	v_mfma_f32_16x16x32_bf16 v[32:35], v[170:173], v[190:193], v[32:35]
	v_mfma_f32_16x16x32_bf16 v[20:23], v[162:165], v[206:209], v[20:23]
	v_mfma_f32_16x16x32_bf16 v[16:19], v[170:173], v[206:209], v[16:19]
	v_mfma_f32_16x16x32_bf16 v[4:7], v[162:165], v[214:217], v[4:7]
	v_mfma_f32_16x16x32_bf16 v[0:3], v[170:173], v[214:217], v[0:3]
	v_mfma_f32_16x16x32_bf16 v[52:55], v[166:169], v[186:189], v[52:55]
	v_mfma_f32_16x16x32_bf16 v[48:51], v[178:181], v[186:189], v[48:51]
	v_mfma_f32_16x16x32_bf16 v[36:39], v[166:169], v[194:197], v[36:39]
	v_mfma_f32_16x16x32_bf16 v[32:35], v[178:181], v[194:197], v[32:35]
	v_mfma_f32_16x16x32_bf16 v[20:23], v[166:169], v[210:213], v[20:23]
	v_mfma_f32_16x16x32_bf16 v[16:19], v[178:181], v[210:213], v[16:19]
	v_mfma_f32_16x16x32_bf16 v[4:7], v[166:169], v[218:221], v[4:7]
	s_setprio 0
	v_mfma_f32_16x16x32_bf16 v[0:3], v[178:181], v[218:221], v[0:3]
	s_barrier
	ds_read_b128 v[182:185], v147 offset:32768
	ds_read_b128 v[186:189], v147 offset:33792
	ds_read_b128 v[190:193], v147 offset:34816
	ds_read_b128 v[194:197], v147 offset:35840
	ds_read_b128 v[206:209], v147 offset:36864
	ds_read_b128 v[210:213], v147 offset:37888
	ds_read_b128 v[214:217], v147 offset:38912
	ds_read_b128 v[218:221], v147 offset:39936
	v_add_u32_e32 v137, s1, v144
	ds_read_b128 v[138:141], v137
	ds_read_b128 v[150:153], v137 offset:1024
	ds_read_b128 v[154:157], v137 offset:2048
	ds_read_b128 v[158:161], v137 offset:3072
	v_add_u32_e32 v137, s9, v144
	ds_read_b128 v[162:165], v137
	ds_read_b128 v[166:169], v137 offset:1024
	ds_read_b128 v[170:173], v137 offset:2048
	ds_read_b128 v[178:181], v137 offset:3072
	s_mov_b32 m0, s80
	v_lshl_add_u64 v[224:225], s[62:63], 0, v[128:129]
	global_load_lds_dwordx4 v[224:225], off
	s_mov_b32 m0, s81
	v_lshl_add_u64 v[224:225], s[62:63], 0, v[132:133]
	global_load_lds_dwordx4 v[224:225], off
	s_waitcnt vmcnt(8) lgkmcnt(0)
	s_setprio 1
	s_barrier
	v_mfma_f32_16x16x32_bf16 v[124:127], v[138:141], v[182:185], v[124:127]
	v_mfma_f32_16x16x32_bf16 v[120:123], v[154:157], v[182:185], v[120:123]
	v_mfma_f32_16x16x32_bf16 v[108:111], v[138:141], v[190:193], v[108:111]
	v_mfma_f32_16x16x32_bf16 v[104:107], v[154:157], v[190:193], v[104:107]
	v_mfma_f32_16x16x32_bf16 v[92:95], v[138:141], v[206:209], v[92:95]
	v_mfma_f32_16x16x32_bf16 v[88:91], v[154:157], v[206:209], v[88:91]
	v_mfma_f32_16x16x32_bf16 v[76:79], v[138:141], v[214:217], v[76:79]
	v_mfma_f32_16x16x32_bf16 v[72:75], v[154:157], v[214:217], v[72:75]
	v_mfma_f32_16x16x32_bf16 v[124:127], v[150:153], v[186:189], v[124:127]
	v_mfma_f32_16x16x32_bf16 v[120:123], v[158:161], v[186:189], v[120:123]
	v_mfma_f32_16x16x32_bf16 v[108:111], v[150:153], v[194:197], v[108:111]
	v_mfma_f32_16x16x32_bf16 v[104:107], v[158:161], v[194:197], v[104:107]
	v_mfma_f32_16x16x32_bf16 v[92:95], v[150:153], v[210:213], v[92:95]
	v_mfma_f32_16x16x32_bf16 v[88:91], v[158:161], v[210:213], v[88:91]
	v_mfma_f32_16x16x32_bf16 v[76:79], v[150:153], v[218:221], v[76:79]
	v_mfma_f32_16x16x32_bf16 v[72:75], v[158:161], v[218:221], v[72:75]
	v_mfma_f32_16x16x32_bf16 v[116:119], v[162:165], v[182:185], v[116:119]
	v_mfma_f32_16x16x32_bf16 v[112:115], v[170:173], v[182:185], v[112:115]
	v_mfma_f32_16x16x32_bf16 v[100:103], v[162:165], v[190:193], v[100:103]
	v_mfma_f32_16x16x32_bf16 v[96:99], v[170:173], v[190:193], v[96:99]
	v_mfma_f32_16x16x32_bf16 v[84:87], v[162:165], v[206:209], v[84:87]
	v_mfma_f32_16x16x32_bf16 v[80:83], v[170:173], v[206:209], v[80:83]
	v_mfma_f32_16x16x32_bf16 v[68:71], v[162:165], v[214:217], v[68:71]
	v_mfma_f32_16x16x32_bf16 v[64:67], v[170:173], v[214:217], v[64:67]
	v_mfma_f32_16x16x32_bf16 v[116:119], v[166:169], v[186:189], v[116:119]
	v_mfma_f32_16x16x32_bf16 v[112:115], v[178:181], v[186:189], v[112:115]
	v_mfma_f32_16x16x32_bf16 v[100:103], v[166:169], v[194:197], v[100:103]
	v_mfma_f32_16x16x32_bf16 v[96:99], v[178:181], v[194:197], v[96:99]
	v_mfma_f32_16x16x32_bf16 v[84:87], v[166:169], v[210:213], v[84:87]
	v_mfma_f32_16x16x32_bf16 v[80:83], v[178:181], v[210:213], v[80:83]
	v_mfma_f32_16x16x32_bf16 v[68:71], v[166:169], v[218:221], v[68:71]
	s_setprio 0
	v_mfma_f32_16x16x32_bf16 v[64:67], v[178:181], v[218:221], v[64:67]
	s_barrier
	ds_read_b128 v[182:185], v147 offset:49152
	ds_read_b128 v[186:189], v147 offset:50176
	ds_read_b128 v[190:193], v147 offset:51200
	ds_read_b128 v[194:197], v147 offset:52224
	ds_read_b128 v[206:209], v147 offset:53248
	ds_read_b128 v[210:213], v147 offset:54272
	ds_read_b128 v[214:217], v147 offset:55296
	ds_read_b128 v[218:221], v147 offset:56320
	s_mov_b32 m0, s3
	v_lshl_add_u64 v[174:175], v[174:175], 0, s[16:17]
	global_load_lds_dwordx4 v[174:175], off
	s_mov_b32 m0, s76
	v_lshl_add_u64 v[174:175], v[198:199], 0, s[16:17]
	global_load_lds_dwordx4 v[174:175], off
	s_mov_b32 m0, s2
	v_lshl_add_u64 v[174:175], s[60:61], 0, v[130:131]
	global_load_lds_dwordx4 v[174:175], off
	s_mov_b32 m0, s0
	v_lshl_add_u64 v[174:175], s[60:61], 0, v[134:135]
	global_load_lds_dwordx4 v[174:175], off
	s_mov_b32 m0, s85
	v_lshl_add_u64 v[174:175], v[202:203], 0, s[16:17]
	global_load_lds_dwordx4 v[174:175], off
	s_mov_b32 m0, s86
	v_lshl_add_u64 v[174:175], v[222:223], 0, s[16:17]
	global_load_lds_dwordx4 v[174:175], off
	s_waitcnt vmcnt(8) lgkmcnt(0)
	s_setprio 1
	s_barrier
	v_mfma_f32_16x16x32_bf16 v[60:63], v[138:141], v[182:185], v[60:63]
	v_mfma_f32_16x16x32_bf16 v[56:59], v[154:157], v[182:185], v[56:59]
	v_mfma_f32_16x16x32_bf16 v[44:47], v[138:141], v[190:193], v[44:47]
	v_mfma_f32_16x16x32_bf16 v[40:43], v[154:157], v[190:193], v[40:43]
	v_mfma_f32_16x16x32_bf16 v[28:31], v[138:141], v[206:209], v[28:31]
	v_mfma_f32_16x16x32_bf16 v[24:27], v[154:157], v[206:209], v[24:27]
	v_mfma_f32_16x16x32_bf16 v[12:15], v[138:141], v[214:217], v[12:15]
	v_mfma_f32_16x16x32_bf16 v[8:11], v[154:157], v[214:217], v[8:11]
	v_mfma_f32_16x16x32_bf16 v[60:63], v[150:153], v[186:189], v[60:63]
	v_mfma_f32_16x16x32_bf16 v[56:59], v[158:161], v[186:189], v[56:59]
	v_mfma_f32_16x16x32_bf16 v[44:47], v[150:153], v[194:197], v[44:47]
	v_mfma_f32_16x16x32_bf16 v[40:43], v[158:161], v[194:197], v[40:43]
	v_mfma_f32_16x16x32_bf16 v[28:31], v[150:153], v[210:213], v[28:31]
	v_mfma_f32_16x16x32_bf16 v[24:27], v[158:161], v[210:213], v[24:27]
	v_mfma_f32_16x16x32_bf16 v[12:15], v[150:153], v[218:221], v[12:15]
	v_mfma_f32_16x16x32_bf16 v[8:11], v[158:161], v[218:221], v[8:11]
	v_mfma_f32_16x16x32_bf16 v[52:55], v[162:165], v[182:185], v[52:55]
	v_mfma_f32_16x16x32_bf16 v[48:51], v[170:173], v[182:185], v[48:51]
	v_mfma_f32_16x16x32_bf16 v[36:39], v[162:165], v[190:193], v[36:39]
	v_mfma_f32_16x16x32_bf16 v[32:35], v[170:173], v[190:193], v[32:35]
	v_mfma_f32_16x16x32_bf16 v[20:23], v[162:165], v[206:209], v[20:23]
	v_mfma_f32_16x16x32_bf16 v[16:19], v[170:173], v[206:209], v[16:19]
	v_mfma_f32_16x16x32_bf16 v[4:7], v[162:165], v[214:217], v[4:7]
	v_mfma_f32_16x16x32_bf16 v[0:3], v[170:173], v[214:217], v[0:3]
	v_mfma_f32_16x16x32_bf16 v[52:55], v[166:169], v[186:189], v[52:55]
	v_mfma_f32_16x16x32_bf16 v[48:51], v[178:181], v[186:189], v[48:51]
	v_mfma_f32_16x16x32_bf16 v[36:39], v[166:169], v[194:197], v[36:39]
	v_mfma_f32_16x16x32_bf16 v[32:35], v[178:181], v[194:197], v[32:35]
	v_mfma_f32_16x16x32_bf16 v[20:23], v[166:169], v[210:213], v[20:23]
	v_mfma_f32_16x16x32_bf16 v[16:19], v[178:181], v[210:213], v[16:19]
	v_mfma_f32_16x16x32_bf16 v[4:7], v[166:169], v[218:221], v[4:7]
	s_setprio 0
	v_mfma_f32_16x16x32_bf16 v[0:3], v[178:181], v[218:221], v[0:3]
	s_barrier
	s_mov_b64 s[64:65], 0
	s_mov_b64 s[60:61], -1
	s_mov_b64 s[62:63], 0x100
	s_cbranch_vccz .LBB0_828
	s_and_b64 vcc, exec, s[18:19]
	s_cbranch_vccz .LBB0_831
	s_barrier

.LBB0_849:
	ds_read_b128 v[138:141], v147
	ds_read_b128 v[152:155], v147 offset:1024
	ds_read_b128 v[156:159], v147 offset:2048
	ds_read_b128 v[160:163], v147 offset:3072
	ds_read_b128 v[164:167], v148
	ds_read_b128 v[168:171], v148 offset:1024
	ds_read_b128 v[172:175], v148 offset:2048
	ds_read_b128 v[178:181], v148 offset:3072
	ds_read_b128 v[182:185], v149
	ds_read_b128 v[186:189], v149 offset:1024
	ds_read_b128 v[190:193], v149 offset:2048
	ds_read_b128 v[194:197], v149 offset:3072
	ds_read_b128 v[206:209], v149 offset:4096
	ds_read_b128 v[210:213], v149 offset:5120
	ds_read_b128 v[214:217], v149 offset:6144
	ds_read_b128 v[218:221], v149 offset:7168
	s_add_u32 s2, s30, s52
	s_addc_u32 s3, s31, s53
	s_add_u32 s9, s2, 0x100
	s_addc_u32 s38, s3, 0
	s_and_b64 s[0:1], s[34:35], exec
	v_cndmask_b32_e64 v137, 0, 1, s[54:55]
	s_cselect_b32 s55, s27, s38
	s_cselect_b32 s54, s89, s9
	s_add_u32 s0, s28, s52
	s_addc_u32 s1, s29, s53
	s_add_u32 s9, s0, 0x100
	s_addc_u32 s38, s1, 0
	s_and_b64 s[0:1], s[34:35], exec
	s_cselect_b32 s57, s90, s38
	s_cselect_b32 s56, s8, s9
	s_add_u32 s60, s2, 0x80080
	s_addc_u32 s61, s3, 0
	s_add_i32 s39, s79, s36
	s_add_i32 m0, s63, 0xc000
	s_add_i32 s74, s63, 0xe000
	s_add_i32 s50, s39, 0x2000
	s_add_u32 s58, s56, 0x80000
	s_addc_u32 s59, s57, 0
	s_add_i32 s38, s80, s36
	s_add_i32 s51, s38, 0x2000
	s_add_i32 s76, 0, 0x18000
	s_add_i32 s0, 0, 0x1c000
	s_add_u32 s52, s54, 0x80000
	s_addc_u32 s53, s55, 0
	s_add_i32 s3, s76, s36
	s_add_i32 s1, s3, 0x2000
	s_add_u32 s34, s56, 0x80080
	s_addc_u32 s35, s57, 0
	s_add_i32 s2, s0, s36
	s_add_i32 s9, s2, 0x2000
	v_cmp_ne_u32_e32 vcc, 1, v137
	v_lshl_add_u64 v[142:143], s[60:61], 0, v[134:135]
	global_load_lds_dwordx4 v[142:143], off
	s_mov_b32 m0, s74
	v_lshl_add_u64 v[142:143], s[60:61], 0, v[130:131]
	global_load_lds_dwordx4 v[142:143], off
	s_waitcnt vmcnt(8) lgkmcnt(0)
	s_setprio 1
	s_barrier
	v_mfma_f32_16x16x32_bf16 v[124:127], v[138:141], v[182:185], v[124:127]
	v_mfma_f32_16x16x32_bf16 v[120:123], v[156:159], v[182:185], v[120:123]
	v_mfma_f32_16x16x32_bf16 v[108:111], v[138:141], v[190:193], v[108:111]
	v_mfma_f32_16x16x32_bf16 v[104:107], v[156:159], v[190:193], v[104:107]
	v_mfma_f32_16x16x32_bf16 v[92:95], v[138:141], v[206:209], v[92:95]
	v_mfma_f32_16x16x32_bf16 v[88:91], v[156:159], v[206:209], v[88:91]
	v_mfma_f32_16x16x32_bf16 v[76:79], v[138:141], v[214:217], v[76:79]
	v_mfma_f32_16x16x32_bf16 v[72:75], v[156:159], v[214:217], v[72:75]
	v_mfma_f32_16x16x32_bf16 v[124:127], v[152:155], v[186:189], v[124:127]
	v_mfma_f32_16x16x32_bf16 v[120:123], v[160:163], v[186:189], v[120:123]
	v_mfma_f32_16x16x32_bf16 v[108:111], v[152:155], v[194:197], v[108:111]
	v_mfma_f32_16x16x32_bf16 v[104:107], v[160:163], v[194:197], v[104:107]
	v_mfma_f32_16x16x32_bf16 v[92:95], v[152:155], v[210:213], v[92:95]
	v_mfma_f32_16x16x32_bf16 v[88:91], v[160:163], v[210:213], v[88:91]
	v_mfma_f32_16x16x32_bf16 v[76:79], v[152:155], v[218:221], v[76:79]
	v_mfma_f32_16x16x32_bf16 v[72:75], v[160:163], v[218:221], v[72:75]
	v_mfma_f32_16x16x32_bf16 v[116:119], v[164:167], v[182:185], v[116:119]
	v_mfma_f32_16x16x32_bf16 v[112:115], v[172:175], v[182:185], v[112:115]
	v_mfma_f32_16x16x32_bf16 v[100:103], v[164:167], v[190:193], v[100:103]
	v_mfma_f32_16x16x32_bf16 v[96:99], v[172:175], v[190:193], v[96:99]
	v_mfma_f32_16x16x32_bf16 v[84:87], v[164:167], v[206:209], v[84:87]
	v_mfma_f32_16x16x32_bf16 v[80:83], v[172:175], v[206:209], v[80:83]
	v_mfma_f32_16x16x32_bf16 v[68:71], v[164:167], v[214:217], v[68:71]
	v_mfma_f32_16x16x32_bf16 v[64:67], v[172:175], v[214:217], v[64:67]
	v_mfma_f32_16x16x32_bf16 v[116:119], v[168:171], v[186:189], v[116:119]
	v_mfma_f32_16x16x32_bf16 v[112:115], v[178:181], v[186:189], v[112:115]
	v_mfma_f32_16x16x32_bf16 v[100:103], v[168:171], v[194:197], v[100:103]
	v_mfma_f32_16x16x32_bf16 v[96:99], v[178:181], v[194:197], v[96:99]
	v_mfma_f32_16x16x32_bf16 v[84:87], v[168:171], v[210:213], v[84:87]
	v_mfma_f32_16x16x32_bf16 v[80:83], v[178:181], v[210:213], v[80:83]
	v_mfma_f32_16x16x32_bf16 v[68:71], v[168:171], v[218:221], v[68:71]
	s_setprio 0
	v_mfma_f32_16x16x32_bf16 v[64:67], v[178:181], v[218:221], v[64:67]
	s_barrier
	ds_read_b128 v[182:185], v149 offset:16384
	ds_read_b128 v[186:189], v149 offset:17408
	ds_read_b128 v[190:193], v149 offset:18432
	ds_read_b128 v[194:197], v149 offset:19456
	ds_read_b128 v[206:209], v149 offset:20480
	ds_read_b128 v[210:213], v149 offset:21504
	ds_read_b128 v[214:217], v149 offset:22528
	ds_read_b128 v[218:221], v149 offset:23552
	s_mov_b32 m0, s39
	v_lshl_add_u64 v[142:143], s[56:57], 0, v[132:133]
	global_load_lds_dwordx4 v[142:143], off
	v_lshl_add_u64 v[198:199], s[56:57], 0, v[128:129]
	s_mov_b32 m0, s50
	v_lshl_add_u64 v[202:203], s[58:59], 0, v[132:133]
	global_load_lds_dwordx4 v[198:199], off
	s_mov_b32 m0, s38
	v_lshl_add_u64 v[222:223], s[54:55], 0, v[130:131]
	global_load_lds_dwordx4 v[202:203], off
	s_mov_b32 m0, s51
	v_lshl_add_u64 v[202:203], s[58:59], 0, v[128:129]
	global_load_lds_dwordx4 v[202:203], off
	s_mov_b32 m0, s63
	v_lshl_add_u64 v[202:203], s[54:55], 0, v[134:135]
	global_load_lds_dwordx4 v[202:203], off
	s_mov_b32 m0, s64
	s_nop 0
	global_load_lds_dwordx4 v[222:223], off
	s_waitcnt vmcnt(8) lgkmcnt(0)
	s_setprio 1
	s_barrier
	v_mfma_f32_16x16x32_bf16 v[60:63], v[138:141], v[182:185], v[60:63]
	v_mfma_f32_16x16x32_bf16 v[56:59], v[156:159], v[182:185], v[56:59]
	v_mfma_f32_16x16x32_bf16 v[44:47], v[138:141], v[190:193], v[44:47]
	v_mfma_f32_16x16x32_bf16 v[40:43], v[156:159], v[190:193], v[40:43]
	v_mfma_f32_16x16x32_bf16 v[28:31], v[138:141], v[206:209], v[28:31]
	v_mfma_f32_16x16x32_bf16 v[24:27], v[156:159], v[206:209], v[24:27]
	v_mfma_f32_16x16x32_bf16 v[12:15], v[138:141], v[214:217], v[12:15]
	v_mfma_f32_16x16x32_bf16 v[8:11], v[156:159], v[214:217], v[8:11]
	v_mfma_f32_16x16x32_bf16 v[60:63], v[152:155], v[186:189], v[60:63]
	v_mfma_f32_16x16x32_bf16 v[56:59], v[160:163], v[186:189], v[56:59]
	v_mfma_f32_16x16x32_bf16 v[44:47], v[152:155], v[194:197], v[44:47]
	v_mfma_f32_16x16x32_bf16 v[40:43], v[160:163], v[194:197], v[40:43]
	v_mfma_f32_16x16x32_bf16 v[28:31], v[152:155], v[210:213], v[28:31]
	v_mfma_f32_16x16x32_bf16 v[24:27], v[160:163], v[210:213], v[24:27]
	v_mfma_f32_16x16x32_bf16 v[12:15], v[152:155], v[218:221], v[12:15]
	v_mfma_f32_16x16x32_bf16 v[8:11], v[160:163], v[218:221], v[8:11]
	v_mfma_f32_16x16x32_bf16 v[52:55], v[164:167], v[182:185], v[52:55]
	v_mfma_f32_16x16x32_bf16 v[48:51], v[172:175], v[182:185], v[48:51]
	v_mfma_f32_16x16x32_bf16 v[36:39], v[164:167], v[190:193], v[36:39]
	v_mfma_f32_16x16x32_bf16 v[32:35], v[172:175], v[190:193], v[32:35]
	v_mfma_f32_16x16x32_bf16 v[20:23], v[164:167], v[206:209], v[20:23]
	v_mfma_f32_16x16x32_bf16 v[16:19], v[172:175], v[206:209], v[16:19]
	v_mfma_f32_16x16x32_bf16 v[4:7], v[164:167], v[214:217], v[4:7]
	v_mfma_f32_16x16x32_bf16 v[0:3], v[172:175], v[214:217], v[0:3]
	v_mfma_f32_16x16x32_bf16 v[52:55], v[168:171], v[186:189], v[52:55]
	v_mfma_f32_16x16x32_bf16 v[48:51], v[178:181], v[186:189], v[48:51]
	v_mfma_f32_16x16x32_bf16 v[36:39], v[168:171], v[194:197], v[36:39]
	v_mfma_f32_16x16x32_bf16 v[32:35], v[178:181], v[194:197], v[32:35]
	v_mfma_f32_16x16x32_bf16 v[20:23], v[168:171], v[210:213], v[20:23]
	v_mfma_f32_16x16x32_bf16 v[16:19], v[178:181], v[210:213], v[16:19]
	v_mfma_f32_16x16x32_bf16 v[4:7], v[168:171], v[218:221], v[4:7]
	s_setprio 0
	v_mfma_f32_16x16x32_bf16 v[0:3], v[178:181], v[218:221], v[0:3]
	s_barrier
	ds_read_b128 v[182:185], v149 offset:32768
	ds_read_b128 v[186:189], v149 offset:33792
	ds_read_b128 v[190:193], v149 offset:34816
	ds_read_b128 v[194:197], v149 offset:35840
	ds_read_b128 v[206:209], v149 offset:36864
	ds_read_b128 v[210:213], v149 offset:37888
	ds_read_b128 v[214:217], v149 offset:38912
	ds_read_b128 v[218:221], v149 offset:39936
	v_add_u32_e32 v137, s76, v146
	ds_read_b128 v[138:141], v137
	ds_read_b128 v[152:155], v137 offset:1024
	ds_read_b128 v[156:159], v137 offset:2048
	ds_read_b128 v[160:163], v137 offset:3072
	v_add_u32_e32 v137, s0, v146
	ds_read_b128 v[164:167], v137
	ds_read_b128 v[168:171], v137 offset:1024
	ds_read_b128 v[172:175], v137 offset:2048
	ds_read_b128 v[178:181], v137 offset:3072
	s_mov_b32 m0, s65
	v_lshl_add_u64 v[224:225], s[52:53], 0, v[134:135]
	global_load_lds_dwordx4 v[224:225], off
	s_mov_b32 m0, s66
	v_lshl_add_u64 v[224:225], s[52:53], 0, v[130:131]
	global_load_lds_dwordx4 v[224:225], off
	s_waitcnt vmcnt(8) lgkmcnt(0)
	s_setprio 1
	s_barrier
	v_mfma_f32_16x16x32_bf16 v[124:127], v[138:141], v[182:185], v[124:127]
	v_mfma_f32_16x16x32_bf16 v[120:123], v[156:159], v[182:185], v[120:123]
	v_mfma_f32_16x16x32_bf16 v[108:111], v[138:141], v[190:193], v[108:111]
	v_mfma_f32_16x16x32_bf16 v[104:107], v[156:159], v[190:193], v[104:107]
	v_mfma_f32_16x16x32_bf16 v[92:95], v[138:141], v[206:209], v[92:95]
	v_mfma_f32_16x16x32_bf16 v[88:91], v[156:159], v[206:209], v[88:91]
	v_mfma_f32_16x16x32_bf16 v[76:79], v[138:141], v[214:217], v[76:79]
	v_mfma_f32_16x16x32_bf16 v[72:75], v[156:159], v[214:217], v[72:75]
	v_mfma_f32_16x16x32_bf16 v[124:127], v[152:155], v[186:189], v[124:127]
	v_mfma_f32_16x16x32_bf16 v[120:123], v[160:163], v[186:189], v[120:123]
	v_mfma_f32_16x16x32_bf16 v[108:111], v[152:155], v[194:197], v[108:111]
	v_mfma_f32_16x16x32_bf16 v[104:107], v[160:163], v[194:197], v[104:107]
	v_mfma_f32_16x16x32_bf16 v[92:95], v[152:155], v[210:213], v[92:95]
	v_mfma_f32_16x16x32_bf16 v[88:91], v[160:163], v[210:213], v[88:91]
	v_mfma_f32_16x16x32_bf16 v[76:79], v[152:155], v[218:221], v[76:79]
	v_mfma_f32_16x16x32_bf16 v[72:75], v[160:163], v[218:221], v[72:75]
	v_mfma_f32_16x16x32_bf16 v[116:119], v[164:167], v[182:185], v[116:119]
	v_mfma_f32_16x16x32_bf16 v[112:115], v[172:175], v[182:185], v[112:115]
	v_mfma_f32_16x16x32_bf16 v[100:103], v[164:167], v[190:193], v[100:103]
	v_mfma_f32_16x16x32_bf16 v[96:99], v[172:175], v[190:193], v[96:99]
	v_mfma_f32_16x16x32_bf16 v[84:87], v[164:167], v[206:209], v[84:87]
	v_mfma_f32_16x16x32_bf16 v[80:83], v[172:175], v[206:209], v[80:83]
	v_mfma_f32_16x16x32_bf16 v[68:71], v[164:167], v[214:217], v[68:71]
	v_mfma_f32_16x16x32_bf16 v[64:67], v[172:175], v[214:217], v[64:67]
	v_mfma_f32_16x16x32_bf16 v[116:119], v[168:171], v[186:189], v[116:119]
	v_mfma_f32_16x16x32_bf16 v[112:115], v[178:181], v[186:189], v[112:115]
	v_mfma_f32_16x16x32_bf16 v[100:103], v[168:171], v[194:197], v[100:103]
	v_mfma_f32_16x16x32_bf16 v[96:99], v[178:181], v[194:197], v[96:99]
	v_mfma_f32_16x16x32_bf16 v[84:87], v[168:171], v[210:213], v[84:87]
	v_mfma_f32_16x16x32_bf16 v[80:83], v[178:181], v[210:213], v[80:83]
	v_mfma_f32_16x16x32_bf16 v[68:71], v[168:171], v[218:221], v[68:71]
	s_setprio 0
	v_mfma_f32_16x16x32_bf16 v[64:67], v[178:181], v[218:221], v[64:67]
	s_barrier
	ds_read_b128 v[182:185], v149 offset:49152
	ds_read_b128 v[186:189], v149 offset:50176
	ds_read_b128 v[190:193], v149 offset:51200
	ds_read_b128 v[194:197], v149 offset:52224
	ds_read_b128 v[206:209], v149 offset:53248
	ds_read_b128 v[210:213], v149 offset:54272
	ds_read_b128 v[214:217], v149 offset:55296
	ds_read_b128 v[218:221], v149 offset:56320
	s_mov_b32 m0, s3
	v_lshl_add_u64 v[142:143], v[142:143], 0, s[14:15]
	global_load_lds_dwordx4 v[142:143], off
	s_mov_b32 m0, s1
	v_lshl_add_u64 v[142:143], v[198:199], 0, s[14:15]
	global_load_lds_dwordx4 v[142:143], off
	s_mov_b32 m0, s2
	v_lshl_add_u64 v[142:143], s[34:35], 0, v[132:133]
	global_load_lds_dwordx4 v[142:143], off
	s_mov_b32 m0, s9
	v_lshl_add_u64 v[142:143], s[34:35], 0, v[128:129]
	global_load_lds_dwordx4 v[142:143], off
	s_mov_b32 m0, s77
	v_lshl_add_u64 v[142:143], v[202:203], 0, s[14:15]
	global_load_lds_dwordx4 v[142:143], off
	s_mov_b32 m0, s78
	v_lshl_add_u64 v[142:143], v[222:223], 0, s[14:15]
	global_load_lds_dwordx4 v[142:143], off
	s_waitcnt vmcnt(8) lgkmcnt(0)
	s_setprio 1
	s_barrier
	v_mfma_f32_16x16x32_bf16 v[60:63], v[138:141], v[182:185], v[60:63]
	v_mfma_f32_16x16x32_bf16 v[56:59], v[156:159], v[182:185], v[56:59]
	v_mfma_f32_16x16x32_bf16 v[44:47], v[138:141], v[190:193], v[44:47]
	v_mfma_f32_16x16x32_bf16 v[40:43], v[156:159], v[190:193], v[40:43]
	v_mfma_f32_16x16x32_bf16 v[28:31], v[138:141], v[206:209], v[28:31]
	v_mfma_f32_16x16x32_bf16 v[24:27], v[156:159], v[206:209], v[24:27]
	v_mfma_f32_16x16x32_bf16 v[12:15], v[138:141], v[214:217], v[12:15]
	v_mfma_f32_16x16x32_bf16 v[8:11], v[156:159], v[214:217], v[8:11]
	v_mfma_f32_16x16x32_bf16 v[60:63], v[152:155], v[186:189], v[60:63]
	v_mfma_f32_16x16x32_bf16 v[56:59], v[160:163], v[186:189], v[56:59]
	v_mfma_f32_16x16x32_bf16 v[44:47], v[152:155], v[194:197], v[44:47]
	v_mfma_f32_16x16x32_bf16 v[40:43], v[160:163], v[194:197], v[40:43]
	v_mfma_f32_16x16x32_bf16 v[28:31], v[152:155], v[210:213], v[28:31]
	v_mfma_f32_16x16x32_bf16 v[24:27], v[160:163], v[210:213], v[24:27]
	v_mfma_f32_16x16x32_bf16 v[12:15], v[152:155], v[218:221], v[12:15]
	v_mfma_f32_16x16x32_bf16 v[8:11], v[160:163], v[218:221], v[8:11]
	v_mfma_f32_16x16x32_bf16 v[52:55], v[164:167], v[182:185], v[52:55]
	v_mfma_f32_16x16x32_bf16 v[48:51], v[172:175], v[182:185], v[48:51]
	v_mfma_f32_16x16x32_bf16 v[36:39], v[164:167], v[190:193], v[36:39]
	v_mfma_f32_16x16x32_bf16 v[32:35], v[172:175], v[190:193], v[32:35]
	v_mfma_f32_16x16x32_bf16 v[20:23], v[164:167], v[206:209], v[20:23]
	v_mfma_f32_16x16x32_bf16 v[16:19], v[172:175], v[206:209], v[16:19]
	v_mfma_f32_16x16x32_bf16 v[4:7], v[164:167], v[214:217], v[4:7]
	v_mfma_f32_16x16x32_bf16 v[0:3], v[172:175], v[214:217], v[0:3]
	v_mfma_f32_16x16x32_bf16 v[52:55], v[168:171], v[186:189], v[52:55]
	v_mfma_f32_16x16x32_bf16 v[48:51], v[178:181], v[186:189], v[48:51]
	v_mfma_f32_16x16x32_bf16 v[36:39], v[168:171], v[194:197], v[36:39]
	v_mfma_f32_16x16x32_bf16 v[32:35], v[178:181], v[194:197], v[32:35]
	v_mfma_f32_16x16x32_bf16 v[20:23], v[168:171], v[210:213], v[20:23]
	v_mfma_f32_16x16x32_bf16 v[16:19], v[178:181], v[210:213], v[16:19]
	v_mfma_f32_16x16x32_bf16 v[4:7], v[168:171], v[218:221], v[4:7]
	s_setprio 0
	v_mfma_f32_16x16x32_bf16 v[0:3], v[178:181], v[218:221], v[0:3]
	s_barrier
	s_mov_b64 s[54:55], 0
	s_mov_b64 s[34:35], -1
	s_mov_b64 s[52:53], 0x100
	s_cbranch_vccz .LBB0_849
	s_and_b64 vcc, exec, s[16:17]
	s_cbranch_vccz .LBB0_852
	s_barrier

.LBB0_877:
	ds_read_b128 v[142:145], v135 offset:1024
	ds_read_b128 v[146:149], v135 offset:2048
	ds_read_b128 v[150:153], v135 offset:3072
	ds_read_b128 v[154:157], v136
	ds_read_b128 v[158:161], v136 offset:1024
	ds_read_b128 v[162:165], v136 offset:2048
	ds_read_b128 v[166:169], v136 offset:3072
	ds_read_b128 v[170:173], v137
	ds_read_b128 v[178:181], v137 offset:1024
	ds_read_b128 v[182:185], v137 offset:2048
	ds_read_b128 v[186:189], v137 offset:3072
	ds_read_b128 v[190:193], v137 offset:4096
	ds_read_b128 v[194:197], v137 offset:5120
	ds_read_b128 v[206:209], v137 offset:6144
	ds_read_b128 v[210:213], v137 offset:7168
	s_add_u32 s2, s54, s64
	s_addc_u32 s3, s55, s65
	s_add_u32 s8, s2, 0x100
	s_addc_u32 s9, s3, 0
	s_and_b64 s[0:1], s[62:63], exec
	v_cndmask_b32_e64 v138, 0, 1, s[66:67]
	s_cselect_b32 s67, s21, s9
	s_cselect_b32 s66, s23, s8
	s_add_u32 s0, s30, s64
	s_addc_u32 s1, s31, s65
	s_add_u32 s8, s0, 0x100
	s_addc_u32 s9, s1, 0
	s_and_b64 s[0:1], s[62:63], exec
	s_cselect_b32 s69, s95, s9
	s_cselect_b32 s68, s96, s8
	s_add_u32 s72, s2, 0x10080
	v_cmp_ne_u32_e32 vcc, 1, v138
	ds_read_b128 v[138:141], v135
	s_addc_u32 s73, s3, 0
	s_add_i32 s19, s91, s77
	s_add_i32 m0, s80, 0xc000
	s_add_i32 s38, s80, 0xe000
	s_add_i32 s0, s19, 0x2000
	s_add_u32 s70, s68, 0x10000
	s_addc_u32 s71, s69, 0
	s_add_i32 s76, s92, s77
	s_add_i32 s18, s76, 0x2000
	s_add_i32 s3, 0, 0x18000
	s_add_i32 s2, 0, 0x1c000
	s_add_u32 s64, s66, 0x10000
	s_addc_u32 s65, s67, 0
	s_add_i32 s1, s3, s77
	s_add_i32 s9, s1, 0x2000
	s_add_u32 s62, s68, 0x10080
	s_addc_u32 s63, s69, 0
	s_add_i32 s97, s2, s77
	s_add_i32 s8, s97, 0x2000
	v_lshl_add_u64 v[174:175], s[72:73], 0, v[128:129]
	global_load_lds_dwordx4 v[174:175], off
	s_mov_b32 m0, s38
	v_lshl_add_u64 v[174:175], s[72:73], 0, v[130:131]
	global_load_lds_dwordx4 v[174:175], off
	s_waitcnt vmcnt(8) lgkmcnt(0)
	s_setprio 1
	s_barrier
	v_mfma_f32_16x16x32_bf16 v[124:127], v[138:141], v[170:173], v[124:127]
	v_mfma_f32_16x16x32_bf16 v[120:123], v[146:149], v[170:173], v[120:123]
	v_mfma_f32_16x16x32_bf16 v[116:119], v[138:141], v[182:185], v[116:119]
	v_mfma_f32_16x16x32_bf16 v[112:115], v[146:149], v[182:185], v[112:115]
	v_mfma_f32_16x16x32_bf16 v[104:107], v[138:141], v[190:193], v[104:107]
	v_mfma_f32_16x16x32_bf16 v[96:99], v[146:149], v[190:193], v[96:99]
	v_mfma_f32_16x16x32_bf16 v[88:91], v[138:141], v[206:209], v[88:91]
	v_mfma_f32_16x16x32_bf16 v[80:83], v[146:149], v[206:209], v[80:83]
	v_mfma_f32_16x16x32_bf16 v[124:127], v[142:145], v[178:181], v[124:127]
	v_mfma_f32_16x16x32_bf16 v[120:123], v[150:153], v[178:181], v[120:123]
	v_mfma_f32_16x16x32_bf16 v[116:119], v[142:145], v[186:189], v[116:119]
	v_mfma_f32_16x16x32_bf16 v[112:115], v[150:153], v[186:189], v[112:115]
	v_mfma_f32_16x16x32_bf16 v[104:107], v[142:145], v[194:197], v[104:107]
	v_mfma_f32_16x16x32_bf16 v[96:99], v[150:153], v[194:197], v[96:99]
	v_mfma_f32_16x16x32_bf16 v[88:91], v[142:145], v[210:213], v[88:91]
	v_mfma_f32_16x16x32_bf16 v[80:83], v[150:153], v[210:213], v[80:83]
	v_mfma_f32_16x16x32_bf16 v[108:111], v[154:157], v[170:173], v[108:111]
	v_mfma_f32_16x16x32_bf16 v[100:103], v[162:165], v[170:173], v[100:103]
	v_mfma_f32_16x16x32_bf16 v[92:95], v[154:157], v[182:185], v[92:95]
	v_mfma_f32_16x16x32_bf16 v[84:87], v[162:165], v[182:185], v[84:87]
	v_mfma_f32_16x16x32_bf16 v[76:79], v[154:157], v[190:193], v[76:79]
	v_mfma_f32_16x16x32_bf16 v[72:75], v[162:165], v[190:193], v[72:75]
	v_mfma_f32_16x16x32_bf16 v[68:71], v[154:157], v[206:209], v[68:71]
	v_mfma_f32_16x16x32_bf16 v[64:67], v[162:165], v[206:209], v[64:67]
	v_mfma_f32_16x16x32_bf16 v[108:111], v[158:161], v[178:181], v[108:111]
	v_mfma_f32_16x16x32_bf16 v[100:103], v[166:169], v[178:181], v[100:103]
	v_mfma_f32_16x16x32_bf16 v[92:95], v[158:161], v[186:189], v[92:95]
	v_mfma_f32_16x16x32_bf16 v[84:87], v[166:169], v[186:189], v[84:87]
	v_mfma_f32_16x16x32_bf16 v[76:79], v[158:161], v[194:197], v[76:79]
	v_mfma_f32_16x16x32_bf16 v[72:75], v[166:169], v[194:197], v[72:75]
	v_mfma_f32_16x16x32_bf16 v[68:71], v[158:161], v[210:213], v[68:71]
	s_setprio 0
	v_mfma_f32_16x16x32_bf16 v[64:67], v[166:169], v[210:213], v[64:67]
	s_barrier
	ds_read_b128 v[170:173], v137 offset:16384
	ds_read_b128 v[178:181], v137 offset:17408
	ds_read_b128 v[182:185], v137 offset:18432
	ds_read_b128 v[186:189], v137 offset:19456
	ds_read_b128 v[190:193], v137 offset:20480
	ds_read_b128 v[194:197], v137 offset:21504
	ds_read_b128 v[206:209], v137 offset:22528
	ds_read_b128 v[210:213], v137 offset:23552
	s_mov_b32 m0, s19
	v_lshl_add_u64 v[174:175], s[68:69], 0, v[128:129]
	global_load_lds_dwordx4 v[174:175], off
	v_lshl_add_u64 v[198:199], s[68:69], 0, v[130:131]
	s_mov_b32 m0, s0
	v_lshl_add_u64 v[202:203], s[70:71], 0, v[128:129]
	global_load_lds_dwordx4 v[198:199], off
	s_mov_b32 m0, s76
	v_lshl_add_u64 v[214:215], s[66:67], 0, v[130:131]
	global_load_lds_dwordx4 v[202:203], off
	s_mov_b32 m0, s18
	v_lshl_add_u64 v[202:203], s[70:71], 0, v[130:131]
	global_load_lds_dwordx4 v[202:203], off
	s_mov_b32 m0, s80
	v_lshl_add_u64 v[202:203], s[66:67], 0, v[128:129]
	global_load_lds_dwordx4 v[202:203], off
	s_mov_b32 m0, s81
	s_nop 0
	global_load_lds_dwordx4 v[214:215], off
	s_waitcnt vmcnt(8) lgkmcnt(0)
	s_setprio 1
	s_barrier
	v_mfma_f32_16x16x32_bf16 v[60:63], v[138:141], v[170:173], v[60:63]
	v_mfma_f32_16x16x32_bf16 v[56:59], v[146:149], v[170:173], v[56:59]
	v_mfma_f32_16x16x32_bf16 v[52:55], v[138:141], v[182:185], v[52:55]
	v_mfma_f32_16x16x32_bf16 v[48:51], v[146:149], v[182:185], v[48:51]
	v_mfma_f32_16x16x32_bf16 v[40:43], v[138:141], v[190:193], v[40:43]
	v_mfma_f32_16x16x32_bf16 v[32:35], v[146:149], v[190:193], v[32:35]
	v_mfma_f32_16x16x32_bf16 v[24:27], v[138:141], v[206:209], v[24:27]
	v_mfma_f32_16x16x32_bf16 v[16:19], v[146:149], v[206:209], v[16:19]
	v_mfma_f32_16x16x32_bf16 v[60:63], v[142:145], v[178:181], v[60:63]
	v_mfma_f32_16x16x32_bf16 v[56:59], v[150:153], v[178:181], v[56:59]
	v_mfma_f32_16x16x32_bf16 v[52:55], v[142:145], v[186:189], v[52:55]
	v_mfma_f32_16x16x32_bf16 v[48:51], v[150:153], v[186:189], v[48:51]
	v_mfma_f32_16x16x32_bf16 v[40:43], v[142:145], v[194:197], v[40:43]
	v_mfma_f32_16x16x32_bf16 v[32:35], v[150:153], v[194:197], v[32:35]
	v_mfma_f32_16x16x32_bf16 v[24:27], v[142:145], v[210:213], v[24:27]
	v_mfma_f32_16x16x32_bf16 v[16:19], v[150:153], v[210:213], v[16:19]
	v_mfma_f32_16x16x32_bf16 v[44:47], v[154:157], v[170:173], v[44:47]
	v_mfma_f32_16x16x32_bf16 v[36:39], v[162:165], v[170:173], v[36:39]
	v_mfma_f32_16x16x32_bf16 v[28:31], v[154:157], v[182:185], v[28:31]
	v_mfma_f32_16x16x32_bf16 v[20:23], v[162:165], v[182:185], v[20:23]
	v_mfma_f32_16x16x32_bf16 v[12:15], v[154:157], v[190:193], v[12:15]
	v_mfma_f32_16x16x32_bf16 v[8:11], v[162:165], v[190:193], v[8:11]
	v_mfma_f32_16x16x32_bf16 v[4:7], v[154:157], v[206:209], v[4:7]
	v_mfma_f32_16x16x32_bf16 v[0:3], v[162:165], v[206:209], v[0:3]
	v_mfma_f32_16x16x32_bf16 v[44:47], v[158:161], v[178:181], v[44:47]
	v_mfma_f32_16x16x32_bf16 v[36:39], v[166:169], v[178:181], v[36:39]
	v_mfma_f32_16x16x32_bf16 v[28:31], v[158:161], v[186:189], v[28:31]
	v_mfma_f32_16x16x32_bf16 v[20:23], v[166:169], v[186:189], v[20:23]
	v_mfma_f32_16x16x32_bf16 v[12:15], v[158:161], v[194:197], v[12:15]
	v_mfma_f32_16x16x32_bf16 v[8:11], v[166:169], v[194:197], v[8:11]
	v_mfma_f32_16x16x32_bf16 v[4:7], v[158:161], v[210:213], v[4:7]
	s_setprio 0
	v_mfma_f32_16x16x32_bf16 v[0:3], v[166:169], v[210:213], v[0:3]
	s_barrier
	ds_read_b128 v[170:173], v137 offset:32768
	ds_read_b128 v[178:181], v137 offset:33792
	ds_read_b128 v[182:185], v137 offset:34816
	ds_read_b128 v[186:189], v137 offset:35840
	ds_read_b128 v[190:193], v137 offset:36864
	ds_read_b128 v[194:197], v137 offset:37888
	ds_read_b128 v[206:209], v137 offset:38912
	ds_read_b128 v[210:213], v137 offset:39936
	v_add_u32_e32 v150, s3, v134
	v_add_u32_e32 v166, s2, v134
	ds_read_b128 v[138:141], v150
	ds_read_b128 v[142:145], v150 offset:1024
	ds_read_b128 v[146:149], v150 offset:2048
	ds_read_b128 v[150:153], v150 offset:3072
	ds_read_b128 v[154:157], v166
	ds_read_b128 v[158:161], v166 offset:1024
	ds_read_b128 v[162:165], v166 offset:2048
	ds_read_b128 v[166:169], v166 offset:3072
	s_mov_b32 m0, s82
	v_lshl_add_u64 v[216:217], s[64:65], 0, v[128:129]
	global_load_lds_dwordx4 v[216:217], off
	s_mov_b32 m0, s83
	v_lshl_add_u64 v[216:217], s[64:65], 0, v[130:131]
	global_load_lds_dwordx4 v[216:217], off
	s_waitcnt vmcnt(8) lgkmcnt(0)
	s_setprio 1
	s_barrier
	v_mfma_f32_16x16x32_bf16 v[124:127], v[138:141], v[170:173], v[124:127]
	v_mfma_f32_16x16x32_bf16 v[120:123], v[146:149], v[170:173], v[120:123]
	v_mfma_f32_16x16x32_bf16 v[116:119], v[138:141], v[182:185], v[116:119]
	v_mfma_f32_16x16x32_bf16 v[112:115], v[146:149], v[182:185], v[112:115]
	v_mfma_f32_16x16x32_bf16 v[104:107], v[138:141], v[190:193], v[104:107]
	v_mfma_f32_16x16x32_bf16 v[96:99], v[146:149], v[190:193], v[96:99]
	v_mfma_f32_16x16x32_bf16 v[88:91], v[138:141], v[206:209], v[88:91]
	v_mfma_f32_16x16x32_bf16 v[80:83], v[146:149], v[206:209], v[80:83]
	v_mfma_f32_16x16x32_bf16 v[124:127], v[142:145], v[178:181], v[124:127]
	v_mfma_f32_16x16x32_bf16 v[120:123], v[150:153], v[178:181], v[120:123]
	v_mfma_f32_16x16x32_bf16 v[116:119], v[142:145], v[186:189], v[116:119]
	v_mfma_f32_16x16x32_bf16 v[112:115], v[150:153], v[186:189], v[112:115]
	v_mfma_f32_16x16x32_bf16 v[104:107], v[142:145], v[194:197], v[104:107]
	v_mfma_f32_16x16x32_bf16 v[96:99], v[150:153], v[194:197], v[96:99]
	v_mfma_f32_16x16x32_bf16 v[88:91], v[142:145], v[210:213], v[88:91]
	v_mfma_f32_16x16x32_bf16 v[80:83], v[150:153], v[210:213], v[80:83]
	v_mfma_f32_16x16x32_bf16 v[108:111], v[154:157], v[170:173], v[108:111]
	v_mfma_f32_16x16x32_bf16 v[100:103], v[162:165], v[170:173], v[100:103]
	v_mfma_f32_16x16x32_bf16 v[92:95], v[154:157], v[182:185], v[92:95]
	v_mfma_f32_16x16x32_bf16 v[84:87], v[162:165], v[182:185], v[84:87]
	v_mfma_f32_16x16x32_bf16 v[76:79], v[154:157], v[190:193], v[76:79]
	v_mfma_f32_16x16x32_bf16 v[72:75], v[162:165], v[190:193], v[72:75]
	v_mfma_f32_16x16x32_bf16 v[68:71], v[154:157], v[206:209], v[68:71]
	v_mfma_f32_16x16x32_bf16 v[64:67], v[162:165], v[206:209], v[64:67]
	v_mfma_f32_16x16x32_bf16 v[108:111], v[158:161], v[178:181], v[108:111]
	v_mfma_f32_16x16x32_bf16 v[100:103], v[166:169], v[178:181], v[100:103]
	v_mfma_f32_16x16x32_bf16 v[92:95], v[158:161], v[186:189], v[92:95]
	v_mfma_f32_16x16x32_bf16 v[84:87], v[166:169], v[186:189], v[84:87]
	v_mfma_f32_16x16x32_bf16 v[76:79], v[158:161], v[194:197], v[76:79]
	v_mfma_f32_16x16x32_bf16 v[72:75], v[166:169], v[194:197], v[72:75]
	v_mfma_f32_16x16x32_bf16 v[68:71], v[158:161], v[210:213], v[68:71]
	s_setprio 0
	v_mfma_f32_16x16x32_bf16 v[64:67], v[166:169], v[210:213], v[64:67]
	s_barrier
	ds_read_b128 v[170:173], v137 offset:49152
	ds_read_b128 v[178:181], v137 offset:50176
	ds_read_b128 v[182:185], v137 offset:51200
	ds_read_b128 v[186:189], v137 offset:52224
	ds_read_b128 v[190:193], v137 offset:53248
	ds_read_b128 v[194:197], v137 offset:54272
	ds_read_b128 v[206:209], v137 offset:55296
	ds_read_b128 v[210:213], v137 offset:56320
	s_mov_b32 m0, s1
	v_lshl_add_u64 v[174:175], v[174:175], 0, s[26:27]
	global_load_lds_dwordx4 v[174:175], off
	s_mov_b32 m0, s9
	v_lshl_add_u64 v[174:175], v[198:199], 0, s[26:27]
	global_load_lds_dwordx4 v[174:175], off
	s_mov_b32 m0, s97
	v_lshl_add_u64 v[174:175], s[62:63], 0, v[128:129]
	global_load_lds_dwordx4 v[174:175], off
	s_mov_b32 m0, s8
	v_lshl_add_u64 v[174:175], s[62:63], 0, v[130:131]
	global_load_lds_dwordx4 v[174:175], off
	s_mov_b32 m0, s89
	v_lshl_add_u64 v[174:175], v[202:203], 0, s[26:27]
	global_load_lds_dwordx4 v[174:175], off
	s_mov_b32 m0, s90
	v_lshl_add_u64 v[174:175], v[214:215], 0, s[26:27]
	global_load_lds_dwordx4 v[174:175], off
	s_waitcnt vmcnt(8) lgkmcnt(0)
	s_setprio 1
	s_barrier
	v_mfma_f32_16x16x32_bf16 v[60:63], v[138:141], v[170:173], v[60:63]
	v_mfma_f32_16x16x32_bf16 v[56:59], v[146:149], v[170:173], v[56:59]
	v_mfma_f32_16x16x32_bf16 v[52:55], v[138:141], v[182:185], v[52:55]
	v_mfma_f32_16x16x32_bf16 v[48:51], v[146:149], v[182:185], v[48:51]
	v_mfma_f32_16x16x32_bf16 v[40:43], v[138:141], v[190:193], v[40:43]
	v_mfma_f32_16x16x32_bf16 v[32:35], v[146:149], v[190:193], v[32:35]
	v_mfma_f32_16x16x32_bf16 v[24:27], v[138:141], v[206:209], v[24:27]
	v_mfma_f32_16x16x32_bf16 v[16:19], v[146:149], v[206:209], v[16:19]
	v_mfma_f32_16x16x32_bf16 v[60:63], v[142:145], v[178:181], v[60:63]
	v_mfma_f32_16x16x32_bf16 v[56:59], v[150:153], v[178:181], v[56:59]
	v_mfma_f32_16x16x32_bf16 v[52:55], v[142:145], v[186:189], v[52:55]
	v_mfma_f32_16x16x32_bf16 v[48:51], v[150:153], v[186:189], v[48:51]
	v_mfma_f32_16x16x32_bf16 v[40:43], v[142:145], v[194:197], v[40:43]
	v_mfma_f32_16x16x32_bf16 v[32:35], v[150:153], v[194:197], v[32:35]
	v_mfma_f32_16x16x32_bf16 v[24:27], v[142:145], v[210:213], v[24:27]
	v_mfma_f32_16x16x32_bf16 v[16:19], v[150:153], v[210:213], v[16:19]
	v_mfma_f32_16x16x32_bf16 v[44:47], v[154:157], v[170:173], v[44:47]
	v_mfma_f32_16x16x32_bf16 v[36:39], v[162:165], v[170:173], v[36:39]
	v_mfma_f32_16x16x32_bf16 v[28:31], v[154:157], v[182:185], v[28:31]
	v_mfma_f32_16x16x32_bf16 v[20:23], v[162:165], v[182:185], v[20:23]
	v_mfma_f32_16x16x32_bf16 v[12:15], v[154:157], v[190:193], v[12:15]
	v_mfma_f32_16x16x32_bf16 v[8:11], v[162:165], v[190:193], v[8:11]
	v_mfma_f32_16x16x32_bf16 v[4:7], v[154:157], v[206:209], v[4:7]
	v_mfma_f32_16x16x32_bf16 v[0:3], v[162:165], v[206:209], v[0:3]
	v_mfma_f32_16x16x32_bf16 v[44:47], v[158:161], v[178:181], v[44:47]
	v_mfma_f32_16x16x32_bf16 v[36:39], v[166:169], v[178:181], v[36:39]
	v_mfma_f32_16x16x32_bf16 v[28:31], v[158:161], v[186:189], v[28:31]
	v_mfma_f32_16x16x32_bf16 v[20:23], v[166:169], v[186:189], v[20:23]
	v_mfma_f32_16x16x32_bf16 v[12:15], v[158:161], v[194:197], v[12:15]
	v_mfma_f32_16x16x32_bf16 v[8:11], v[166:169], v[194:197], v[8:11]
	v_mfma_f32_16x16x32_bf16 v[4:7], v[158:161], v[210:213], v[4:7]
	s_setprio 0
	v_mfma_f32_16x16x32_bf16 v[0:3], v[166:169], v[210:213], v[0:3]
	s_barrier
	s_mov_b64 s[66:67], 0
	s_mov_b64 s[62:63], -1
	s_mov_b64 s[64:65], 0x100
	s_cbranch_vccz .LBB0_877
	s_and_b64 vcc, exec, s[28:29]
	s_cbranch_vccz .LBB0_880
	s_barrier

.LBB0_904:
	ds_read_b128 v[142:145], v135 offset:1024
	ds_read_b128 v[146:149], v135 offset:2048
	ds_read_b128 v[150:153], v135 offset:3072
	ds_read_b128 v[154:157], v136
	ds_read_b128 v[158:161], v136 offset:1024
	ds_read_b128 v[162:165], v136 offset:2048
	ds_read_b128 v[166:169], v136 offset:3072
	ds_read_b128 v[170:173], v137
	ds_read_b128 v[178:181], v137 offset:1024
	ds_read_b128 v[182:185], v137 offset:2048
	ds_read_b128 v[186:189], v137 offset:3072
	ds_read_b128 v[190:193], v137 offset:4096
	ds_read_b128 v[194:197], v137 offset:5120
	ds_read_b128 v[206:209], v137 offset:6144
	ds_read_b128 v[210:213], v137 offset:7168
	s_add_u32 s2, s28, s56
	s_addc_u32 s3, s29, s57
	s_add_u32 s8, s2, 0x100
	s_addc_u32 s9, s3, 0
	s_and_b64 s[0:1], s[54:55], exec
	v_cndmask_b32_e64 v138, 0, 1, s[58:59]
	s_cselect_b32 s59, s13, s9
	s_cselect_b32 s58, s15, s8
	s_add_u32 s0, s22, s56
	s_addc_u32 s1, s23, s57
	s_add_u32 s8, s0, 0x100
	s_addc_u32 s9, s1, 0
	s_and_b64 s[0:1], s[54:55], exec
	s_cselect_b32 s61, s87, s9
	s_cselect_b32 s60, s88, s8
	s_add_u32 s64, s2, 0x10080
	v_cmp_ne_u32_e32 vcc, 1, v138
	ds_read_b128 v[138:141], v135
	s_addc_u32 s65, s3, 0
	s_add_i32 s38, s83, s66
	s_add_i32 m0, s69, 0xc000
	s_add_i32 s39, s69, 0xe000
	s_add_i32 s0, s38, 0x2000
	s_add_u32 s62, s60, 0x10000
	s_addc_u32 s63, s61, 0
	s_add_i32 s90, s84, s66
	s_add_i32 s76, s90, 0x2000
	s_add_i32 s3, 0, 0x18000
	s_add_i32 s2, 0, 0x1c000
	s_add_u32 s56, s58, 0x10000
	s_addc_u32 s57, s59, 0
	s_add_i32 s1, s3, s66
	s_add_i32 s9, s1, 0x2000
	s_add_u32 s54, s60, 0x10080
	s_addc_u32 s55, s61, 0
	s_add_i32 s89, s2, s66
	s_add_i32 s8, s89, 0x2000
	v_lshl_add_u64 v[174:175], s[64:65], 0, v[128:129]
	global_load_lds_dwordx4 v[174:175], off
	s_mov_b32 m0, s39
	v_lshl_add_u64 v[174:175], s[64:65], 0, v[130:131]
	global_load_lds_dwordx4 v[174:175], off
	s_waitcnt vmcnt(8) lgkmcnt(0)
	s_setprio 1
	s_barrier
	v_mfma_f32_16x16x32_bf16 v[124:127], v[138:141], v[170:173], v[124:127]
	v_mfma_f32_16x16x32_bf16 v[120:123], v[146:149], v[170:173], v[120:123]
	v_mfma_f32_16x16x32_bf16 v[116:119], v[138:141], v[182:185], v[116:119]
	v_mfma_f32_16x16x32_bf16 v[112:115], v[146:149], v[182:185], v[112:115]
	v_mfma_f32_16x16x32_bf16 v[104:107], v[138:141], v[190:193], v[104:107]
	v_mfma_f32_16x16x32_bf16 v[96:99], v[146:149], v[190:193], v[96:99]
	v_mfma_f32_16x16x32_bf16 v[88:91], v[138:141], v[206:209], v[88:91]
	v_mfma_f32_16x16x32_bf16 v[80:83], v[146:149], v[206:209], v[80:83]
	v_mfma_f32_16x16x32_bf16 v[124:127], v[142:145], v[178:181], v[124:127]
	v_mfma_f32_16x16x32_bf16 v[120:123], v[150:153], v[178:181], v[120:123]
	v_mfma_f32_16x16x32_bf16 v[116:119], v[142:145], v[186:189], v[116:119]
	v_mfma_f32_16x16x32_bf16 v[112:115], v[150:153], v[186:189], v[112:115]
	v_mfma_f32_16x16x32_bf16 v[104:107], v[142:145], v[194:197], v[104:107]
	v_mfma_f32_16x16x32_bf16 v[96:99], v[150:153], v[194:197], v[96:99]
	v_mfma_f32_16x16x32_bf16 v[88:91], v[142:145], v[210:213], v[88:91]
	v_mfma_f32_16x16x32_bf16 v[80:83], v[150:153], v[210:213], v[80:83]
	v_mfma_f32_16x16x32_bf16 v[108:111], v[154:157], v[170:173], v[108:111]
	v_mfma_f32_16x16x32_bf16 v[100:103], v[162:165], v[170:173], v[100:103]
	v_mfma_f32_16x16x32_bf16 v[92:95], v[154:157], v[182:185], v[92:95]
	v_mfma_f32_16x16x32_bf16 v[84:87], v[162:165], v[182:185], v[84:87]
	v_mfma_f32_16x16x32_bf16 v[76:79], v[154:157], v[190:193], v[76:79]
	v_mfma_f32_16x16x32_bf16 v[72:75], v[162:165], v[190:193], v[72:75]
	v_mfma_f32_16x16x32_bf16 v[68:71], v[154:157], v[206:209], v[68:71]
	v_mfma_f32_16x16x32_bf16 v[64:67], v[162:165], v[206:209], v[64:67]
	v_mfma_f32_16x16x32_bf16 v[108:111], v[158:161], v[178:181], v[108:111]
	v_mfma_f32_16x16x32_bf16 v[100:103], v[166:169], v[178:181], v[100:103]
	v_mfma_f32_16x16x32_bf16 v[92:95], v[158:161], v[186:189], v[92:95]
	v_mfma_f32_16x16x32_bf16 v[84:87], v[166:169], v[186:189], v[84:87]
	v_mfma_f32_16x16x32_bf16 v[76:79], v[158:161], v[194:197], v[76:79]
	v_mfma_f32_16x16x32_bf16 v[72:75], v[166:169], v[194:197], v[72:75]
	v_mfma_f32_16x16x32_bf16 v[68:71], v[158:161], v[210:213], v[68:71]
	s_setprio 0
	v_mfma_f32_16x16x32_bf16 v[64:67], v[166:169], v[210:213], v[64:67]
	s_barrier
	ds_read_b128 v[170:173], v137 offset:16384
	ds_read_b128 v[178:181], v137 offset:17408
	ds_read_b128 v[182:185], v137 offset:18432
	ds_read_b128 v[186:189], v137 offset:19456
	ds_read_b128 v[190:193], v137 offset:20480
	ds_read_b128 v[194:197], v137 offset:21504
	ds_read_b128 v[206:209], v137 offset:22528
	ds_read_b128 v[210:213], v137 offset:23552
	s_mov_b32 m0, s38
	v_lshl_add_u64 v[174:175], s[60:61], 0, v[128:129]
	global_load_lds_dwordx4 v[174:175], off
	v_lshl_add_u64 v[198:199], s[60:61], 0, v[130:131]
	s_mov_b32 m0, s0
	v_lshl_add_u64 v[202:203], s[62:63], 0, v[128:129]
	global_load_lds_dwordx4 v[198:199], off
	s_mov_b32 m0, s90
	v_lshl_add_u64 v[214:215], s[58:59], 0, v[130:131]
	global_load_lds_dwordx4 v[202:203], off
	s_mov_b32 m0, s76
	v_lshl_add_u64 v[202:203], s[62:63], 0, v[130:131]
	global_load_lds_dwordx4 v[202:203], off
	s_mov_b32 m0, s69
	v_lshl_add_u64 v[202:203], s[58:59], 0, v[128:129]
	global_load_lds_dwordx4 v[202:203], off
	s_mov_b32 m0, s70
	s_nop 0
	global_load_lds_dwordx4 v[214:215], off
	s_waitcnt vmcnt(8) lgkmcnt(0)
	s_setprio 1
	s_barrier
	v_mfma_f32_16x16x32_bf16 v[60:63], v[138:141], v[170:173], v[60:63]
	v_mfma_f32_16x16x32_bf16 v[56:59], v[146:149], v[170:173], v[56:59]
	v_mfma_f32_16x16x32_bf16 v[52:55], v[138:141], v[182:185], v[52:55]
	v_mfma_f32_16x16x32_bf16 v[48:51], v[146:149], v[182:185], v[48:51]
	v_mfma_f32_16x16x32_bf16 v[40:43], v[138:141], v[190:193], v[40:43]
	v_mfma_f32_16x16x32_bf16 v[32:35], v[146:149], v[190:193], v[32:35]
	v_mfma_f32_16x16x32_bf16 v[24:27], v[138:141], v[206:209], v[24:27]
	v_mfma_f32_16x16x32_bf16 v[16:19], v[146:149], v[206:209], v[16:19]
	v_mfma_f32_16x16x32_bf16 v[60:63], v[142:145], v[178:181], v[60:63]
	v_mfma_f32_16x16x32_bf16 v[56:59], v[150:153], v[178:181], v[56:59]
	v_mfma_f32_16x16x32_bf16 v[52:55], v[142:145], v[186:189], v[52:55]
	v_mfma_f32_16x16x32_bf16 v[48:51], v[150:153], v[186:189], v[48:51]
	v_mfma_f32_16x16x32_bf16 v[40:43], v[142:145], v[194:197], v[40:43]
	v_mfma_f32_16x16x32_bf16 v[32:35], v[150:153], v[194:197], v[32:35]
	v_mfma_f32_16x16x32_bf16 v[24:27], v[142:145], v[210:213], v[24:27]
	v_mfma_f32_16x16x32_bf16 v[16:19], v[150:153], v[210:213], v[16:19]
	v_mfma_f32_16x16x32_bf16 v[44:47], v[154:157], v[170:173], v[44:47]
	v_mfma_f32_16x16x32_bf16 v[36:39], v[162:165], v[170:173], v[36:39]
	v_mfma_f32_16x16x32_bf16 v[28:31], v[154:157], v[182:185], v[28:31]
	v_mfma_f32_16x16x32_bf16 v[20:23], v[162:165], v[182:185], v[20:23]
	v_mfma_f32_16x16x32_bf16 v[12:15], v[154:157], v[190:193], v[12:15]
	v_mfma_f32_16x16x32_bf16 v[8:11], v[162:165], v[190:193], v[8:11]
	v_mfma_f32_16x16x32_bf16 v[4:7], v[154:157], v[206:209], v[4:7]
	v_mfma_f32_16x16x32_bf16 v[0:3], v[162:165], v[206:209], v[0:3]
	v_mfma_f32_16x16x32_bf16 v[44:47], v[158:161], v[178:181], v[44:47]
	v_mfma_f32_16x16x32_bf16 v[36:39], v[166:169], v[178:181], v[36:39]
	v_mfma_f32_16x16x32_bf16 v[28:31], v[158:161], v[186:189], v[28:31]
	v_mfma_f32_16x16x32_bf16 v[20:23], v[166:169], v[186:189], v[20:23]
	v_mfma_f32_16x16x32_bf16 v[12:15], v[158:161], v[194:197], v[12:15]
	v_mfma_f32_16x16x32_bf16 v[8:11], v[166:169], v[194:197], v[8:11]
	v_mfma_f32_16x16x32_bf16 v[4:7], v[158:161], v[210:213], v[4:7]
	s_setprio 0
	v_mfma_f32_16x16x32_bf16 v[0:3], v[166:169], v[210:213], v[0:3]
	s_barrier
	ds_read_b128 v[170:173], v137 offset:32768
	ds_read_b128 v[178:181], v137 offset:33792
	ds_read_b128 v[182:185], v137 offset:34816
	ds_read_b128 v[186:189], v137 offset:35840
	ds_read_b128 v[190:193], v137 offset:36864
	ds_read_b128 v[194:197], v137 offset:37888
	ds_read_b128 v[206:209], v137 offset:38912
	ds_read_b128 v[210:213], v137 offset:39936
	v_add_u32_e32 v150, s3, v134
	v_add_u32_e32 v166, s2, v134
	ds_read_b128 v[138:141], v150
	ds_read_b128 v[142:145], v150 offset:1024
	ds_read_b128 v[146:149], v150 offset:2048
	ds_read_b128 v[150:153], v150 offset:3072
	ds_read_b128 v[154:157], v166
	ds_read_b128 v[158:161], v166 offset:1024
	ds_read_b128 v[162:165], v166 offset:2048
	ds_read_b128 v[166:169], v166 offset:3072
	s_mov_b32 m0, s71
	v_lshl_add_u64 v[216:217], s[56:57], 0, v[128:129]
	global_load_lds_dwordx4 v[216:217], off
	s_mov_b32 m0, s72
	v_lshl_add_u64 v[216:217], s[56:57], 0, v[130:131]
	global_load_lds_dwordx4 v[216:217], off
	s_waitcnt vmcnt(8) lgkmcnt(0)
	s_setprio 1
	s_barrier
	v_mfma_f32_16x16x32_bf16 v[124:127], v[138:141], v[170:173], v[124:127]
	v_mfma_f32_16x16x32_bf16 v[120:123], v[146:149], v[170:173], v[120:123]
	v_mfma_f32_16x16x32_bf16 v[116:119], v[138:141], v[182:185], v[116:119]
	v_mfma_f32_16x16x32_bf16 v[112:115], v[146:149], v[182:185], v[112:115]
	v_mfma_f32_16x16x32_bf16 v[104:107], v[138:141], v[190:193], v[104:107]
	v_mfma_f32_16x16x32_bf16 v[96:99], v[146:149], v[190:193], v[96:99]
	v_mfma_f32_16x16x32_bf16 v[88:91], v[138:141], v[206:209], v[88:91]
	v_mfma_f32_16x16x32_bf16 v[80:83], v[146:149], v[206:209], v[80:83]
	v_mfma_f32_16x16x32_bf16 v[124:127], v[142:145], v[178:181], v[124:127]
	v_mfma_f32_16x16x32_bf16 v[120:123], v[150:153], v[178:181], v[120:123]
	v_mfma_f32_16x16x32_bf16 v[116:119], v[142:145], v[186:189], v[116:119]
	v_mfma_f32_16x16x32_bf16 v[112:115], v[150:153], v[186:189], v[112:115]
	v_mfma_f32_16x16x32_bf16 v[104:107], v[142:145], v[194:197], v[104:107]
	v_mfma_f32_16x16x32_bf16 v[96:99], v[150:153], v[194:197], v[96:99]
	v_mfma_f32_16x16x32_bf16 v[88:91], v[142:145], v[210:213], v[88:91]
	v_mfma_f32_16x16x32_bf16 v[80:83], v[150:153], v[210:213], v[80:83]
	v_mfma_f32_16x16x32_bf16 v[108:111], v[154:157], v[170:173], v[108:111]
	v_mfma_f32_16x16x32_bf16 v[100:103], v[162:165], v[170:173], v[100:103]
	v_mfma_f32_16x16x32_bf16 v[92:95], v[154:157], v[182:185], v[92:95]
	v_mfma_f32_16x16x32_bf16 v[84:87], v[162:165], v[182:185], v[84:87]
	v_mfma_f32_16x16x32_bf16 v[76:79], v[154:157], v[190:193], v[76:79]
	v_mfma_f32_16x16x32_bf16 v[72:75], v[162:165], v[190:193], v[72:75]
	v_mfma_f32_16x16x32_bf16 v[68:71], v[154:157], v[206:209], v[68:71]
	v_mfma_f32_16x16x32_bf16 v[64:67], v[162:165], v[206:209], v[64:67]
	v_mfma_f32_16x16x32_bf16 v[108:111], v[158:161], v[178:181], v[108:111]
	v_mfma_f32_16x16x32_bf16 v[100:103], v[166:169], v[178:181], v[100:103]
	v_mfma_f32_16x16x32_bf16 v[92:95], v[158:161], v[186:189], v[92:95]
	v_mfma_f32_16x16x32_bf16 v[84:87], v[166:169], v[186:189], v[84:87]
	v_mfma_f32_16x16x32_bf16 v[76:79], v[158:161], v[194:197], v[76:79]
	v_mfma_f32_16x16x32_bf16 v[72:75], v[166:169], v[194:197], v[72:75]
	v_mfma_f32_16x16x32_bf16 v[68:71], v[158:161], v[210:213], v[68:71]
	s_setprio 0
	v_mfma_f32_16x16x32_bf16 v[64:67], v[166:169], v[210:213], v[64:67]
	s_barrier
	ds_read_b128 v[170:173], v137 offset:49152
	ds_read_b128 v[178:181], v137 offset:50176
	ds_read_b128 v[182:185], v137 offset:51200
	ds_read_b128 v[186:189], v137 offset:52224
	ds_read_b128 v[190:193], v137 offset:53248
	ds_read_b128 v[194:197], v137 offset:54272
	ds_read_b128 v[206:209], v137 offset:55296
	ds_read_b128 v[210:213], v137 offset:56320
	s_mov_b32 m0, s1
	v_lshl_add_u64 v[174:175], v[174:175], 0, s[18:19]
	global_load_lds_dwordx4 v[174:175], off
	s_mov_b32 m0, s9
	v_lshl_add_u64 v[174:175], v[198:199], 0, s[18:19]
	global_load_lds_dwordx4 v[174:175], off
	s_mov_b32 m0, s89
	v_lshl_add_u64 v[174:175], s[54:55], 0, v[128:129]
	global_load_lds_dwordx4 v[174:175], off
	s_mov_b32 m0, s8
	v_lshl_add_u64 v[174:175], s[54:55], 0, v[130:131]
	global_load_lds_dwordx4 v[174:175], off
	s_mov_b32 m0, s81
	v_lshl_add_u64 v[174:175], v[202:203], 0, s[18:19]
	global_load_lds_dwordx4 v[174:175], off
	s_mov_b32 m0, s82
	v_lshl_add_u64 v[174:175], v[214:215], 0, s[18:19]
	global_load_lds_dwordx4 v[174:175], off
	s_waitcnt vmcnt(8) lgkmcnt(0)
	s_setprio 1
	s_barrier
	v_mfma_f32_16x16x32_bf16 v[60:63], v[138:141], v[170:173], v[60:63]
	v_mfma_f32_16x16x32_bf16 v[56:59], v[146:149], v[170:173], v[56:59]
	v_mfma_f32_16x16x32_bf16 v[52:55], v[138:141], v[182:185], v[52:55]
	v_mfma_f32_16x16x32_bf16 v[48:51], v[146:149], v[182:185], v[48:51]
	v_mfma_f32_16x16x32_bf16 v[40:43], v[138:141], v[190:193], v[40:43]
	v_mfma_f32_16x16x32_bf16 v[32:35], v[146:149], v[190:193], v[32:35]
	v_mfma_f32_16x16x32_bf16 v[24:27], v[138:141], v[206:209], v[24:27]
	v_mfma_f32_16x16x32_bf16 v[16:19], v[146:149], v[206:209], v[16:19]
	v_mfma_f32_16x16x32_bf16 v[60:63], v[142:145], v[178:181], v[60:63]
	v_mfma_f32_16x16x32_bf16 v[56:59], v[150:153], v[178:181], v[56:59]
	v_mfma_f32_16x16x32_bf16 v[52:55], v[142:145], v[186:189], v[52:55]
	v_mfma_f32_16x16x32_bf16 v[48:51], v[150:153], v[186:189], v[48:51]
	v_mfma_f32_16x16x32_bf16 v[40:43], v[142:145], v[194:197], v[40:43]
	v_mfma_f32_16x16x32_bf16 v[32:35], v[150:153], v[194:197], v[32:35]
	v_mfma_f32_16x16x32_bf16 v[24:27], v[142:145], v[210:213], v[24:27]
	v_mfma_f32_16x16x32_bf16 v[16:19], v[150:153], v[210:213], v[16:19]
	v_mfma_f32_16x16x32_bf16 v[44:47], v[154:157], v[170:173], v[44:47]
	v_mfma_f32_16x16x32_bf16 v[36:39], v[162:165], v[170:173], v[36:39]
	v_mfma_f32_16x16x32_bf16 v[28:31], v[154:157], v[182:185], v[28:31]
	v_mfma_f32_16x16x32_bf16 v[20:23], v[162:165], v[182:185], v[20:23]
	v_mfma_f32_16x16x32_bf16 v[12:15], v[154:157], v[190:193], v[12:15]
	v_mfma_f32_16x16x32_bf16 v[8:11], v[162:165], v[190:193], v[8:11]
	v_mfma_f32_16x16x32_bf16 v[4:7], v[154:157], v[206:209], v[4:7]
	v_mfma_f32_16x16x32_bf16 v[0:3], v[162:165], v[206:209], v[0:3]
	v_mfma_f32_16x16x32_bf16 v[44:47], v[158:161], v[178:181], v[44:47]
	v_mfma_f32_16x16x32_bf16 v[36:39], v[166:169], v[178:181], v[36:39]
	v_mfma_f32_16x16x32_bf16 v[28:31], v[158:161], v[186:189], v[28:31]
	v_mfma_f32_16x16x32_bf16 v[20:23], v[166:169], v[186:189], v[20:23]
	v_mfma_f32_16x16x32_bf16 v[12:15], v[158:161], v[194:197], v[12:15]
	v_mfma_f32_16x16x32_bf16 v[8:11], v[166:169], v[194:197], v[8:11]
	v_mfma_f32_16x16x32_bf16 v[4:7], v[158:161], v[210:213], v[4:7]
	s_setprio 0
	v_mfma_f32_16x16x32_bf16 v[0:3], v[166:169], v[210:213], v[0:3]
	s_barrier
	s_mov_b64 s[58:59], 0
	s_mov_b64 s[54:55], -1
	s_mov_b64 s[56:57], 0x100
	s_cbranch_vccz .LBB0_904
	s_and_b64 vcc, exec, s[20:21]
	s_cbranch_vccz .LBB0_907
	s_barrier

.LBB0_953:
	ds_read_b128 v[148:151], v145
	ds_read_b128 v[152:155], v145 offset:1024
	ds_read_b128 v[156:159], v145 offset:2048
	ds_read_b128 v[160:163], v145 offset:3072
	ds_read_b128 v[164:167], v146
	ds_read_b128 v[168:171], v146 offset:1024
	ds_read_b128 v[172:175], v146 offset:2048
	ds_read_b128 v[178:181], v146 offset:3072
	ds_read_b128 v[182:185], v147
	ds_read_b128 v[186:189], v147 offset:1024
	ds_read_b128 v[190:193], v147 offset:2048
	ds_read_b128 v[194:197], v147 offset:3072
	ds_read_b128 v[206:209], v147 offset:4096
	ds_read_b128 v[210:213], v147 offset:5120
	ds_read_b128 v[214:217], v147 offset:6144
	ds_read_b128 v[218:221], v147 offset:7168
	s_add_u32 s56, s54, 0x100
	s_addc_u32 s57, s55, 0
	s_cmp_eq_u32 vcc_hi, 20
	s_cselect_b32 s61, s93, s57
	s_cselect_b32 s60, s94, s56
	s_cselect_b32 s59, s95, vcc_lo
	s_cselect_b32 s58, s96, s97
	s_add_i32 m0, s67, 0xc000
	v_lshl_add_u64 v[140:141], s[54:55], 0, v[136:137]
	global_load_lds_dwordx4 v[140:141], off
	s_add_i32 m0, s67, 0xe000
	v_lshl_add_u64 v[140:141], s[54:55], 0, v[138:139]
	global_load_lds_dwordx4 v[140:141], off
	s_waitcnt vmcnt(8) lgkmcnt(0)
	s_setprio 1
	s_barrier
	v_mfma_f32_16x16x32_bf16 v[124:127], v[148:151], v[182:185], v[124:127]
	v_mfma_f32_16x16x32_bf16 v[120:123], v[156:159], v[182:185], v[120:123]
	v_mfma_f32_16x16x32_bf16 v[116:119], v[148:151], v[190:193], v[116:119]
	v_mfma_f32_16x16x32_bf16 v[108:111], v[156:159], v[190:193], v[108:111]
	v_mfma_f32_16x16x32_bf16 v[100:103], v[148:151], v[206:209], v[100:103]
	v_mfma_f32_16x16x32_bf16 v[92:95], v[156:159], v[206:209], v[92:95]
	v_mfma_f32_16x16x32_bf16 v[84:87], v[148:151], v[214:217], v[84:87]
	v_mfma_f32_16x16x32_bf16 v[76:79], v[156:159], v[214:217], v[76:79]
	v_mfma_f32_16x16x32_bf16 v[124:127], v[152:155], v[186:189], v[124:127]
	v_mfma_f32_16x16x32_bf16 v[120:123], v[160:163], v[186:189], v[120:123]
	v_mfma_f32_16x16x32_bf16 v[116:119], v[152:155], v[194:197], v[116:119]
	v_mfma_f32_16x16x32_bf16 v[108:111], v[160:163], v[194:197], v[108:111]
	v_mfma_f32_16x16x32_bf16 v[100:103], v[152:155], v[210:213], v[100:103]
	v_mfma_f32_16x16x32_bf16 v[92:95], v[160:163], v[210:213], v[92:95]
	v_mfma_f32_16x16x32_bf16 v[84:87], v[152:155], v[218:221], v[84:87]
	v_mfma_f32_16x16x32_bf16 v[76:79], v[160:163], v[218:221], v[76:79]
	v_mfma_f32_16x16x32_bf16 v[112:115], v[164:167], v[182:185], v[112:115]
	v_mfma_f32_16x16x32_bf16 v[104:107], v[172:175], v[182:185], v[104:107]
	v_mfma_f32_16x16x32_bf16 v[96:99], v[164:167], v[190:193], v[96:99]
	v_mfma_f32_16x16x32_bf16 v[88:91], v[172:175], v[190:193], v[88:91]
	v_mfma_f32_16x16x32_bf16 v[80:83], v[164:167], v[206:209], v[80:83]
	v_mfma_f32_16x16x32_bf16 v[72:75], v[172:175], v[206:209], v[72:75]
	v_mfma_f32_16x16x32_bf16 v[68:71], v[164:167], v[214:217], v[68:71]
	v_mfma_f32_16x16x32_bf16 v[64:67], v[172:175], v[214:217], v[64:67]
	v_mfma_f32_16x16x32_bf16 v[112:115], v[168:171], v[186:189], v[112:115]
	v_mfma_f32_16x16x32_bf16 v[104:107], v[178:181], v[186:189], v[104:107]
	v_mfma_f32_16x16x32_bf16 v[96:99], v[168:171], v[194:197], v[96:99]
	v_mfma_f32_16x16x32_bf16 v[88:91], v[178:181], v[194:197], v[88:91]
	v_mfma_f32_16x16x32_bf16 v[80:83], v[168:171], v[210:213], v[80:83]
	v_mfma_f32_16x16x32_bf16 v[72:75], v[178:181], v[210:213], v[72:75]
	v_mfma_f32_16x16x32_bf16 v[68:71], v[168:171], v[218:221], v[68:71]
	s_setprio 0
	v_mfma_f32_16x16x32_bf16 v[64:67], v[178:181], v[218:221], v[64:67]
	s_barrier
	ds_read_b128 v[182:185], v147 offset:16384
	ds_read_b128 v[186:189], v147 offset:17408
	ds_read_b128 v[190:193], v147 offset:18432
	ds_read_b128 v[194:197], v147 offset:19456
	ds_read_b128 v[206:209], v147 offset:20480
	ds_read_b128 v[210:213], v147 offset:21504
	ds_read_b128 v[214:217], v147 offset:22528
	ds_read_b128 v[218:221], v147 offset:23552
	s_add_i32 s0, s79, s66
	s_mov_b32 m0, s0
	v_lshl_add_u64 v[140:141], s[58:59], 0, v[130:131]
	global_load_lds_dwordx4 v[140:141], off
	s_add_i32 m0, s0, 0x2000
	s_add_u32 s0, s58, 0x60000
	v_lshl_add_u64 v[198:199], s[58:59], 0, v[134:135]
	s_addc_u32 s1, s59, 0
	s_add_i32 s2, s80, s66
	global_load_lds_dwordx4 v[198:199], off
	v_lshl_add_u64 v[202:203], s[0:1], 0, v[130:131]
	s_mov_b32 m0, s2
	v_lshl_add_u64 v[222:223], s[60:61], 0, v[132:133]
	global_load_lds_dwordx4 v[202:203], off
	s_add_i32 m0, s2, 0x2000
	v_lshl_add_u64 v[202:203], s[0:1], 0, v[134:135]
	global_load_lds_dwordx4 v[202:203], off
	s_mov_b32 m0, s67
	v_lshl_add_u64 v[202:203], s[60:61], 0, v[128:129]
	global_load_lds_dwordx4 v[202:203], off
	s_mov_b32 m0, s68
	s_nop 0
	global_load_lds_dwordx4 v[222:223], off
	s_waitcnt vmcnt(8) lgkmcnt(0)
	s_setprio 1
	s_barrier
	v_mfma_f32_16x16x32_bf16 v[60:63], v[148:151], v[182:185], v[60:63]
	v_mfma_f32_16x16x32_bf16 v[56:59], v[156:159], v[182:185], v[56:59]
	v_mfma_f32_16x16x32_bf16 v[52:55], v[148:151], v[190:193], v[52:55]
	v_mfma_f32_16x16x32_bf16 v[44:47], v[156:159], v[190:193], v[44:47]
	v_mfma_f32_16x16x32_bf16 v[36:39], v[148:151], v[206:209], v[36:39]
	v_mfma_f32_16x16x32_bf16 v[28:31], v[156:159], v[206:209], v[28:31]
	v_mfma_f32_16x16x32_bf16 v[20:23], v[148:151], v[214:217], v[20:23]
	v_mfma_f32_16x16x32_bf16 v[12:15], v[156:159], v[214:217], v[12:15]
	v_mfma_f32_16x16x32_bf16 v[60:63], v[152:155], v[186:189], v[60:63]
	v_mfma_f32_16x16x32_bf16 v[56:59], v[160:163], v[186:189], v[56:59]
	v_mfma_f32_16x16x32_bf16 v[52:55], v[152:155], v[194:197], v[52:55]
	v_mfma_f32_16x16x32_bf16 v[44:47], v[160:163], v[194:197], v[44:47]
	v_mfma_f32_16x16x32_bf16 v[36:39], v[152:155], v[210:213], v[36:39]
	v_mfma_f32_16x16x32_bf16 v[28:31], v[160:163], v[210:213], v[28:31]
	v_mfma_f32_16x16x32_bf16 v[20:23], v[152:155], v[218:221], v[20:23]
	v_mfma_f32_16x16x32_bf16 v[12:15], v[160:163], v[218:221], v[12:15]
	v_mfma_f32_16x16x32_bf16 v[48:51], v[164:167], v[182:185], v[48:51]
	v_mfma_f32_16x16x32_bf16 v[40:43], v[172:175], v[182:185], v[40:43]
	v_mfma_f32_16x16x32_bf16 v[32:35], v[164:167], v[190:193], v[32:35]
	v_mfma_f32_16x16x32_bf16 v[24:27], v[172:175], v[190:193], v[24:27]
	v_mfma_f32_16x16x32_bf16 v[16:19], v[164:167], v[206:209], v[16:19]
	v_mfma_f32_16x16x32_bf16 v[8:11], v[172:175], v[206:209], v[8:11]
	v_mfma_f32_16x16x32_bf16 v[4:7], v[164:167], v[214:217], v[4:7]
	v_mfma_f32_16x16x32_bf16 v[0:3], v[172:175], v[214:217], v[0:3]
	v_mfma_f32_16x16x32_bf16 v[48:51], v[168:171], v[186:189], v[48:51]
	v_mfma_f32_16x16x32_bf16 v[40:43], v[178:181], v[186:189], v[40:43]
	v_mfma_f32_16x16x32_bf16 v[32:35], v[168:171], v[194:197], v[32:35]
	v_mfma_f32_16x16x32_bf16 v[24:27], v[178:181], v[194:197], v[24:27]
	v_mfma_f32_16x16x32_bf16 v[16:19], v[168:171], v[210:213], v[16:19]
	v_mfma_f32_16x16x32_bf16 v[8:11], v[178:181], v[210:213], v[8:11]
	v_mfma_f32_16x16x32_bf16 v[4:7], v[168:171], v[218:221], v[4:7]
	s_setprio 0
	v_mfma_f32_16x16x32_bf16 v[0:3], v[178:181], v[218:221], v[0:3]
	s_barrier
	ds_read_b128 v[182:185], v147 offset:32768
	ds_read_b128 v[186:189], v147 offset:33792
	ds_read_b128 v[190:193], v147 offset:34816
	ds_read_b128 v[194:197], v147 offset:35840
	ds_read_b128 v[206:209], v147 offset:36864
	ds_read_b128 v[210:213], v147 offset:37888
	ds_read_b128 v[214:217], v147 offset:38912
	ds_read_b128 v[218:221], v147 offset:39936
	s_add_i32 s2, 0, 0x18000
	s_add_i32 s3, 0, 0x1c000
	v_add_u32_e32 v160, s2, v144
	v_add_u32_e32 v177, s3, v144
	ds_read_b128 v[148:151], v160
	ds_read_b128 v[152:155], v160 offset:1024
	ds_read_b128 v[156:159], v160 offset:2048
	ds_read_b128 v[160:163], v160 offset:3072
	ds_read_b128 v[164:167], v177
	ds_read_b128 v[168:171], v177 offset:1024
	ds_read_b128 v[172:175], v177 offset:2048
	ds_read_b128 v[178:181], v177 offset:3072
	s_add_u32 s0, s60, 0x60000
	s_addc_u32 s1, s61, 0
	s_mov_b32 m0, s69
	v_lshl_add_u64 v[224:225], s[0:1], 0, v[128:129]
	global_load_lds_dwordx4 v[224:225], off
	s_mov_b32 m0, s70
	v_lshl_add_u64 v[224:225], s[0:1], 0, v[132:133]
	global_load_lds_dwordx4 v[224:225], off
	s_waitcnt vmcnt(8) lgkmcnt(0)
	s_setprio 1
	s_barrier
	v_mfma_f32_16x16x32_bf16 v[124:127], v[148:151], v[182:185], v[124:127]
	v_mfma_f32_16x16x32_bf16 v[120:123], v[156:159], v[182:185], v[120:123]
	v_mfma_f32_16x16x32_bf16 v[116:119], v[148:151], v[190:193], v[116:119]
	v_mfma_f32_16x16x32_bf16 v[108:111], v[156:159], v[190:193], v[108:111]
	v_mfma_f32_16x16x32_bf16 v[100:103], v[148:151], v[206:209], v[100:103]
	v_mfma_f32_16x16x32_bf16 v[92:95], v[156:159], v[206:209], v[92:95]
	v_mfma_f32_16x16x32_bf16 v[84:87], v[148:151], v[214:217], v[84:87]
	v_mfma_f32_16x16x32_bf16 v[76:79], v[156:159], v[214:217], v[76:79]
	v_mfma_f32_16x16x32_bf16 v[124:127], v[152:155], v[186:189], v[124:127]
	v_mfma_f32_16x16x32_bf16 v[120:123], v[160:163], v[186:189], v[120:123]
	v_mfma_f32_16x16x32_bf16 v[116:119], v[152:155], v[194:197], v[116:119]
	v_mfma_f32_16x16x32_bf16 v[108:111], v[160:163], v[194:197], v[108:111]
	v_mfma_f32_16x16x32_bf16 v[100:103], v[152:155], v[210:213], v[100:103]
	v_mfma_f32_16x16x32_bf16 v[92:95], v[160:163], v[210:213], v[92:95]
	v_mfma_f32_16x16x32_bf16 v[84:87], v[152:155], v[218:221], v[84:87]
	v_mfma_f32_16x16x32_bf16 v[76:79], v[160:163], v[218:221], v[76:79]
	v_mfma_f32_16x16x32_bf16 v[112:115], v[164:167], v[182:185], v[112:115]
	v_mfma_f32_16x16x32_bf16 v[104:107], v[172:175], v[182:185], v[104:107]
	v_mfma_f32_16x16x32_bf16 v[96:99], v[164:167], v[190:193], v[96:99]
	v_mfma_f32_16x16x32_bf16 v[88:91], v[172:175], v[190:193], v[88:91]
	v_mfma_f32_16x16x32_bf16 v[80:83], v[164:167], v[206:209], v[80:83]
	v_mfma_f32_16x16x32_bf16 v[72:75], v[172:175], v[206:209], v[72:75]
	v_mfma_f32_16x16x32_bf16 v[68:71], v[164:167], v[214:217], v[68:71]
	v_mfma_f32_16x16x32_bf16 v[64:67], v[172:175], v[214:217], v[64:67]
	v_mfma_f32_16x16x32_bf16 v[112:115], v[168:171], v[186:189], v[112:115]
	v_mfma_f32_16x16x32_bf16 v[104:107], v[178:181], v[186:189], v[104:107]
	v_mfma_f32_16x16x32_bf16 v[96:99], v[168:171], v[194:197], v[96:99]
	v_mfma_f32_16x16x32_bf16 v[88:91], v[178:181], v[194:197], v[88:91]
	v_mfma_f32_16x16x32_bf16 v[80:83], v[168:171], v[210:213], v[80:83]
	v_mfma_f32_16x16x32_bf16 v[72:75], v[178:181], v[210:213], v[72:75]
	v_mfma_f32_16x16x32_bf16 v[68:71], v[168:171], v[218:221], v[68:71]
	s_setprio 0
	v_mfma_f32_16x16x32_bf16 v[64:67], v[178:181], v[218:221], v[64:67]
	s_barrier
	ds_read_b128 v[182:185], v147 offset:49152
	ds_read_b128 v[186:189], v147 offset:50176
	ds_read_b128 v[190:193], v147 offset:51200
	ds_read_b128 v[194:197], v147 offset:52224
	ds_read_b128 v[206:209], v147 offset:53248
	ds_read_b128 v[210:213], v147 offset:54272
	ds_read_b128 v[214:217], v147 offset:55296
	ds_read_b128 v[218:221], v147 offset:56320
	s_add_i32 s0, s2, s66
	s_mov_b32 m0, s0
	v_lshl_add_u64 v[140:141], v[140:141], 0, s[12:13]
	global_load_lds_dwordx4 v[140:141], off
	s_add_i32 m0, s0, 0x2000
	s_add_u32 s0, s58, 0x60080
	v_lshl_add_u64 v[140:141], v[198:199], 0, s[12:13]
	s_addc_u32 s1, s59, 0
	s_add_i32 s2, s3, s66
	global_load_lds_dwordx4 v[140:141], off
	s_mov_b32 m0, s2
	v_lshl_add_u64 v[140:141], s[0:1], 0, v[130:131]
	global_load_lds_dwordx4 v[140:141], off
	s_add_i32 m0, s2, 0x2000
	v_lshl_add_u64 v[140:141], s[0:1], 0, v[134:135]
	global_load_lds_dwordx4 v[140:141], off
	s_mov_b32 m0, s77
	v_lshl_add_u64 v[140:141], v[202:203], 0, s[12:13]
	global_load_lds_dwordx4 v[140:141], off
	s_mov_b32 m0, s78
	v_lshl_add_u64 v[140:141], v[222:223], 0, s[12:13]
	global_load_lds_dwordx4 v[140:141], off
	s_waitcnt vmcnt(8) lgkmcnt(0)
	s_setprio 1
	s_barrier
	v_mfma_f32_16x16x32_bf16 v[60:63], v[148:151], v[182:185], v[60:63]
	v_mfma_f32_16x16x32_bf16 v[56:59], v[156:159], v[182:185], v[56:59]
	v_mfma_f32_16x16x32_bf16 v[52:55], v[148:151], v[190:193], v[52:55]
	v_mfma_f32_16x16x32_bf16 v[44:47], v[156:159], v[190:193], v[44:47]
	v_mfma_f32_16x16x32_bf16 v[36:39], v[148:151], v[206:209], v[36:39]
	v_mfma_f32_16x16x32_bf16 v[28:31], v[156:159], v[206:209], v[28:31]
	v_mfma_f32_16x16x32_bf16 v[20:23], v[148:151], v[214:217], v[20:23]
	v_mfma_f32_16x16x32_bf16 v[12:15], v[156:159], v[214:217], v[12:15]
	v_mfma_f32_16x16x32_bf16 v[60:63], v[152:155], v[186:189], v[60:63]
	v_mfma_f32_16x16x32_bf16 v[56:59], v[160:163], v[186:189], v[56:59]
	v_mfma_f32_16x16x32_bf16 v[52:55], v[152:155], v[194:197], v[52:55]
	v_mfma_f32_16x16x32_bf16 v[44:47], v[160:163], v[194:197], v[44:47]
	v_mfma_f32_16x16x32_bf16 v[36:39], v[152:155], v[210:213], v[36:39]
	v_mfma_f32_16x16x32_bf16 v[28:31], v[160:163], v[210:213], v[28:31]
	v_mfma_f32_16x16x32_bf16 v[20:23], v[152:155], v[218:221], v[20:23]
	v_mfma_f32_16x16x32_bf16 v[12:15], v[160:163], v[218:221], v[12:15]
	v_mfma_f32_16x16x32_bf16 v[48:51], v[164:167], v[182:185], v[48:51]
	v_mfma_f32_16x16x32_bf16 v[40:43], v[172:175], v[182:185], v[40:43]
	v_mfma_f32_16x16x32_bf16 v[32:35], v[164:167], v[190:193], v[32:35]
	v_mfma_f32_16x16x32_bf16 v[24:27], v[172:175], v[190:193], v[24:27]
	v_mfma_f32_16x16x32_bf16 v[16:19], v[164:167], v[206:209], v[16:19]
	v_mfma_f32_16x16x32_bf16 v[8:11], v[172:175], v[206:209], v[8:11]
	v_mfma_f32_16x16x32_bf16 v[4:7], v[164:167], v[214:217], v[4:7]
	v_mfma_f32_16x16x32_bf16 v[0:3], v[172:175], v[214:217], v[0:3]
	v_mfma_f32_16x16x32_bf16 v[48:51], v[168:171], v[186:189], v[48:51]
	v_mfma_f32_16x16x32_bf16 v[40:43], v[178:181], v[186:189], v[40:43]
	s_add_i32 vcc_hi, vcc_hi, 2
	v_mfma_f32_16x16x32_bf16 v[32:35], v[168:171], v[194:197], v[32:35]
	s_add_u32 s97, s97, 0x100
	v_mfma_f32_16x16x32_bf16 v[24:27], v[178:181], v[194:197], v[24:27]
	s_addc_u32 vcc_lo, vcc_lo, 0
	v_mfma_f32_16x16x32_bf16 v[16:19], v[168:171], v[210:213], v[16:19]
	s_cmp_gt_u32 vcc_hi, 21
	v_mfma_f32_16x16x32_bf16 v[8:11], v[178:181], v[210:213], v[8:11]
	s_mov_b64 s[54:55], s[56:57]
	v_mfma_f32_16x16x32_bf16 v[4:7], v[168:171], v[218:221], v[4:7]
	s_setprio 0
	v_mfma_f32_16x16x32_bf16 v[0:3], v[178:181], v[218:221], v[0:3]
	s_barrier
	s_cbranch_scc0 .LBB0_953
	s_and_b64 vcc, exec, s[14:15]
	s_cbranch_vccz .LBB0_956
	s_barrier

.LBB0_979:
	ds_read_b128 v[144:147], v141
	ds_read_b128 v[148:151], v141 offset:1024
	ds_read_b128 v[152:155], v141 offset:2048
	ds_read_b128 v[156:159], v141 offset:3072
	ds_read_b128 v[160:163], v142
	ds_read_b128 v[164:167], v142 offset:1024
	ds_read_b128 v[168:171], v142 offset:2048
	ds_read_b128 v[172:175], v142 offset:3072
	ds_read_b128 v[178:181], v143
	ds_read_b128 v[182:185], v143 offset:1024
	ds_read_b128 v[186:189], v143 offset:2048
	ds_read_b128 v[190:193], v143 offset:3072
	ds_read_b128 v[194:197], v143 offset:4096
	ds_read_b128 v[206:209], v143 offset:5120
	ds_read_b128 v[210:213], v143 offset:6144
	ds_read_b128 v[214:217], v143 offset:7168
	s_add_u32 s2, s46, s58
	s_addc_u32 s3, s47, 0
	s_add_u32 s38, s2, 0x100
	s_addc_u32 s39, s3, 0
	s_and_b64 s[0:1], s[52:53], exec
	s_cselect_b32 s57, s23, s39
	s_cselect_b32 s56, s85, s38
	s_add_u32 s0, s34, s58
	s_addc_u32 s1, s35, 0
	s_add_u32 s38, s0, 0x100
	s_addc_u32 s39, s1, 0
	s_and_b64 s[0:1], s[52:53], exec
	s_cselect_b32 s59, s86, s39
	s_cselect_b32 s58, s87, s38
	s_add_u32 s62, s2, 0x10080
	s_addc_u32 s63, s3, 0
	s_add_i32 s38, s78, s66
	s_add_i32 m0, s25, 0xc000
	s_add_i32 s39, s25, 0xe000
	s_add_i32 s0, s38, 0x2000
	s_add_u32 s60, s58, 0x10000
	s_addc_u32 s61, s59, 0
	s_add_i32 s91, s79, s66
	s_add_i32 s76, s91, 0x2000
	s_add_i32 s3, 0, 0x18000
	s_add_i32 s2, 0, 0x1c000
	v_cndmask_b32_e64 v136, 0, 1, s[54:55]
	s_add_u32 s54, s56, 0x10000
	s_addc_u32 s55, s57, 0
	s_add_i32 s1, s3, s66
	s_add_i32 s89, s1, 0x2000
	s_add_u32 s52, s58, 0x10080
	s_addc_u32 s53, s59, 0
	s_add_i32 s90, s2, s66
	s_add_i32 s88, s90, 0x2000
	v_cmp_ne_u32_e32 vcc, 1, v136
	v_lshl_add_u64 v[136:137], s[62:63], 0, v[128:129]
	global_load_lds_dwordx4 v[136:137], off
	s_mov_b32 m0, s39
	v_lshl_add_u64 v[136:137], s[62:63], 0, v[132:133]
	global_load_lds_dwordx4 v[136:137], off
	s_waitcnt vmcnt(8) lgkmcnt(0)
	s_setprio 1
	s_barrier
	v_mfma_f32_16x16x32_bf16 v[124:127], v[144:147], v[178:181], v[124:127]
	v_mfma_f32_16x16x32_bf16 v[120:123], v[152:155], v[178:181], v[120:123]
	v_mfma_f32_16x16x32_bf16 v[116:119], v[144:147], v[186:189], v[116:119]
	v_mfma_f32_16x16x32_bf16 v[108:111], v[152:155], v[186:189], v[108:111]
	v_mfma_f32_16x16x32_bf16 v[100:103], v[144:147], v[194:197], v[100:103]
	v_mfma_f32_16x16x32_bf16 v[92:95], v[152:155], v[194:197], v[92:95]
	v_mfma_f32_16x16x32_bf16 v[84:87], v[144:147], v[210:213], v[84:87]
	v_mfma_f32_16x16x32_bf16 v[76:79], v[152:155], v[210:213], v[76:79]
	v_mfma_f32_16x16x32_bf16 v[124:127], v[148:151], v[182:185], v[124:127]
	v_mfma_f32_16x16x32_bf16 v[120:123], v[156:159], v[182:185], v[120:123]
	v_mfma_f32_16x16x32_bf16 v[116:119], v[148:151], v[190:193], v[116:119]
	v_mfma_f32_16x16x32_bf16 v[108:111], v[156:159], v[190:193], v[108:111]
	v_mfma_f32_16x16x32_bf16 v[100:103], v[148:151], v[206:209], v[100:103]
	v_mfma_f32_16x16x32_bf16 v[92:95], v[156:159], v[206:209], v[92:95]
	v_mfma_f32_16x16x32_bf16 v[84:87], v[148:151], v[214:217], v[84:87]
	v_mfma_f32_16x16x32_bf16 v[76:79], v[156:159], v[214:217], v[76:79]
	v_mfma_f32_16x16x32_bf16 v[112:115], v[160:163], v[178:181], v[112:115]
	v_mfma_f32_16x16x32_bf16 v[104:107], v[168:171], v[178:181], v[104:107]
	v_mfma_f32_16x16x32_bf16 v[96:99], v[160:163], v[186:189], v[96:99]
	v_mfma_f32_16x16x32_bf16 v[88:91], v[168:171], v[186:189], v[88:91]
	v_mfma_f32_16x16x32_bf16 v[80:83], v[160:163], v[194:197], v[80:83]
	v_mfma_f32_16x16x32_bf16 v[72:75], v[168:171], v[194:197], v[72:75]
	v_mfma_f32_16x16x32_bf16 v[68:71], v[160:163], v[210:213], v[68:71]
	v_mfma_f32_16x16x32_bf16 v[64:67], v[168:171], v[210:213], v[64:67]
	v_mfma_f32_16x16x32_bf16 v[112:115], v[164:167], v[182:185], v[112:115]
	v_mfma_f32_16x16x32_bf16 v[104:107], v[172:175], v[182:185], v[104:107]
	v_mfma_f32_16x16x32_bf16 v[96:99], v[164:167], v[190:193], v[96:99]
	v_mfma_f32_16x16x32_bf16 v[88:91], v[172:175], v[190:193], v[88:91]
	v_mfma_f32_16x16x32_bf16 v[80:83], v[164:167], v[206:209], v[80:83]
	v_mfma_f32_16x16x32_bf16 v[72:75], v[172:175], v[206:209], v[72:75]
	v_mfma_f32_16x16x32_bf16 v[68:71], v[164:167], v[214:217], v[68:71]
	s_setprio 0
	v_mfma_f32_16x16x32_bf16 v[64:67], v[172:175], v[214:217], v[64:67]
	s_barrier
	ds_read_b128 v[178:181], v143 offset:16384
	ds_read_b128 v[182:185], v143 offset:17408
	ds_read_b128 v[186:189], v143 offset:18432
	ds_read_b128 v[190:193], v143 offset:19456
	ds_read_b128 v[194:197], v143 offset:20480
	ds_read_b128 v[206:209], v143 offset:21504
	ds_read_b128 v[210:213], v143 offset:22528
	ds_read_b128 v[214:217], v143 offset:23552
	s_mov_b32 m0, s38
	v_lshl_add_u64 v[136:137], s[58:59], 0, v[130:131]
	global_load_lds_dwordx4 v[136:137], off
	v_lshl_add_u64 v[198:199], s[58:59], 0, v[134:135]
	s_mov_b32 m0, s0
	v_lshl_add_u64 v[202:203], s[60:61], 0, v[130:131]
	global_load_lds_dwordx4 v[198:199], off
	s_mov_b32 m0, s91
	v_lshl_add_u64 v[218:219], s[56:57], 0, v[132:133]
	global_load_lds_dwordx4 v[202:203], off
	s_mov_b32 m0, s76
	v_lshl_add_u64 v[202:203], s[60:61], 0, v[134:135]
	global_load_lds_dwordx4 v[202:203], off
	s_mov_b32 m0, s25
	v_lshl_add_u64 v[202:203], s[56:57], 0, v[128:129]
	global_load_lds_dwordx4 v[202:203], off
	s_mov_b32 m0, s69
	s_nop 0
	global_load_lds_dwordx4 v[218:219], off
	s_waitcnt vmcnt(8) lgkmcnt(0)
	s_setprio 1
	s_barrier
	v_mfma_f32_16x16x32_bf16 v[60:63], v[144:147], v[178:181], v[60:63]
	v_mfma_f32_16x16x32_bf16 v[56:59], v[152:155], v[178:181], v[56:59]
	v_mfma_f32_16x16x32_bf16 v[52:55], v[144:147], v[186:189], v[52:55]
	v_mfma_f32_16x16x32_bf16 v[44:47], v[152:155], v[186:189], v[44:47]
	v_mfma_f32_16x16x32_bf16 v[36:39], v[144:147], v[194:197], v[36:39]
	v_mfma_f32_16x16x32_bf16 v[28:31], v[152:155], v[194:197], v[28:31]
	v_mfma_f32_16x16x32_bf16 v[20:23], v[144:147], v[210:213], v[20:23]
	v_mfma_f32_16x16x32_bf16 v[12:15], v[152:155], v[210:213], v[12:15]
	v_mfma_f32_16x16x32_bf16 v[60:63], v[148:151], v[182:185], v[60:63]
	v_mfma_f32_16x16x32_bf16 v[56:59], v[156:159], v[182:185], v[56:59]
	v_mfma_f32_16x16x32_bf16 v[52:55], v[148:151], v[190:193], v[52:55]
	v_mfma_f32_16x16x32_bf16 v[44:47], v[156:159], v[190:193], v[44:47]
	v_mfma_f32_16x16x32_bf16 v[36:39], v[148:151], v[206:209], v[36:39]
	v_mfma_f32_16x16x32_bf16 v[28:31], v[156:159], v[206:209], v[28:31]
	v_mfma_f32_16x16x32_bf16 v[20:23], v[148:151], v[214:217], v[20:23]
	v_mfma_f32_16x16x32_bf16 v[12:15], v[156:159], v[214:217], v[12:15]
	v_mfma_f32_16x16x32_bf16 v[48:51], v[160:163], v[178:181], v[48:51]
	v_mfma_f32_16x16x32_bf16 v[40:43], v[168:171], v[178:181], v[40:43]
	v_mfma_f32_16x16x32_bf16 v[32:35], v[160:163], v[186:189], v[32:35]
	v_mfma_f32_16x16x32_bf16 v[24:27], v[168:171], v[186:189], v[24:27]
	v_mfma_f32_16x16x32_bf16 v[16:19], v[160:163], v[194:197], v[16:19]
	v_mfma_f32_16x16x32_bf16 v[8:11], v[168:171], v[194:197], v[8:11]
	v_mfma_f32_16x16x32_bf16 v[4:7], v[160:163], v[210:213], v[4:7]
	v_mfma_f32_16x16x32_bf16 v[0:3], v[168:171], v[210:213], v[0:3]
	v_mfma_f32_16x16x32_bf16 v[48:51], v[164:167], v[182:185], v[48:51]
	v_mfma_f32_16x16x32_bf16 v[40:43], v[172:175], v[182:185], v[40:43]
	v_mfma_f32_16x16x32_bf16 v[32:35], v[164:167], v[190:193], v[32:35]
	v_mfma_f32_16x16x32_bf16 v[24:27], v[172:175], v[190:193], v[24:27]
	v_mfma_f32_16x16x32_bf16 v[16:19], v[164:167], v[206:209], v[16:19]
	v_mfma_f32_16x16x32_bf16 v[8:11], v[172:175], v[206:209], v[8:11]
	v_mfma_f32_16x16x32_bf16 v[4:7], v[164:167], v[214:217], v[4:7]
	s_setprio 0
	v_mfma_f32_16x16x32_bf16 v[0:3], v[172:175], v[214:217], v[0:3]
	s_barrier
	ds_read_b128 v[178:181], v143 offset:32768
	ds_read_b128 v[182:185], v143 offset:33792
	ds_read_b128 v[186:189], v143 offset:34816
	ds_read_b128 v[190:193], v143 offset:35840
	ds_read_b128 v[194:197], v143 offset:36864
	ds_read_b128 v[206:209], v143 offset:37888
	ds_read_b128 v[210:213], v143 offset:38912
	ds_read_b128 v[214:217], v143 offset:39936
	v_add_u32_e32 v156, s3, v140
	v_add_u32_e32 v172, s2, v140
	ds_read_b128 v[144:147], v156
	ds_read_b128 v[148:151], v156 offset:1024
	ds_read_b128 v[152:155], v156 offset:2048
	ds_read_b128 v[156:159], v156 offset:3072
	ds_read_b128 v[160:163], v172
	ds_read_b128 v[164:167], v172 offset:1024
	ds_read_b128 v[168:171], v172 offset:2048
	ds_read_b128 v[172:175], v172 offset:3072
	s_mov_b32 m0, s70
	v_lshl_add_u64 v[220:221], s[54:55], 0, v[128:129]
	global_load_lds_dwordx4 v[220:221], off
	s_mov_b32 m0, s71
	v_lshl_add_u64 v[220:221], s[54:55], 0, v[132:133]
	global_load_lds_dwordx4 v[220:221], off
	s_waitcnt vmcnt(8) lgkmcnt(0)
	s_setprio 1
	s_barrier
	v_mfma_f32_16x16x32_bf16 v[124:127], v[144:147], v[178:181], v[124:127]
	v_mfma_f32_16x16x32_bf16 v[120:123], v[152:155], v[178:181], v[120:123]
	v_mfma_f32_16x16x32_bf16 v[116:119], v[144:147], v[186:189], v[116:119]
	v_mfma_f32_16x16x32_bf16 v[108:111], v[152:155], v[186:189], v[108:111]
	v_mfma_f32_16x16x32_bf16 v[100:103], v[144:147], v[194:197], v[100:103]
	v_mfma_f32_16x16x32_bf16 v[92:95], v[152:155], v[194:197], v[92:95]
	v_mfma_f32_16x16x32_bf16 v[84:87], v[144:147], v[210:213], v[84:87]
	v_mfma_f32_16x16x32_bf16 v[76:79], v[152:155], v[210:213], v[76:79]
	v_mfma_f32_16x16x32_bf16 v[124:127], v[148:151], v[182:185], v[124:127]
	v_mfma_f32_16x16x32_bf16 v[120:123], v[156:159], v[182:185], v[120:123]
	v_mfma_f32_16x16x32_bf16 v[116:119], v[148:151], v[190:193], v[116:119]
	v_mfma_f32_16x16x32_bf16 v[108:111], v[156:159], v[190:193], v[108:111]
	v_mfma_f32_16x16x32_bf16 v[100:103], v[148:151], v[206:209], v[100:103]
	v_mfma_f32_16x16x32_bf16 v[92:95], v[156:159], v[206:209], v[92:95]
	v_mfma_f32_16x16x32_bf16 v[84:87], v[148:151], v[214:217], v[84:87]
	v_mfma_f32_16x16x32_bf16 v[76:79], v[156:159], v[214:217], v[76:79]
	v_mfma_f32_16x16x32_bf16 v[112:115], v[160:163], v[178:181], v[112:115]
	v_mfma_f32_16x16x32_bf16 v[104:107], v[168:171], v[178:181], v[104:107]
	v_mfma_f32_16x16x32_bf16 v[96:99], v[160:163], v[186:189], v[96:99]
	v_mfma_f32_16x16x32_bf16 v[88:91], v[168:171], v[186:189], v[88:91]
	v_mfma_f32_16x16x32_bf16 v[80:83], v[160:163], v[194:197], v[80:83]
	v_mfma_f32_16x16x32_bf16 v[72:75], v[168:171], v[194:197], v[72:75]
	v_mfma_f32_16x16x32_bf16 v[68:71], v[160:163], v[210:213], v[68:71]
	v_mfma_f32_16x16x32_bf16 v[64:67], v[168:171], v[210:213], v[64:67]
	v_mfma_f32_16x16x32_bf16 v[112:115], v[164:167], v[182:185], v[112:115]
	v_mfma_f32_16x16x32_bf16 v[104:107], v[172:175], v[182:185], v[104:107]
	v_mfma_f32_16x16x32_bf16 v[96:99], v[164:167], v[190:193], v[96:99]
	v_mfma_f32_16x16x32_bf16 v[88:91], v[172:175], v[190:193], v[88:91]
	v_mfma_f32_16x16x32_bf16 v[80:83], v[164:167], v[206:209], v[80:83]
	v_mfma_f32_16x16x32_bf16 v[72:75], v[172:175], v[206:209], v[72:75]
	v_mfma_f32_16x16x32_bf16 v[68:71], v[164:167], v[214:217], v[68:71]
	s_setprio 0
	v_mfma_f32_16x16x32_bf16 v[64:67], v[172:175], v[214:217], v[64:67]
	s_barrier
	ds_read_b128 v[178:181], v143 offset:49152
	ds_read_b128 v[182:185], v143 offset:50176
	ds_read_b128 v[186:189], v143 offset:51200
	ds_read_b128 v[190:193], v143 offset:52224
	ds_read_b128 v[194:197], v143 offset:53248
	ds_read_b128 v[206:209], v143 offset:54272
	ds_read_b128 v[210:213], v143 offset:55296
	ds_read_b128 v[214:217], v143 offset:56320
	s_mov_b32 m0, s1
	v_lshl_add_u64 v[136:137], v[136:137], 0, s[10:11]
	global_load_lds_dwordx4 v[136:137], off
	s_mov_b32 m0, s89
	v_lshl_add_u64 v[136:137], v[198:199], 0, s[10:11]
	global_load_lds_dwordx4 v[136:137], off
	s_mov_b32 m0, s90
	v_lshl_add_u64 v[136:137], s[52:53], 0, v[130:131]
	global_load_lds_dwordx4 v[136:137], off
	s_mov_b32 m0, s88
	v_lshl_add_u64 v[136:137], s[52:53], 0, v[134:135]
	global_load_lds_dwordx4 v[136:137], off
	s_mov_b32 m0, s75
	v_lshl_add_u64 v[136:137], v[202:203], 0, s[10:11]
	global_load_lds_dwordx4 v[136:137], off
	s_mov_b32 m0, s77
	v_lshl_add_u64 v[136:137], v[218:219], 0, s[10:11]
	global_load_lds_dwordx4 v[136:137], off
	s_waitcnt vmcnt(8) lgkmcnt(0)
	s_setprio 1
	s_barrier
	v_mfma_f32_16x16x32_bf16 v[60:63], v[144:147], v[178:181], v[60:63]
	v_mfma_f32_16x16x32_bf16 v[56:59], v[152:155], v[178:181], v[56:59]
	v_mfma_f32_16x16x32_bf16 v[52:55], v[144:147], v[186:189], v[52:55]
	v_mfma_f32_16x16x32_bf16 v[44:47], v[152:155], v[186:189], v[44:47]
	v_mfma_f32_16x16x32_bf16 v[36:39], v[144:147], v[194:197], v[36:39]
	v_mfma_f32_16x16x32_bf16 v[28:31], v[152:155], v[194:197], v[28:31]
	v_mfma_f32_16x16x32_bf16 v[20:23], v[144:147], v[210:213], v[20:23]
	v_mfma_f32_16x16x32_bf16 v[12:15], v[152:155], v[210:213], v[12:15]
	v_mfma_f32_16x16x32_bf16 v[60:63], v[148:151], v[182:185], v[60:63]
	v_mfma_f32_16x16x32_bf16 v[56:59], v[156:159], v[182:185], v[56:59]
	v_mfma_f32_16x16x32_bf16 v[52:55], v[148:151], v[190:193], v[52:55]
	v_mfma_f32_16x16x32_bf16 v[44:47], v[156:159], v[190:193], v[44:47]
	v_mfma_f32_16x16x32_bf16 v[36:39], v[148:151], v[206:209], v[36:39]
	v_mfma_f32_16x16x32_bf16 v[28:31], v[156:159], v[206:209], v[28:31]
	v_mfma_f32_16x16x32_bf16 v[20:23], v[148:151], v[214:217], v[20:23]
	v_mfma_f32_16x16x32_bf16 v[12:15], v[156:159], v[214:217], v[12:15]
	v_mfma_f32_16x16x32_bf16 v[48:51], v[160:163], v[178:181], v[48:51]
	v_mfma_f32_16x16x32_bf16 v[40:43], v[168:171], v[178:181], v[40:43]
	v_mfma_f32_16x16x32_bf16 v[32:35], v[160:163], v[186:189], v[32:35]
	v_mfma_f32_16x16x32_bf16 v[24:27], v[168:171], v[186:189], v[24:27]
	v_mfma_f32_16x16x32_bf16 v[16:19], v[160:163], v[194:197], v[16:19]
	v_mfma_f32_16x16x32_bf16 v[8:11], v[168:171], v[194:197], v[8:11]
	v_mfma_f32_16x16x32_bf16 v[4:7], v[160:163], v[210:213], v[4:7]
	v_mfma_f32_16x16x32_bf16 v[0:3], v[168:171], v[210:213], v[0:3]
	v_mfma_f32_16x16x32_bf16 v[48:51], v[164:167], v[182:185], v[48:51]
	v_mfma_f32_16x16x32_bf16 v[40:43], v[172:175], v[182:185], v[40:43]
	v_mfma_f32_16x16x32_bf16 v[32:35], v[164:167], v[190:193], v[32:35]
	v_mfma_f32_16x16x32_bf16 v[24:27], v[172:175], v[190:193], v[24:27]
	v_mfma_f32_16x16x32_bf16 v[16:19], v[164:167], v[206:209], v[16:19]
	v_mfma_f32_16x16x32_bf16 v[8:11], v[172:175], v[206:209], v[8:11]
	v_mfma_f32_16x16x32_bf16 v[4:7], v[164:167], v[214:217], v[4:7]
	s_setprio 0
	v_mfma_f32_16x16x32_bf16 v[0:3], v[172:175], v[214:217], v[0:3]
	s_barrier
	s_movk_i32 s58, 0x100
	s_mov_b64 s[54:55], 0
	s_mov_b64 s[52:53], -1
	s_cbranch_vccz .LBB0_979
	s_and_b64 vcc, exec, s[12:13]
	s_cbranch_vccz .LBB0_982
	s_barrier

.LBB0_1037:
	ds_read_b128 v[128:131], v157
	ds_read_b128 v[132:135], v157 offset:1024
	ds_read_b128 v[136:139], v157 offset:2048
	ds_read_b128 v[140:143], v157 offset:3072
	ds_read_b128 v[160:163], v158
	ds_read_b128 v[164:167], v158 offset:1024
	ds_read_b128 v[168:171], v158 offset:2048
	ds_read_b128 v[172:175], v158 offset:3072
	ds_read_b128 v[178:181], v159
	ds_read_b128 v[182:185], v159 offset:1024
	ds_read_b128 v[186:189], v159 offset:2048
	ds_read_b128 v[190:193], v159 offset:3072
	ds_read_b128 v[194:197], v159 offset:4096
	ds_read_b128 v[206:209], v159 offset:5120
	ds_read_b128 v[210:213], v159 offset:6144
	ds_read_b128 v[214:217], v159 offset:7168
	s_add_u32 s0, s58, 0xfff00080
	s_addc_u32 s1, s59, -1
	s_cmp_eq_u32 s87, 60
	s_cselect_b32 s63, s12, s1
	s_cselect_b32 s62, s29, s0
	s_cselect_b32 s61, s57, s86
	s_cselect_b32 s60, s64, s65
	s_add_i32 m0, s68, 0xc000
	v_lshl_add_u64 v[152:153], s[58:59], 0, v[148:149]
	global_load_lds_dwordx4 v[152:153], off
	s_add_i32 m0, s68, 0xe000
	v_lshl_add_u64 v[152:153], s[58:59], 0, v[150:151]
	global_load_lds_dwordx4 v[152:153], off
	s_waitcnt vmcnt(8) lgkmcnt(0)
	s_setprio 1
	s_barrier
	v_mfma_f32_16x16x32_bf16 v[124:127], v[128:131], v[178:181], v[124:127]
	v_mfma_f32_16x16x32_bf16 v[120:123], v[136:139], v[178:181], v[120:123]
	v_mfma_f32_16x16x32_bf16 v[112:115], v[128:131], v[186:189], v[112:115]
	v_mfma_f32_16x16x32_bf16 v[108:111], v[136:139], v[186:189], v[108:111]
	v_mfma_f32_16x16x32_bf16 v[96:99], v[128:131], v[194:197], v[96:99]
	v_mfma_f32_16x16x32_bf16 v[92:95], v[136:139], v[194:197], v[92:95]
	v_mfma_f32_16x16x32_bf16 v[80:83], v[128:131], v[210:213], v[80:83]
	v_mfma_f32_16x16x32_bf16 v[76:79], v[136:139], v[210:213], v[76:79]
	v_mfma_f32_16x16x32_bf16 v[124:127], v[132:135], v[182:185], v[124:127]
	v_mfma_f32_16x16x32_bf16 v[120:123], v[140:143], v[182:185], v[120:123]
	v_mfma_f32_16x16x32_bf16 v[112:115], v[132:135], v[190:193], v[112:115]
	v_mfma_f32_16x16x32_bf16 v[108:111], v[140:143], v[190:193], v[108:111]
	v_mfma_f32_16x16x32_bf16 v[96:99], v[132:135], v[206:209], v[96:99]
	v_mfma_f32_16x16x32_bf16 v[92:95], v[140:143], v[206:209], v[92:95]
	v_mfma_f32_16x16x32_bf16 v[80:83], v[132:135], v[214:217], v[80:83]
	v_mfma_f32_16x16x32_bf16 v[76:79], v[140:143], v[214:217], v[76:79]
	v_mfma_f32_16x16x32_bf16 v[116:119], v[160:163], v[178:181], v[116:119]
	v_mfma_f32_16x16x32_bf16 v[104:107], v[168:171], v[178:181], v[104:107]
	v_mfma_f32_16x16x32_bf16 v[100:103], v[160:163], v[186:189], v[100:103]
	v_mfma_f32_16x16x32_bf16 v[88:91], v[168:171], v[186:189], v[88:91]
	v_mfma_f32_16x16x32_bf16 v[84:87], v[160:163], v[194:197], v[84:87]
	v_mfma_f32_16x16x32_bf16 v[72:75], v[168:171], v[194:197], v[72:75]
	v_mfma_f32_16x16x32_bf16 v[68:71], v[160:163], v[210:213], v[68:71]
	v_mfma_f32_16x16x32_bf16 v[64:67], v[168:171], v[210:213], v[64:67]
	v_mfma_f32_16x16x32_bf16 v[116:119], v[164:167], v[182:185], v[116:119]
	v_mfma_f32_16x16x32_bf16 v[104:107], v[172:175], v[182:185], v[104:107]
	v_mfma_f32_16x16x32_bf16 v[100:103], v[164:167], v[190:193], v[100:103]
	v_mfma_f32_16x16x32_bf16 v[88:91], v[172:175], v[190:193], v[88:91]
	v_mfma_f32_16x16x32_bf16 v[84:87], v[164:167], v[206:209], v[84:87]
	v_mfma_f32_16x16x32_bf16 v[72:75], v[172:175], v[206:209], v[72:75]
	v_mfma_f32_16x16x32_bf16 v[68:71], v[164:167], v[214:217], v[68:71]
	s_setprio 0
	v_mfma_f32_16x16x32_bf16 v[64:67], v[172:175], v[214:217], v[64:67]
	s_barrier
	ds_read_b128 v[178:181], v159 offset:16384
	ds_read_b128 v[182:185], v159 offset:17408
	ds_read_b128 v[186:189], v159 offset:18432
	ds_read_b128 v[190:193], v159 offset:19456
	ds_read_b128 v[194:197], v159 offset:20480
	ds_read_b128 v[206:209], v159 offset:21504
	ds_read_b128 v[210:213], v159 offset:22528
	ds_read_b128 v[214:217], v159 offset:23552
	s_add_i32 s0, s81, s67
	s_mov_b32 m0, s0
	v_lshl_add_u64 v[152:153], s[60:61], 0, v[146:147]
	global_load_lds_dwordx4 v[152:153], off
	s_add_i32 m0, s0, 0x2000
	s_add_u32 s0, s60, 0x100000
	v_lshl_add_u64 v[198:199], s[60:61], 0, v[144:145]
	s_addc_u32 s1, s61, 0
	s_add_i32 s2, s82, s67
	global_load_lds_dwordx4 v[198:199], off
	v_lshl_add_u64 v[202:203], s[0:1], 0, v[146:147]
	s_mov_b32 m0, s2
	v_lshl_add_u64 v[218:219], s[62:63], 0, v[144:145]
	global_load_lds_dwordx4 v[202:203], off
	s_add_i32 m0, s2, 0x2000
	v_lshl_add_u64 v[202:203], s[0:1], 0, v[144:145]
	global_load_lds_dwordx4 v[202:203], off
	s_mov_b32 m0, s68
	v_lshl_add_u64 v[202:203], s[62:63], 0, v[146:147]
	global_load_lds_dwordx4 v[202:203], off
	s_mov_b32 m0, s69
	s_nop 0
	global_load_lds_dwordx4 v[218:219], off
	s_waitcnt vmcnt(8) lgkmcnt(0)
	s_setprio 1
	s_barrier
	v_mfma_f32_16x16x32_bf16 v[60:63], v[128:131], v[178:181], v[60:63]
	v_mfma_f32_16x16x32_bf16 v[56:59], v[136:139], v[178:181], v[56:59]
	v_mfma_f32_16x16x32_bf16 v[48:51], v[128:131], v[186:189], v[48:51]
	v_mfma_f32_16x16x32_bf16 v[44:47], v[136:139], v[186:189], v[44:47]
	v_mfma_f32_16x16x32_bf16 v[32:35], v[128:131], v[194:197], v[32:35]
	v_mfma_f32_16x16x32_bf16 v[28:31], v[136:139], v[194:197], v[28:31]
	v_mfma_f32_16x16x32_bf16 v[16:19], v[128:131], v[210:213], v[16:19]
	v_mfma_f32_16x16x32_bf16 v[12:15], v[136:139], v[210:213], v[12:15]
	v_mfma_f32_16x16x32_bf16 v[60:63], v[132:135], v[182:185], v[60:63]
	v_mfma_f32_16x16x32_bf16 v[56:59], v[140:143], v[182:185], v[56:59]
	v_mfma_f32_16x16x32_bf16 v[48:51], v[132:135], v[190:193], v[48:51]
	v_mfma_f32_16x16x32_bf16 v[44:47], v[140:143], v[190:193], v[44:47]
	v_mfma_f32_16x16x32_bf16 v[32:35], v[132:135], v[206:209], v[32:35]
	v_mfma_f32_16x16x32_bf16 v[28:31], v[140:143], v[206:209], v[28:31]
	v_mfma_f32_16x16x32_bf16 v[16:19], v[132:135], v[214:217], v[16:19]
	v_mfma_f32_16x16x32_bf16 v[12:15], v[140:143], v[214:217], v[12:15]
	v_mfma_f32_16x16x32_bf16 v[52:55], v[160:163], v[178:181], v[52:55]
	v_mfma_f32_16x16x32_bf16 v[40:43], v[168:171], v[178:181], v[40:43]
	v_mfma_f32_16x16x32_bf16 v[36:39], v[160:163], v[186:189], v[36:39]
	v_mfma_f32_16x16x32_bf16 v[24:27], v[168:171], v[186:189], v[24:27]
	v_mfma_f32_16x16x32_bf16 v[20:23], v[160:163], v[194:197], v[20:23]
	v_mfma_f32_16x16x32_bf16 v[8:11], v[168:171], v[194:197], v[8:11]
	v_mfma_f32_16x16x32_bf16 v[4:7], v[160:163], v[210:213], v[4:7]
	v_mfma_f32_16x16x32_bf16 v[0:3], v[168:171], v[210:213], v[0:3]
	v_mfma_f32_16x16x32_bf16 v[52:55], v[164:167], v[182:185], v[52:55]
	v_mfma_f32_16x16x32_bf16 v[40:43], v[172:175], v[182:185], v[40:43]
	v_mfma_f32_16x16x32_bf16 v[36:39], v[164:167], v[190:193], v[36:39]
	v_mfma_f32_16x16x32_bf16 v[24:27], v[172:175], v[190:193], v[24:27]
	v_mfma_f32_16x16x32_bf16 v[20:23], v[164:167], v[206:209], v[20:23]
	v_mfma_f32_16x16x32_bf16 v[8:11], v[172:175], v[206:209], v[8:11]
	v_mfma_f32_16x16x32_bf16 v[4:7], v[164:167], v[214:217], v[4:7]
	s_setprio 0
	v_mfma_f32_16x16x32_bf16 v[0:3], v[172:175], v[214:217], v[0:3]
	s_barrier
	ds_read_b128 v[178:181], v159 offset:32768
	ds_read_b128 v[182:185], v159 offset:33792
	ds_read_b128 v[186:189], v159 offset:34816
	ds_read_b128 v[190:193], v159 offset:35840
	ds_read_b128 v[194:197], v159 offset:36864
	ds_read_b128 v[206:209], v159 offset:37888
	ds_read_b128 v[210:213], v159 offset:38912
	ds_read_b128 v[214:217], v159 offset:39936
	s_add_i32 s2, 0, 0x18000
	s_add_i32 s3, 0, 0x1c000
	v_add_u32_e32 v140, s2, v156
	v_add_u32_e32 v172, s3, v156
	ds_read_b128 v[128:131], v140
	ds_read_b128 v[132:135], v140 offset:1024
	ds_read_b128 v[136:139], v140 offset:2048
	ds_read_b128 v[140:143], v140 offset:3072
	ds_read_b128 v[160:163], v172
	ds_read_b128 v[164:167], v172 offset:1024
	ds_read_b128 v[168:171], v172 offset:2048
	ds_read_b128 v[172:175], v172 offset:3072
	s_add_u32 s0, s62, 0x100000
	s_addc_u32 s1, s63, 0
	s_mov_b32 m0, s70
	v_lshl_add_u64 v[220:221], s[0:1], 0, v[146:147]
	global_load_lds_dwordx4 v[220:221], off
	s_mov_b32 m0, s71
	v_lshl_add_u64 v[220:221], s[0:1], 0, v[144:145]
	global_load_lds_dwordx4 v[220:221], off
	s_waitcnt vmcnt(8) lgkmcnt(0)
	s_setprio 1
	s_barrier
	v_mfma_f32_16x16x32_bf16 v[124:127], v[128:131], v[178:181], v[124:127]
	v_mfma_f32_16x16x32_bf16 v[120:123], v[136:139], v[178:181], v[120:123]
	v_mfma_f32_16x16x32_bf16 v[112:115], v[128:131], v[186:189], v[112:115]
	v_mfma_f32_16x16x32_bf16 v[108:111], v[136:139], v[186:189], v[108:111]
	v_mfma_f32_16x16x32_bf16 v[96:99], v[128:131], v[194:197], v[96:99]
	v_mfma_f32_16x16x32_bf16 v[92:95], v[136:139], v[194:197], v[92:95]
	v_mfma_f32_16x16x32_bf16 v[80:83], v[128:131], v[210:213], v[80:83]
	v_mfma_f32_16x16x32_bf16 v[76:79], v[136:139], v[210:213], v[76:79]
	v_mfma_f32_16x16x32_bf16 v[124:127], v[132:135], v[182:185], v[124:127]
	v_mfma_f32_16x16x32_bf16 v[120:123], v[140:143], v[182:185], v[120:123]
	v_mfma_f32_16x16x32_bf16 v[112:115], v[132:135], v[190:193], v[112:115]
	v_mfma_f32_16x16x32_bf16 v[108:111], v[140:143], v[190:193], v[108:111]
	v_mfma_f32_16x16x32_bf16 v[96:99], v[132:135], v[206:209], v[96:99]
	v_mfma_f32_16x16x32_bf16 v[92:95], v[140:143], v[206:209], v[92:95]
	v_mfma_f32_16x16x32_bf16 v[80:83], v[132:135], v[214:217], v[80:83]
	v_mfma_f32_16x16x32_bf16 v[76:79], v[140:143], v[214:217], v[76:79]
	v_mfma_f32_16x16x32_bf16 v[116:119], v[160:163], v[178:181], v[116:119]
	v_mfma_f32_16x16x32_bf16 v[104:107], v[168:171], v[178:181], v[104:107]
	v_mfma_f32_16x16x32_bf16 v[100:103], v[160:163], v[186:189], v[100:103]
	v_mfma_f32_16x16x32_bf16 v[88:91], v[168:171], v[186:189], v[88:91]
	v_mfma_f32_16x16x32_bf16 v[84:87], v[160:163], v[194:197], v[84:87]
	v_mfma_f32_16x16x32_bf16 v[72:75], v[168:171], v[194:197], v[72:75]
	v_mfma_f32_16x16x32_bf16 v[68:71], v[160:163], v[210:213], v[68:71]
	v_mfma_f32_16x16x32_bf16 v[64:67], v[168:171], v[210:213], v[64:67]
	v_mfma_f32_16x16x32_bf16 v[116:119], v[164:167], v[182:185], v[116:119]
	v_mfma_f32_16x16x32_bf16 v[104:107], v[172:175], v[182:185], v[104:107]
	v_mfma_f32_16x16x32_bf16 v[100:103], v[164:167], v[190:193], v[100:103]
	v_mfma_f32_16x16x32_bf16 v[88:91], v[172:175], v[190:193], v[88:91]
	v_mfma_f32_16x16x32_bf16 v[84:87], v[164:167], v[206:209], v[84:87]
	v_mfma_f32_16x16x32_bf16 v[72:75], v[172:175], v[206:209], v[72:75]
	v_mfma_f32_16x16x32_bf16 v[68:71], v[164:167], v[214:217], v[68:71]
	s_setprio 0
	v_mfma_f32_16x16x32_bf16 v[64:67], v[172:175], v[214:217], v[64:67]
	s_barrier
	ds_read_b128 v[178:181], v159 offset:49152
	ds_read_b128 v[182:185], v159 offset:50176
	ds_read_b128 v[186:189], v159 offset:51200
	ds_read_b128 v[190:193], v159 offset:52224
	ds_read_b128 v[194:197], v159 offset:53248
	ds_read_b128 v[206:209], v159 offset:54272
	ds_read_b128 v[210:213], v159 offset:55296
	ds_read_b128 v[214:217], v159 offset:56320
	s_add_i32 s0, s2, s67
	s_mov_b32 m0, s0
	v_lshl_add_u64 v[152:153], v[152:153], 0, s[10:11]
	global_load_lds_dwordx4 v[152:153], off
	s_add_i32 m0, s0, 0x2000
	s_add_u32 s0, s60, 0x100080
	v_lshl_add_u64 v[152:153], v[198:199], 0, s[10:11]
	s_addc_u32 s1, s61, 0
	s_add_i32 s2, s3, s67
	global_load_lds_dwordx4 v[152:153], off
	s_mov_b32 m0, s2
	v_lshl_add_u64 v[152:153], s[0:1], 0, v[146:147]
	global_load_lds_dwordx4 v[152:153], off
	s_add_i32 m0, s2, 0x2000
	v_lshl_add_u64 v[152:153], s[0:1], 0, v[144:145]
	global_load_lds_dwordx4 v[152:153], off
	s_mov_b32 m0, s79
	v_lshl_add_u64 v[152:153], v[202:203], 0, s[10:11]
	global_load_lds_dwordx4 v[152:153], off
	s_mov_b32 m0, s80
	v_lshl_add_u64 v[152:153], v[218:219], 0, s[10:11]
	global_load_lds_dwordx4 v[152:153], off
	s_waitcnt vmcnt(8) lgkmcnt(0)
	s_setprio 1
	s_barrier
	v_mfma_f32_16x16x32_bf16 v[60:63], v[128:131], v[178:181], v[60:63]
	v_mfma_f32_16x16x32_bf16 v[56:59], v[136:139], v[178:181], v[56:59]
	v_mfma_f32_16x16x32_bf16 v[48:51], v[128:131], v[186:189], v[48:51]
	v_mfma_f32_16x16x32_bf16 v[44:47], v[136:139], v[186:189], v[44:47]
	v_mfma_f32_16x16x32_bf16 v[32:35], v[128:131], v[194:197], v[32:35]
	v_mfma_f32_16x16x32_bf16 v[28:31], v[136:139], v[194:197], v[28:31]
	v_mfma_f32_16x16x32_bf16 v[16:19], v[128:131], v[210:213], v[16:19]
	v_mfma_f32_16x16x32_bf16 v[12:15], v[136:139], v[210:213], v[12:15]
	v_mfma_f32_16x16x32_bf16 v[60:63], v[132:135], v[182:185], v[60:63]
	v_mfma_f32_16x16x32_bf16 v[56:59], v[140:143], v[182:185], v[56:59]
	v_mfma_f32_16x16x32_bf16 v[48:51], v[132:135], v[190:193], v[48:51]
	v_mfma_f32_16x16x32_bf16 v[44:47], v[140:143], v[190:193], v[44:47]
	v_mfma_f32_16x16x32_bf16 v[32:35], v[132:135], v[206:209], v[32:35]
	v_mfma_f32_16x16x32_bf16 v[28:31], v[140:143], v[206:209], v[28:31]
	v_mfma_f32_16x16x32_bf16 v[16:19], v[132:135], v[214:217], v[16:19]
	v_mfma_f32_16x16x32_bf16 v[12:15], v[140:143], v[214:217], v[12:15]
	v_mfma_f32_16x16x32_bf16 v[52:55], v[160:163], v[178:181], v[52:55]
	v_mfma_f32_16x16x32_bf16 v[40:43], v[168:171], v[178:181], v[40:43]
	v_mfma_f32_16x16x32_bf16 v[36:39], v[160:163], v[186:189], v[36:39]
	v_mfma_f32_16x16x32_bf16 v[24:27], v[168:171], v[186:189], v[24:27]
	v_mfma_f32_16x16x32_bf16 v[20:23], v[160:163], v[194:197], v[20:23]
	v_mfma_f32_16x16x32_bf16 v[8:11], v[168:171], v[194:197], v[8:11]
	v_mfma_f32_16x16x32_bf16 v[4:7], v[160:163], v[210:213], v[4:7]
	v_mfma_f32_16x16x32_bf16 v[0:3], v[168:171], v[210:213], v[0:3]
	v_mfma_f32_16x16x32_bf16 v[52:55], v[164:167], v[182:185], v[52:55]
	s_add_i32 s87, s87, 2
	v_mfma_f32_16x16x32_bf16 v[40:43], v[172:175], v[182:185], v[40:43]
	s_add_u32 s58, s58, 0x100
	v_mfma_f32_16x16x32_bf16 v[36:39], v[164:167], v[190:193], v[36:39]
	s_addc_u32 s59, s59, 0
	v_mfma_f32_16x16x32_bf16 v[24:27], v[172:175], v[190:193], v[24:27]
	s_add_u32 s65, s65, 0x100
	v_mfma_f32_16x16x32_bf16 v[20:23], v[164:167], v[206:209], v[20:23]
	s_addc_u32 s86, s86, 0
	v_mfma_f32_16x16x32_bf16 v[8:11], v[172:175], v[206:209], v[8:11]
	s_cmp_gt_u32 s87, 61
	v_mfma_f32_16x16x32_bf16 v[4:7], v[164:167], v[214:217], v[4:7]
	s_setprio 0
	v_mfma_f32_16x16x32_bf16 v[0:3], v[172:175], v[214:217], v[0:3]
	s_barrier
	s_cbranch_scc0 .LBB0_1037
	s_and_b64 vcc, exec, s[14:15]
	s_cbranch_vccz .LBB0_1040
	s_barrier

.LBB0_1107:
	ds_read_b128 v[128:131], v203
	ds_read_b128 v[132:135], v203 offset:1024
	ds_read_b128 v[136:139], v203 offset:2048
	ds_read_b128 v[140:143], v203 offset:3072
	ds_read_b128 v[144:147], v204
	ds_read_b128 v[148:151], v204 offset:1024
	ds_read_b128 v[152:155], v204 offset:2048
	ds_read_b128 v[156:159], v204 offset:3072
	ds_read_b128 v[160:163], v205
	ds_read_b128 v[164:167], v205 offset:1024
	ds_read_b128 v[168:171], v205 offset:2048
	ds_read_b128 v[172:175], v205 offset:3072
	ds_read_b128 v[190:193], v205 offset:4096
	ds_read_b128 v[194:197], v205 offset:5120
	ds_read_b128 v[206:209], v205 offset:6144
	ds_read_b128 v[210:213], v205 offset:7168
	s_add_u32 s0, s4, 0xfff80080
	s_addc_u32 s1, s5, -1
	s_cmp_eq_u32 s96, 28
	s_cselect_b32 s9, s13, s1
	s_cselect_b32 s8, s15, s0
	s_cselect_b32 s7, s37, s11
	s_cselect_b32 s6, s63, s10
	s_add_i32 m0, s77, 0xc000
	v_lshl_add_u64 v[198:199], s[4:5], 0, v[186:187]
	global_load_lds_dwordx4 v[198:199], off
	s_add_i32 m0, s77, 0xe000
	v_lshl_add_u64 v[198:199], s[4:5], 0, v[188:189]
	global_load_lds_dwordx4 v[198:199], off
	s_waitcnt vmcnt(8) lgkmcnt(0)
	s_setprio 1
	s_barrier
	v_mfma_f32_16x16x32_bf16 v[124:127], v[128:131], v[160:163], v[124:127]
	v_mfma_f32_16x16x32_bf16 v[56:59], v[136:139], v[160:163], v[56:59]
	v_mfma_f32_16x16x32_bf16 v[116:119], v[128:131], v[168:171], v[116:119]
	v_mfma_f32_16x16x32_bf16 v[52:55], v[136:139], v[168:171], v[52:55]
	v_mfma_f32_16x16x32_bf16 v[108:111], v[128:131], v[190:193], v[108:111]
	v_mfma_f32_16x16x32_bf16 v[44:47], v[136:139], v[190:193], v[44:47]
	v_mfma_f32_16x16x32_bf16 v[104:107], v[128:131], v[206:209], v[104:107]
	v_mfma_f32_16x16x32_bf16 v[32:35], v[136:139], v[206:209], v[32:35]
	v_mfma_f32_16x16x32_bf16 v[124:127], v[132:135], v[164:167], v[124:127]
	v_mfma_f32_16x16x32_bf16 v[56:59], v[140:143], v[164:167], v[56:59]
	v_mfma_f32_16x16x32_bf16 v[116:119], v[132:135], v[172:175], v[116:119]
	v_mfma_f32_16x16x32_bf16 v[52:55], v[140:143], v[172:175], v[52:55]
	v_mfma_f32_16x16x32_bf16 v[108:111], v[132:135], v[194:197], v[108:111]
	v_mfma_f32_16x16x32_bf16 v[44:47], v[140:143], v[194:197], v[44:47]
	v_mfma_f32_16x16x32_bf16 v[104:107], v[132:135], v[210:213], v[104:107]
	v_mfma_f32_16x16x32_bf16 v[32:35], v[140:143], v[210:213], v[32:35]
	v_mfma_f32_16x16x32_bf16 v[120:123], v[144:147], v[160:163], v[120:123]
	v_mfma_f32_16x16x32_bf16 v[60:63], v[152:155], v[160:163], v[60:63]
	v_mfma_f32_16x16x32_bf16 v[112:115], v[144:147], v[168:171], v[112:115]
	v_mfma_f32_16x16x32_bf16 v[48:51], v[152:155], v[168:171], v[48:51]
	v_mfma_f32_16x16x32_bf16 v[100:103], v[144:147], v[190:193], v[100:103]
	v_mfma_f32_16x16x32_bf16 v[40:43], v[152:155], v[190:193], v[40:43]
	v_mfma_f32_16x16x32_bf16 v[96:99], v[144:147], v[206:209], v[96:99]
	v_mfma_f32_16x16x32_bf16 v[36:39], v[152:155], v[206:209], v[36:39]
	v_mfma_f32_16x16x32_bf16 v[120:123], v[148:151], v[164:167], v[120:123]
	v_mfma_f32_16x16x32_bf16 v[60:63], v[156:159], v[164:167], v[60:63]
	v_mfma_f32_16x16x32_bf16 v[112:115], v[148:151], v[172:175], v[112:115]
	v_mfma_f32_16x16x32_bf16 v[48:51], v[156:159], v[172:175], v[48:51]
	v_mfma_f32_16x16x32_bf16 v[100:103], v[148:151], v[194:197], v[100:103]
	v_mfma_f32_16x16x32_bf16 v[40:43], v[156:159], v[194:197], v[40:43]
	v_mfma_f32_16x16x32_bf16 v[96:99], v[148:151], v[210:213], v[96:99]
	s_setprio 0
	v_mfma_f32_16x16x32_bf16 v[36:39], v[156:159], v[210:213], v[36:39]
	s_barrier
	ds_read_b128 v[160:163], v205 offset:16384
	ds_read_b128 v[164:167], v205 offset:17408
	ds_read_b128 v[168:171], v205 offset:18432
	ds_read_b128 v[172:175], v205 offset:19456
	ds_read_b128 v[190:193], v205 offset:20480
	ds_read_b128 v[194:197], v205 offset:21504
	ds_read_b128 v[206:209], v205 offset:22528
	ds_read_b128 v[210:213], v205 offset:23552
	s_add_i32 s0, s92, s76
	s_mov_b32 m0, s0
	v_lshl_add_u64 v[198:199], s[6:7], 0, v[180:181]
	global_load_lds_dwordx4 v[198:199], off
	s_add_i32 m0, s0, 0x2000
	s_add_u32 s0, s6, 0x80000
	v_lshl_add_u64 v[214:215], s[6:7], 0, v[184:185]
	s_addc_u32 s1, s7, 0
	s_add_i32 s2, s93, s76
	global_load_lds_dwordx4 v[214:215], off
	v_lshl_add_u64 v[216:217], s[0:1], 0, v[180:181]
	s_mov_b32 m0, s2
	v_lshl_add_u64 v[218:219], s[8:9], 0, v[182:183]
	global_load_lds_dwordx4 v[216:217], off
	s_add_i32 m0, s2, 0x2000
	v_lshl_add_u64 v[216:217], s[0:1], 0, v[184:185]
	global_load_lds_dwordx4 v[216:217], off
	s_mov_b32 m0, s77
	v_lshl_add_u64 v[216:217], s[8:9], 0, v[178:179]
	global_load_lds_dwordx4 v[216:217], off
	s_mov_b32 m0, s78
	s_nop 0
	global_load_lds_dwordx4 v[218:219], off
	s_waitcnt vmcnt(8) lgkmcnt(0)
	s_setprio 1
	s_barrier
	v_mfma_f32_16x16x32_bf16 v[92:95], v[128:131], v[160:163], v[92:95]
	v_mfma_f32_16x16x32_bf16 v[24:27], v[136:139], v[160:163], v[24:27]
	v_mfma_f32_16x16x32_bf16 v[84:87], v[128:131], v[168:171], v[84:87]
	v_mfma_f32_16x16x32_bf16 v[20:23], v[136:139], v[168:171], v[20:23]
	v_mfma_f32_16x16x32_bf16 v[76:79], v[128:131], v[190:193], v[76:79]
	v_mfma_f32_16x16x32_bf16 v[12:15], v[136:139], v[190:193], v[12:15]
	v_mfma_f32_16x16x32_bf16 v[72:75], v[128:131], v[206:209], v[72:75]
	v_mfma_f32_16x16x32_bf16 v[0:3], v[136:139], v[206:209], v[0:3]
	v_mfma_f32_16x16x32_bf16 v[92:95], v[132:135], v[164:167], v[92:95]
	v_mfma_f32_16x16x32_bf16 v[24:27], v[140:143], v[164:167], v[24:27]
	v_mfma_f32_16x16x32_bf16 v[84:87], v[132:135], v[172:175], v[84:87]
	v_mfma_f32_16x16x32_bf16 v[20:23], v[140:143], v[172:175], v[20:23]
	v_mfma_f32_16x16x32_bf16 v[76:79], v[132:135], v[194:197], v[76:79]
	v_mfma_f32_16x16x32_bf16 v[12:15], v[140:143], v[194:197], v[12:15]
	v_mfma_f32_16x16x32_bf16 v[72:75], v[132:135], v[210:213], v[72:75]
	v_mfma_f32_16x16x32_bf16 v[0:3], v[140:143], v[210:213], v[0:3]
	v_mfma_f32_16x16x32_bf16 v[88:91], v[144:147], v[160:163], v[88:91]
	v_mfma_f32_16x16x32_bf16 v[28:31], v[152:155], v[160:163], v[28:31]
	v_mfma_f32_16x16x32_bf16 v[80:83], v[144:147], v[168:171], v[80:83]
	v_mfma_f32_16x16x32_bf16 v[16:19], v[152:155], v[168:171], v[16:19]
	v_mfma_f32_16x16x32_bf16 v[68:71], v[144:147], v[190:193], v[68:71]
	v_mfma_f32_16x16x32_bf16 v[8:11], v[152:155], v[190:193], v[8:11]
	v_mfma_f32_16x16x32_bf16 v[64:67], v[144:147], v[206:209], v[64:67]
	v_mfma_f32_16x16x32_bf16 v[4:7], v[152:155], v[206:209], v[4:7]
	v_mfma_f32_16x16x32_bf16 v[88:91], v[148:151], v[164:167], v[88:91]
	v_mfma_f32_16x16x32_bf16 v[28:31], v[156:159], v[164:167], v[28:31]
	v_mfma_f32_16x16x32_bf16 v[80:83], v[148:151], v[172:175], v[80:83]
	v_mfma_f32_16x16x32_bf16 v[16:19], v[156:159], v[172:175], v[16:19]
	v_mfma_f32_16x16x32_bf16 v[68:71], v[148:151], v[194:197], v[68:71]
	v_mfma_f32_16x16x32_bf16 v[8:11], v[156:159], v[194:197], v[8:11]
	v_mfma_f32_16x16x32_bf16 v[64:67], v[148:151], v[210:213], v[64:67]
	s_setprio 0
	v_mfma_f32_16x16x32_bf16 v[4:7], v[156:159], v[210:213], v[4:7]
	s_barrier
	ds_read_b128 v[160:163], v205 offset:32768
	ds_read_b128 v[164:167], v205 offset:33792
	ds_read_b128 v[168:171], v205 offset:34816
	ds_read_b128 v[172:175], v205 offset:35840
	ds_read_b128 v[190:193], v205 offset:36864
	ds_read_b128 v[194:197], v205 offset:37888
	ds_read_b128 v[206:209], v205 offset:38912
	ds_read_b128 v[210:213], v205 offset:39936
	s_add_i32 s2, 0, 0x18000
	s_add_i32 s38, 0, 0x1c000
	v_add_u32_e32 v140, s2, v202
	v_add_u32_e32 v156, s38, v202
	ds_read_b128 v[128:131], v140
	ds_read_b128 v[132:135], v140 offset:1024
	ds_read_b128 v[136:139], v140 offset:2048
	ds_read_b128 v[140:143], v140 offset:3072
	ds_read_b128 v[144:147], v156
	ds_read_b128 v[148:151], v156 offset:1024
	ds_read_b128 v[152:155], v156 offset:2048
	ds_read_b128 v[156:159], v156 offset:3072
	s_add_u32 s0, s8, 0x80000
	s_addc_u32 s1, s9, 0
	s_mov_b32 m0, s79
	v_lshl_add_u64 v[220:221], s[0:1], 0, v[178:179]
	global_load_lds_dwordx4 v[220:221], off
	s_mov_b32 m0, s80
	v_lshl_add_u64 v[220:221], s[0:1], 0, v[182:183]
	global_load_lds_dwordx4 v[220:221], off
	s_waitcnt vmcnt(8) lgkmcnt(0)
	s_setprio 1
	s_barrier
	v_mfma_f32_16x16x32_bf16 v[124:127], v[128:131], v[160:163], v[124:127]
	v_mfma_f32_16x16x32_bf16 v[56:59], v[136:139], v[160:163], v[56:59]
	v_mfma_f32_16x16x32_bf16 v[116:119], v[128:131], v[168:171], v[116:119]
	v_mfma_f32_16x16x32_bf16 v[52:55], v[136:139], v[168:171], v[52:55]
	v_mfma_f32_16x16x32_bf16 v[108:111], v[128:131], v[190:193], v[108:111]
	v_mfma_f32_16x16x32_bf16 v[44:47], v[136:139], v[190:193], v[44:47]
	v_mfma_f32_16x16x32_bf16 v[104:107], v[128:131], v[206:209], v[104:107]
	v_mfma_f32_16x16x32_bf16 v[32:35], v[136:139], v[206:209], v[32:35]
	v_mfma_f32_16x16x32_bf16 v[124:127], v[132:135], v[164:167], v[124:127]
	v_mfma_f32_16x16x32_bf16 v[56:59], v[140:143], v[164:167], v[56:59]
	v_mfma_f32_16x16x32_bf16 v[116:119], v[132:135], v[172:175], v[116:119]
	v_mfma_f32_16x16x32_bf16 v[52:55], v[140:143], v[172:175], v[52:55]
	v_mfma_f32_16x16x32_bf16 v[108:111], v[132:135], v[194:197], v[108:111]
	v_mfma_f32_16x16x32_bf16 v[44:47], v[140:143], v[194:197], v[44:47]
	v_mfma_f32_16x16x32_bf16 v[104:107], v[132:135], v[210:213], v[104:107]
	v_mfma_f32_16x16x32_bf16 v[32:35], v[140:143], v[210:213], v[32:35]
	v_mfma_f32_16x16x32_bf16 v[120:123], v[144:147], v[160:163], v[120:123]
	v_mfma_f32_16x16x32_bf16 v[60:63], v[152:155], v[160:163], v[60:63]
	v_mfma_f32_16x16x32_bf16 v[112:115], v[144:147], v[168:171], v[112:115]
	v_mfma_f32_16x16x32_bf16 v[48:51], v[152:155], v[168:171], v[48:51]
	v_mfma_f32_16x16x32_bf16 v[100:103], v[144:147], v[190:193], v[100:103]
	v_mfma_f32_16x16x32_bf16 v[40:43], v[152:155], v[190:193], v[40:43]
	v_mfma_f32_16x16x32_bf16 v[96:99], v[144:147], v[206:209], v[96:99]
	v_mfma_f32_16x16x32_bf16 v[36:39], v[152:155], v[206:209], v[36:39]
	v_mfma_f32_16x16x32_bf16 v[120:123], v[148:151], v[164:167], v[120:123]
	v_mfma_f32_16x16x32_bf16 v[60:63], v[156:159], v[164:167], v[60:63]
	v_mfma_f32_16x16x32_bf16 v[112:115], v[148:151], v[172:175], v[112:115]
	v_mfma_f32_16x16x32_bf16 v[48:51], v[156:159], v[172:175], v[48:51]
	v_mfma_f32_16x16x32_bf16 v[100:103], v[148:151], v[194:197], v[100:103]
	v_mfma_f32_16x16x32_bf16 v[40:43], v[156:159], v[194:197], v[40:43]
	v_mfma_f32_16x16x32_bf16 v[96:99], v[148:151], v[210:213], v[96:99]
	s_setprio 0
	v_mfma_f32_16x16x32_bf16 v[36:39], v[156:159], v[210:213], v[36:39]
	s_barrier
	ds_read_b128 v[160:163], v205 offset:49152
	ds_read_b128 v[164:167], v205 offset:50176
	ds_read_b128 v[168:171], v205 offset:51200
	ds_read_b128 v[172:175], v205 offset:52224
	ds_read_b128 v[190:193], v205 offset:53248
	ds_read_b128 v[194:197], v205 offset:54272
	ds_read_b128 v[206:209], v205 offset:55296
	ds_read_b128 v[210:213], v205 offset:56320
	s_add_i32 s0, s2, s76
	s_mov_b32 m0, s0
	v_lshl_add_u64 v[198:199], v[198:199], 0, s[24:25]
	global_load_lds_dwordx4 v[198:199], off
	s_add_i32 m0, s0, 0x2000
	s_add_u32 s0, s6, 0x80080
	v_lshl_add_u64 v[198:199], v[214:215], 0, s[24:25]
	s_addc_u32 s1, s7, 0
	s_add_i32 s2, s38, s76
	global_load_lds_dwordx4 v[198:199], off
	s_mov_b32 m0, s2
	v_lshl_add_u64 v[198:199], s[0:1], 0, v[180:181]
	global_load_lds_dwordx4 v[198:199], off
	s_add_i32 m0, s2, 0x2000
	v_lshl_add_u64 v[198:199], s[0:1], 0, v[184:185]
	global_load_lds_dwordx4 v[198:199], off
	s_mov_b32 m0, s86
	v_lshl_add_u64 v[198:199], v[216:217], 0, s[24:25]
	global_load_lds_dwordx4 v[198:199], off
	s_mov_b32 m0, s87
	v_lshl_add_u64 v[198:199], v[218:219], 0, s[24:25]
	global_load_lds_dwordx4 v[198:199], off
	s_waitcnt vmcnt(8) lgkmcnt(0)
	s_setprio 1
	s_barrier
	v_mfma_f32_16x16x32_bf16 v[92:95], v[128:131], v[160:163], v[92:95]
	v_mfma_f32_16x16x32_bf16 v[24:27], v[136:139], v[160:163], v[24:27]
	v_mfma_f32_16x16x32_bf16 v[84:87], v[128:131], v[168:171], v[84:87]
	v_mfma_f32_16x16x32_bf16 v[20:23], v[136:139], v[168:171], v[20:23]
	v_mfma_f32_16x16x32_bf16 v[76:79], v[128:131], v[190:193], v[76:79]
	v_mfma_f32_16x16x32_bf16 v[12:15], v[136:139], v[190:193], v[12:15]
	v_mfma_f32_16x16x32_bf16 v[72:75], v[128:131], v[206:209], v[72:75]
	v_mfma_f32_16x16x32_bf16 v[0:3], v[136:139], v[206:209], v[0:3]
	v_mfma_f32_16x16x32_bf16 v[92:95], v[132:135], v[164:167], v[92:95]
	v_mfma_f32_16x16x32_bf16 v[24:27], v[140:143], v[164:167], v[24:27]
	v_mfma_f32_16x16x32_bf16 v[84:87], v[132:135], v[172:175], v[84:87]
	v_mfma_f32_16x16x32_bf16 v[20:23], v[140:143], v[172:175], v[20:23]
	v_mfma_f32_16x16x32_bf16 v[76:79], v[132:135], v[194:197], v[76:79]
	v_mfma_f32_16x16x32_bf16 v[12:15], v[140:143], v[194:197], v[12:15]
	v_mfma_f32_16x16x32_bf16 v[72:75], v[132:135], v[210:213], v[72:75]
	v_mfma_f32_16x16x32_bf16 v[0:3], v[140:143], v[210:213], v[0:3]
	v_mfma_f32_16x16x32_bf16 v[88:91], v[144:147], v[160:163], v[88:91]
	v_mfma_f32_16x16x32_bf16 v[28:31], v[152:155], v[160:163], v[28:31]
	v_mfma_f32_16x16x32_bf16 v[80:83], v[144:147], v[168:171], v[80:83]
	v_mfma_f32_16x16x32_bf16 v[16:19], v[152:155], v[168:171], v[16:19]
	v_mfma_f32_16x16x32_bf16 v[68:71], v[144:147], v[190:193], v[68:71]
	v_mfma_f32_16x16x32_bf16 v[8:11], v[152:155], v[190:193], v[8:11]
	v_mfma_f32_16x16x32_bf16 v[64:67], v[144:147], v[206:209], v[64:67]
	v_mfma_f32_16x16x32_bf16 v[4:7], v[152:155], v[206:209], v[4:7]
	v_mfma_f32_16x16x32_bf16 v[88:91], v[148:151], v[164:167], v[88:91]
	s_add_i32 s96, s96, 2
	v_mfma_f32_16x16x32_bf16 v[28:31], v[156:159], v[164:167], v[28:31]
	s_add_u32 s4, s4, 0x100
	v_mfma_f32_16x16x32_bf16 v[80:83], v[148:151], v[172:175], v[80:83]
	s_addc_u32 s5, s5, 0
	v_mfma_f32_16x16x32_bf16 v[16:19], v[156:159], v[172:175], v[16:19]
	s_add_u32 s10, s10, 0x100
	v_mfma_f32_16x16x32_bf16 v[68:71], v[148:151], v[194:197], v[68:71]
	s_addc_u32 s11, s11, 0
	v_mfma_f32_16x16x32_bf16 v[8:11], v[156:159], v[194:197], v[8:11]
	s_cmp_gt_u32 s96, 29
	v_mfma_f32_16x16x32_bf16 v[64:67], v[148:151], v[210:213], v[64:67]
	s_setprio 0
	v_mfma_f32_16x16x32_bf16 v[4:7], v[156:159], v[210:213], v[4:7]
	s_barrier
	s_cbranch_scc0 .LBB0_1107
	s_and_b64 vcc, exec, s[26:27]
	s_cbranch_vccz .LBB0_1110
	s_barrier

.LBB0_1249:
	ds_read_b128 v[128:131], v157
	ds_read_b128 v[132:135], v157 offset:1024
	ds_read_b128 v[136:139], v157 offset:2048
	ds_read_b128 v[140:143], v157 offset:3072
	ds_read_b128 v[160:163], v158
	ds_read_b128 v[164:167], v158 offset:1024
	ds_read_b128 v[168:171], v158 offset:2048
	ds_read_b128 v[172:175], v158 offset:3072
	ds_read_b128 v[176:179], v159
	ds_read_b128 v[180:183], v159 offset:1024
	ds_read_b128 v[184:187], v159 offset:2048
	ds_read_b128 v[188:191], v159 offset:3072
	ds_read_b128 v[192:195], v159 offset:4096
	ds_read_b128 v[196:199], v159 offset:5120
	ds_read_b128 v[200:203], v159 offset:6144
	ds_read_b128 v[204:207], v159 offset:7168
	s_add_u32 s38, s36, 0x100
	s_addc_u32 s39, s37, 0
	s_cmpk_eq_i32 s74, 0x54
	s_cselect_b32 s45, s6, s39
	s_cselect_b32 s44, s35, s38
	s_cselect_b32 s43, s70, s73
	s_cselect_b32 s42, s71, s72
	s_add_i32 m0, s52, 0xc000
	v_lshl_add_u64 v[152:153], s[36:37], 0, v[148:149]
	global_load_lds_dwordx4 v[152:153], off
	s_add_i32 m0, s52, 0xe000
	v_lshl_add_u64 v[152:153], s[36:37], 0, v[150:151]
	global_load_lds_dwordx4 v[152:153], off
	s_waitcnt vmcnt(8) lgkmcnt(0)
	s_setprio 1
	s_barrier
	v_mfma_f32_16x16x32_bf16 v[124:127], v[128:131], v[176:179], v[124:127]
	v_mfma_f32_16x16x32_bf16 v[120:123], v[136:139], v[176:179], v[120:123]
	v_mfma_f32_16x16x32_bf16 v[112:115], v[128:131], v[184:187], v[112:115]
	v_mfma_f32_16x16x32_bf16 v[108:111], v[136:139], v[184:187], v[108:111]
	v_mfma_f32_16x16x32_bf16 v[96:99], v[128:131], v[192:195], v[96:99]
	v_mfma_f32_16x16x32_bf16 v[92:95], v[136:139], v[192:195], v[92:95]
	v_mfma_f32_16x16x32_bf16 v[80:83], v[128:131], v[200:203], v[80:83]
	v_mfma_f32_16x16x32_bf16 v[76:79], v[136:139], v[200:203], v[76:79]
	v_mfma_f32_16x16x32_bf16 v[124:127], v[132:135], v[180:183], v[124:127]
	v_mfma_f32_16x16x32_bf16 v[120:123], v[140:143], v[180:183], v[120:123]
	v_mfma_f32_16x16x32_bf16 v[112:115], v[132:135], v[188:191], v[112:115]
	v_mfma_f32_16x16x32_bf16 v[108:111], v[140:143], v[188:191], v[108:111]
	v_mfma_f32_16x16x32_bf16 v[96:99], v[132:135], v[196:199], v[96:99]
	v_mfma_f32_16x16x32_bf16 v[92:95], v[140:143], v[196:199], v[92:95]
	v_mfma_f32_16x16x32_bf16 v[80:83], v[132:135], v[204:207], v[80:83]
	v_mfma_f32_16x16x32_bf16 v[76:79], v[140:143], v[204:207], v[76:79]
	v_mfma_f32_16x16x32_bf16 v[116:119], v[160:163], v[176:179], v[116:119]
	v_mfma_f32_16x16x32_bf16 v[104:107], v[168:171], v[176:179], v[104:107]
	v_mfma_f32_16x16x32_bf16 v[100:103], v[160:163], v[184:187], v[100:103]
	v_mfma_f32_16x16x32_bf16 v[88:91], v[168:171], v[184:187], v[88:91]
	v_mfma_f32_16x16x32_bf16 v[84:87], v[160:163], v[192:195], v[84:87]
	v_mfma_f32_16x16x32_bf16 v[72:75], v[168:171], v[192:195], v[72:75]
	v_mfma_f32_16x16x32_bf16 v[68:71], v[160:163], v[200:203], v[68:71]
	v_mfma_f32_16x16x32_bf16 v[64:67], v[168:171], v[200:203], v[64:67]
	v_mfma_f32_16x16x32_bf16 v[116:119], v[164:167], v[180:183], v[116:119]
	v_mfma_f32_16x16x32_bf16 v[104:107], v[172:175], v[180:183], v[104:107]
	v_mfma_f32_16x16x32_bf16 v[100:103], v[164:167], v[188:191], v[100:103]
	v_mfma_f32_16x16x32_bf16 v[88:91], v[172:175], v[188:191], v[88:91]
	v_mfma_f32_16x16x32_bf16 v[84:87], v[164:167], v[196:199], v[84:87]
	v_mfma_f32_16x16x32_bf16 v[72:75], v[172:175], v[196:199], v[72:75]
	v_mfma_f32_16x16x32_bf16 v[68:71], v[164:167], v[204:207], v[68:71]
	s_setprio 0
	v_mfma_f32_16x16x32_bf16 v[64:67], v[172:175], v[204:207], v[64:67]
	s_barrier
	ds_read_b128 v[176:179], v159 offset:16384
	ds_read_b128 v[180:183], v159 offset:17408
	ds_read_b128 v[184:187], v159 offset:18432
	ds_read_b128 v[188:191], v159 offset:19456
	ds_read_b128 v[192:195], v159 offset:20480
	ds_read_b128 v[196:199], v159 offset:21504
	ds_read_b128 v[200:203], v159 offset:22528
	ds_read_b128 v[204:207], v159 offset:23552
	s_add_i32 s36, s64, s51
	s_mov_b32 m0, s36
	v_lshl_add_u64 v[152:153], s[42:43], 0, v[146:147]
	global_load_lds_dwordx4 v[152:153], off
	s_add_i32 m0, s36, 0x2000
	s_add_u32 s36, s42, 0x160000
	v_lshl_add_u64 v[208:209], s[42:43], 0, v[144:145]
	s_addc_u32 s37, s43, 0
	s_add_i32 s75, s65, s51
	global_load_lds_dwordx4 v[208:209], off
	v_lshl_add_u64 v[210:211], s[36:37], 0, v[146:147]
	s_mov_b32 m0, s75
	v_lshl_add_u64 v[212:213], s[44:45], 0, v[144:145]
	global_load_lds_dwordx4 v[210:211], off
	s_add_i32 m0, s75, 0x2000
	v_lshl_add_u64 v[210:211], s[36:37], 0, v[144:145]
	global_load_lds_dwordx4 v[210:211], off
	s_mov_b32 m0, s52
	v_lshl_add_u64 v[210:211], s[44:45], 0, v[146:147]
	global_load_lds_dwordx4 v[210:211], off
	s_mov_b32 m0, s53
	s_nop 0
	global_load_lds_dwordx4 v[212:213], off
	s_waitcnt vmcnt(8) lgkmcnt(0)
	s_setprio 1
	s_barrier
	v_mfma_f32_16x16x32_bf16 v[60:63], v[128:131], v[176:179], v[60:63]
	v_mfma_f32_16x16x32_bf16 v[56:59], v[136:139], v[176:179], v[56:59]
	v_mfma_f32_16x16x32_bf16 v[48:51], v[128:131], v[184:187], v[48:51]
	v_mfma_f32_16x16x32_bf16 v[44:47], v[136:139], v[184:187], v[44:47]
	v_mfma_f32_16x16x32_bf16 v[32:35], v[128:131], v[192:195], v[32:35]
	v_mfma_f32_16x16x32_bf16 v[28:31], v[136:139], v[192:195], v[28:31]
	v_mfma_f32_16x16x32_bf16 v[16:19], v[128:131], v[200:203], v[16:19]
	v_mfma_f32_16x16x32_bf16 v[12:15], v[136:139], v[200:203], v[12:15]
	v_mfma_f32_16x16x32_bf16 v[60:63], v[132:135], v[180:183], v[60:63]
	v_mfma_f32_16x16x32_bf16 v[56:59], v[140:143], v[180:183], v[56:59]
	v_mfma_f32_16x16x32_bf16 v[48:51], v[132:135], v[188:191], v[48:51]
	v_mfma_f32_16x16x32_bf16 v[44:47], v[140:143], v[188:191], v[44:47]
	v_mfma_f32_16x16x32_bf16 v[32:35], v[132:135], v[196:199], v[32:35]
	v_mfma_f32_16x16x32_bf16 v[28:31], v[140:143], v[196:199], v[28:31]
	v_mfma_f32_16x16x32_bf16 v[16:19], v[132:135], v[204:207], v[16:19]
	v_mfma_f32_16x16x32_bf16 v[12:15], v[140:143], v[204:207], v[12:15]
	v_mfma_f32_16x16x32_bf16 v[52:55], v[160:163], v[176:179], v[52:55]
	v_mfma_f32_16x16x32_bf16 v[40:43], v[168:171], v[176:179], v[40:43]
	v_mfma_f32_16x16x32_bf16 v[36:39], v[160:163], v[184:187], v[36:39]
	v_mfma_f32_16x16x32_bf16 v[24:27], v[168:171], v[184:187], v[24:27]
	v_mfma_f32_16x16x32_bf16 v[20:23], v[160:163], v[192:195], v[20:23]
	v_mfma_f32_16x16x32_bf16 v[8:11], v[168:171], v[192:195], v[8:11]
	v_mfma_f32_16x16x32_bf16 v[4:7], v[160:163], v[200:203], v[4:7]
	v_mfma_f32_16x16x32_bf16 v[0:3], v[168:171], v[200:203], v[0:3]
	v_mfma_f32_16x16x32_bf16 v[52:55], v[164:167], v[180:183], v[52:55]
	v_mfma_f32_16x16x32_bf16 v[40:43], v[172:175], v[180:183], v[40:43]
	v_mfma_f32_16x16x32_bf16 v[36:39], v[164:167], v[188:191], v[36:39]
	v_mfma_f32_16x16x32_bf16 v[24:27], v[172:175], v[188:191], v[24:27]
	v_mfma_f32_16x16x32_bf16 v[20:23], v[164:167], v[196:199], v[20:23]
	v_mfma_f32_16x16x32_bf16 v[8:11], v[172:175], v[196:199], v[8:11]
	v_mfma_f32_16x16x32_bf16 v[4:7], v[164:167], v[204:207], v[4:7]
	s_setprio 0
	v_mfma_f32_16x16x32_bf16 v[0:3], v[172:175], v[204:207], v[0:3]
	s_barrier
	ds_read_b128 v[176:179], v159 offset:32768
	ds_read_b128 v[180:183], v159 offset:33792
	ds_read_b128 v[184:187], v159 offset:34816
	ds_read_b128 v[188:191], v159 offset:35840
	ds_read_b128 v[192:195], v159 offset:36864
	ds_read_b128 v[196:199], v159 offset:37888
	ds_read_b128 v[200:203], v159 offset:38912
	ds_read_b128 v[204:207], v159 offset:39936
	s_add_i32 s75, 0, 0x18000
	s_add_i32 s76, 0, 0x1c000
	v_add_u32_e32 v140, s75, v156
	v_add_u32_e32 v172, s76, v156
	ds_read_b128 v[128:131], v140
	ds_read_b128 v[132:135], v140 offset:1024
	ds_read_b128 v[136:139], v140 offset:2048
	ds_read_b128 v[140:143], v140 offset:3072
	ds_read_b128 v[160:163], v172
	ds_read_b128 v[164:167], v172 offset:1024
	ds_read_b128 v[168:171], v172 offset:2048
	ds_read_b128 v[172:175], v172 offset:3072
	s_add_u32 s36, s44, 0x160000
	s_addc_u32 s37, s45, 0
	s_mov_b32 m0, s54
	v_lshl_add_u64 v[214:215], s[36:37], 0, v[146:147]
	global_load_lds_dwordx4 v[214:215], off
	s_mov_b32 m0, s55
	v_lshl_add_u64 v[214:215], s[36:37], 0, v[144:145]
	global_load_lds_dwordx4 v[214:215], off
	s_waitcnt vmcnt(8) lgkmcnt(0)
	s_setprio 1
	s_barrier
	v_mfma_f32_16x16x32_bf16 v[124:127], v[128:131], v[176:179], v[124:127]
	v_mfma_f32_16x16x32_bf16 v[120:123], v[136:139], v[176:179], v[120:123]
	v_mfma_f32_16x16x32_bf16 v[112:115], v[128:131], v[184:187], v[112:115]
	v_mfma_f32_16x16x32_bf16 v[108:111], v[136:139], v[184:187], v[108:111]
	v_mfma_f32_16x16x32_bf16 v[96:99], v[128:131], v[192:195], v[96:99]
	v_mfma_f32_16x16x32_bf16 v[92:95], v[136:139], v[192:195], v[92:95]
	v_mfma_f32_16x16x32_bf16 v[80:83], v[128:131], v[200:203], v[80:83]
	v_mfma_f32_16x16x32_bf16 v[76:79], v[136:139], v[200:203], v[76:79]
	v_mfma_f32_16x16x32_bf16 v[124:127], v[132:135], v[180:183], v[124:127]
	v_mfma_f32_16x16x32_bf16 v[120:123], v[140:143], v[180:183], v[120:123]
	v_mfma_f32_16x16x32_bf16 v[112:115], v[132:135], v[188:191], v[112:115]
	v_mfma_f32_16x16x32_bf16 v[108:111], v[140:143], v[188:191], v[108:111]
	v_mfma_f32_16x16x32_bf16 v[96:99], v[132:135], v[196:199], v[96:99]
	v_mfma_f32_16x16x32_bf16 v[92:95], v[140:143], v[196:199], v[92:95]
	v_mfma_f32_16x16x32_bf16 v[80:83], v[132:135], v[204:207], v[80:83]
	v_mfma_f32_16x16x32_bf16 v[76:79], v[140:143], v[204:207], v[76:79]
	v_mfma_f32_16x16x32_bf16 v[116:119], v[160:163], v[176:179], v[116:119]
	v_mfma_f32_16x16x32_bf16 v[104:107], v[168:171], v[176:179], v[104:107]
	v_mfma_f32_16x16x32_bf16 v[100:103], v[160:163], v[184:187], v[100:103]
	v_mfma_f32_16x16x32_bf16 v[88:91], v[168:171], v[184:187], v[88:91]
	v_mfma_f32_16x16x32_bf16 v[84:87], v[160:163], v[192:195], v[84:87]
	v_mfma_f32_16x16x32_bf16 v[72:75], v[168:171], v[192:195], v[72:75]
	v_mfma_f32_16x16x32_bf16 v[68:71], v[160:163], v[200:203], v[68:71]
	v_mfma_f32_16x16x32_bf16 v[64:67], v[168:171], v[200:203], v[64:67]
	v_mfma_f32_16x16x32_bf16 v[116:119], v[164:167], v[180:183], v[116:119]
	v_mfma_f32_16x16x32_bf16 v[104:107], v[172:175], v[180:183], v[104:107]
	v_mfma_f32_16x16x32_bf16 v[100:103], v[164:167], v[188:191], v[100:103]
	v_mfma_f32_16x16x32_bf16 v[88:91], v[172:175], v[188:191], v[88:91]
	v_mfma_f32_16x16x32_bf16 v[84:87], v[164:167], v[196:199], v[84:87]
	v_mfma_f32_16x16x32_bf16 v[72:75], v[172:175], v[196:199], v[72:75]
	v_mfma_f32_16x16x32_bf16 v[68:71], v[164:167], v[204:207], v[68:71]
	s_setprio 0
	v_mfma_f32_16x16x32_bf16 v[64:67], v[172:175], v[204:207], v[64:67]
	s_barrier
	ds_read_b128 v[176:179], v159 offset:49152
	ds_read_b128 v[180:183], v159 offset:50176
	ds_read_b128 v[184:187], v159 offset:51200
	ds_read_b128 v[188:191], v159 offset:52224
	ds_read_b128 v[192:195], v159 offset:53248
	ds_read_b128 v[196:199], v159 offset:54272
	ds_read_b128 v[200:203], v159 offset:55296
	ds_read_b128 v[204:207], v159 offset:56320
	s_add_i32 s36, s75, s51
	s_mov_b32 m0, s36
	v_lshl_add_u64 v[152:153], v[152:153], 0, s[4:5]
	global_load_lds_dwordx4 v[152:153], off
	s_add_i32 m0, s36, 0x2000
	s_add_u32 s36, s42, 0x160080
	v_lshl_add_u64 v[152:153], v[208:209], 0, s[4:5]
	s_addc_u32 s37, s43, 0
	s_add_i32 s42, s76, s51
	global_load_lds_dwordx4 v[152:153], off
	s_mov_b32 m0, s42
	v_lshl_add_u64 v[152:153], s[36:37], 0, v[146:147]
	global_load_lds_dwordx4 v[152:153], off
	s_add_i32 m0, s42, 0x2000
	v_lshl_add_u64 v[152:153], s[36:37], 0, v[144:145]
	global_load_lds_dwordx4 v[152:153], off
	s_mov_b32 m0, s62
	v_lshl_add_u64 v[152:153], v[210:211], 0, s[4:5]
	global_load_lds_dwordx4 v[152:153], off
	s_mov_b32 m0, s63
	v_lshl_add_u64 v[152:153], v[212:213], 0, s[4:5]
	global_load_lds_dwordx4 v[152:153], off
	s_waitcnt vmcnt(8) lgkmcnt(0)
	s_setprio 1
	s_barrier
	v_mfma_f32_16x16x32_bf16 v[60:63], v[128:131], v[176:179], v[60:63]
	v_mfma_f32_16x16x32_bf16 v[56:59], v[136:139], v[176:179], v[56:59]
	v_mfma_f32_16x16x32_bf16 v[48:51], v[128:131], v[184:187], v[48:51]
	v_mfma_f32_16x16x32_bf16 v[44:47], v[136:139], v[184:187], v[44:47]
	v_mfma_f32_16x16x32_bf16 v[32:35], v[128:131], v[192:195], v[32:35]
	v_mfma_f32_16x16x32_bf16 v[28:31], v[136:139], v[192:195], v[28:31]
	v_mfma_f32_16x16x32_bf16 v[16:19], v[128:131], v[200:203], v[16:19]
	v_mfma_f32_16x16x32_bf16 v[12:15], v[136:139], v[200:203], v[12:15]
	v_mfma_f32_16x16x32_bf16 v[60:63], v[132:135], v[180:183], v[60:63]
	v_mfma_f32_16x16x32_bf16 v[56:59], v[140:143], v[180:183], v[56:59]
	v_mfma_f32_16x16x32_bf16 v[48:51], v[132:135], v[188:191], v[48:51]
	v_mfma_f32_16x16x32_bf16 v[44:47], v[140:143], v[188:191], v[44:47]
	v_mfma_f32_16x16x32_bf16 v[32:35], v[132:135], v[196:199], v[32:35]
	v_mfma_f32_16x16x32_bf16 v[28:31], v[140:143], v[196:199], v[28:31]
	v_mfma_f32_16x16x32_bf16 v[16:19], v[132:135], v[204:207], v[16:19]
	v_mfma_f32_16x16x32_bf16 v[12:15], v[140:143], v[204:207], v[12:15]
	v_mfma_f32_16x16x32_bf16 v[52:55], v[160:163], v[176:179], v[52:55]
	v_mfma_f32_16x16x32_bf16 v[40:43], v[168:171], v[176:179], v[40:43]
	v_mfma_f32_16x16x32_bf16 v[36:39], v[160:163], v[184:187], v[36:39]
	v_mfma_f32_16x16x32_bf16 v[24:27], v[168:171], v[184:187], v[24:27]
	v_mfma_f32_16x16x32_bf16 v[20:23], v[160:163], v[192:195], v[20:23]
	v_mfma_f32_16x16x32_bf16 v[8:11], v[168:171], v[192:195], v[8:11]
	v_mfma_f32_16x16x32_bf16 v[4:7], v[160:163], v[200:203], v[4:7]
	v_mfma_f32_16x16x32_bf16 v[0:3], v[168:171], v[200:203], v[0:3]
	v_mfma_f32_16x16x32_bf16 v[52:55], v[164:167], v[180:183], v[52:55]
	v_mfma_f32_16x16x32_bf16 v[40:43], v[172:175], v[180:183], v[40:43]
	s_add_i32 s74, s74, 2
	v_mfma_f32_16x16x32_bf16 v[36:39], v[164:167], v[188:191], v[36:39]
	s_add_u32 s72, s72, 0x100
	v_mfma_f32_16x16x32_bf16 v[24:27], v[172:175], v[188:191], v[24:27]
	s_addc_u32 s73, s73, 0
	v_mfma_f32_16x16x32_bf16 v[20:23], v[164:167], v[196:199], v[20:23]
	s_cmpk_gt_u32 s74, 0x55
	v_mfma_f32_16x16x32_bf16 v[8:11], v[172:175], v[196:199], v[8:11]
	s_mov_b64 s[36:37], s[38:39]
	v_mfma_f32_16x16x32_bf16 v[4:7], v[164:167], v[204:207], v[4:7]
	s_setprio 0
	v_mfma_f32_16x16x32_bf16 v[0:3], v[172:175], v[204:207], v[0:3]
	s_barrier
	s_cbranch_scc0 .LBB0_1249
	s_and_b64 vcc, exec, s[8:9]
	s_cbranch_vccz .LBB0_1252
	s_barrier
